# decode + conv: packed f32 VALU ops (v_pk_fma/mul/add_f32) rewritten as pairs of single f32 ops
# speedup vs baseline: 1.0120x; 1.0120x over previous
.LBB0_429:
	s_lshr_b32 s44, s53, 3
	s_cmp_eq_u32 s44, 2
	s_cselect_b32 s4, s47, s49
	s_cmp_eq_u32 s44, 1
	s_waitcnt vmcnt(8)
	v_cvt_pk_bf16_f32 v112, v144, v145
	v_cvt_pk_bf16_f32 v113, v146, v147
	s_cselect_b32 s4, s41, s4
	s_cmp_lt_u32 s53, 8
	ds_write_b64 v181, v[112:113] offset:43008
	v_cvt_pk_bf16_f32 v112, v140, v141
	v_cvt_pk_bf16_f32 v113, v142, v143
	s_cselect_b32 s4, s40, s4
	ds_write_b64 v181, v[112:113] offset:43552
	v_cvt_pk_bf16_f32 v112, v136, v137
	v_cvt_pk_bf16_f32 v113, v138, v139
	s_ashr_i32 s5, s4, 31
	s_and_b32 s48, s51, 0x60
	ds_write_b64 v181, v[112:113] offset:44096
	v_cvt_pk_bf16_f32 v112, v132, v133
	v_cvt_pk_bf16_f32 v113, v134, v135
	s_or_b32 s16, s48, 16
	s_lshl_b64 s[42:43], s[4:5], 18
	ds_write_b64 v181, v[112:113] offset:44640
	v_cvt_pk_bf16_f32 v112, v128, v129
	v_cvt_pk_bf16_f32 v113, v130, v131
	s_add_u32 s4, s8, s42
	ds_write_b64 v181, v[112:113] offset:45184
	v_cvt_pk_bf16_f32 v112, v124, v125
	v_cvt_pk_bf16_f32 v113, v126, v127
	s_addc_u32 s5, s9, s43
	s_lshl_b32 s46, s16, 11
	ds_write_b64 v181, v[112:113] offset:45728
	v_cvt_pk_bf16_f32 v112, v120, v121
	v_cvt_pk_bf16_f32 v113, v122, v123
	s_add_u32 s54, s4, s46
	ds_write_b64 v181, v[112:113] offset:46272
	v_cvt_pk_bf16_f32 v112, v116, v117
	v_cvt_pk_bf16_f32 v113, v118, v119
	s_addc_u32 s55, s5, 0
	ds_write_b64 v181, v[112:113] offset:46816
	v_lshl_add_u64 v[112:113], s[54:55], 0, v[168:169]
	v_add_co_u32_e64 v114, s[4:5], s13, v112
	v_mov_b32_e32 v183, v182
	s_nop 0
	v_addc_co_u32_e64 v115, s[4:5], 0, v113, s[4:5]
	global_load_dwordx4 v[140:143], v[114:115], off offset:-4096 nt
	global_load_dwordx4 v[136:139], v[114:115], off nt
	v_add_co_u32_e64 v114, s[4:5], s14, v112
	s_nop 1
	v_addc_co_u32_e64 v115, s[4:5], 0, v113, s[4:5]
	global_load_dwordx4 v[132:135], v[114:115], off offset:-4096 nt
	global_load_dwordx4 v[128:131], v[114:115], off nt
	v_add_co_u32_e64 v114, s[4:5], s15, v112
	s_nop 1
	v_addc_co_u32_e64 v115, s[4:5], 0, v113, s[4:5]
	v_add_co_u32_e64 v112, s[4:5], s26, v112
	global_load_dwordx4 v[124:127], v[114:115], off offset:-4096 nt
	global_load_dwordx4 v[120:123], v[114:115], off nt
	v_addc_co_u32_e64 v113, s[4:5], 0, v113, s[4:5]
	global_load_dwordx4 v[144:147], v168, s[54:55] nt
	global_load_dwordx4 v[116:119], v[112:113], off nt
	s_or_b32 s4, s44, s45
	s_lshl_b32 s44, s4, 7
	s_or_b32 s4, s44, s48
	v_add_u32_e32 v112, s4, v179
	v_add_u32_e32 v113, -1, v112
	v_add_u32_e32 v114, -2, v112
	v_add_u32_e32 v115, -3, v112
	s_waitcnt lgkmcnt(0)
	v_cvt_f32_i32_e32 v152, v112
	v_cvt_f32_i32_e32 v153, v113
	v_cvt_f32_i32_e32 v155, v115
	v_cvt_f32_i32_e32 v154, v114
	ds_read_b128 v[112:115], v190 offset:43008
	ds_read_b128 v[148:151], v190 offset:43072
	v_mul_f32_e32 v152, v184, v152
	v_mul_f32_e32 v153, v185, v153
	v_mul_f32_e32 v154, v182, v154
	v_mul_f32_e32 v155, v183, v155
	s_waitcnt lgkmcnt(1)
	s_nop 0
	v_mfma_f32_16x16x32_bf16 v[112:115], v[24:27], v[112:115], v[152:155]
	s_waitcnt lgkmcnt(0)
	v_mfma_f32_16x16x32_bf16 v[112:115], v[48:51], v[148:151], v[112:115]
	ds_read_b128 v[148:151], v190 offset:43136
	ds_read_b128 v[152:155], v190 offset:43200
	s_waitcnt lgkmcnt(1)
	v_mfma_f32_16x16x32_bf16 v[112:115], v[52:55], v[148:151], v[112:115]
	s_waitcnt lgkmcnt(0)
	v_mfma_f32_16x16x32_bf16 v[112:115], v[60:63], v[152:155], v[112:115]
	s_nop 7
	v_mov_b32_dpp v148, v112 quad_perm:[1,0,3,2] row_mask:0xf bank_mask:0xf bound_ctrl:1
	v_max_f32_e32 v149, v112, v112
	v_max_f32_e32 v148, v148, v148
	v_max_f32_e32 v148, v149, v148
	s_nop 1
	v_mov_b32_dpp v149, v148 quad_perm:[2,3,0,1] row_mask:0xf bank_mask:0xf bound_ctrl:1
	v_max_f32_e32 v149, v149, v149
	v_max_f32_e32 v148, v148, v149
	s_nop 1
	v_mov_b32_dpp v149, v148 row_half_mirror row_mask:0xf bank_mask:0xf bound_ctrl:1
	v_max_f32_e32 v149, v149, v149
	v_max_f32_e32 v148, v148, v149
	s_nop 1
	v_mov_b32_dpp v149, v148 row_ror:8 row_mask:0xf bank_mask:0xf bound_ctrl:1
	v_max3_f32 v192, v172, v148, v149
	v_mov_b32_dpp v148, v113 quad_perm:[1,0,3,2] row_mask:0xf bank_mask:0xf bound_ctrl:1
	v_max_f32_e32 v149, v113, v113
	v_max_f32_e32 v148, v148, v148
	v_max_f32_e32 v148, v149, v148
	v_sub_f32_e32 v112, v112, v192
	v_exp_f32_e32 v112, v112
	v_mov_b32_dpp v149, v148 quad_perm:[2,3,0,1] row_mask:0xf bank_mask:0xf bound_ctrl:1
	v_max_f32_e32 v149, v149, v149
	v_max_f32_e32 v148, v148, v149
	s_nop 1
	v_mov_b32_dpp v149, v148 row_half_mirror row_mask:0xf bank_mask:0xf bound_ctrl:1
	v_max_f32_e32 v149, v149, v149
	v_max_f32_e32 v148, v148, v149
	s_nop 1
	v_mov_b32_dpp v149, v148 row_ror:8 row_mask:0xf bank_mask:0xf bound_ctrl:1
	v_max3_f32 v193, v178, v148, v149
	v_mov_b32_dpp v148, v114 quad_perm:[1,0,3,2] row_mask:0xf bank_mask:0xf bound_ctrl:1
	v_max_f32_e32 v149, v114, v114
	v_max_f32_e32 v148, v148, v148
	v_max_f32_e32 v148, v149, v148
	v_sub_f32_e32 v113, v113, v193
	v_exp_f32_e32 v113, v113
	v_mov_b32_dpp v149, v148 quad_perm:[2,3,0,1] row_mask:0xf bank_mask:0xf bound_ctrl:1
	v_max_f32_e32 v149, v149, v149
	v_max_f32_e32 v148, v148, v149
	s_nop 1
	v_mov_b32_dpp v149, v148 row_half_mirror row_mask:0xf bank_mask:0xf bound_ctrl:1
	v_max_f32_e32 v149, v149, v149
	v_max_f32_e32 v148, v148, v149
	s_nop 1
	v_mov_b32_dpp v149, v148 row_ror:8 row_mask:0xf bank_mask:0xf bound_ctrl:1
	v_max3_f32 v194, v180, v148, v149
	v_mov_b32_dpp v148, v115 quad_perm:[1,0,3,2] row_mask:0xf bank_mask:0xf bound_ctrl:1
	v_max_f32_e32 v149, v115, v115
	v_max_f32_e32 v148, v148, v148
	v_max_f32_e32 v148, v149, v148
	v_sub_f32_e32 v114, v114, v194
	v_exp_f32_e32 v114, v114
	v_mov_b32_dpp v149, v148 quad_perm:[2,3,0,1] row_mask:0xf bank_mask:0xf bound_ctrl:1
	v_max_f32_e32 v149, v149, v149
	v_max_f32_e32 v148, v148, v149
	s_nop 1
	v_mov_b32_dpp v149, v148 row_half_mirror row_mask:0xf bank_mask:0xf bound_ctrl:1
	v_max_f32_e32 v149, v149, v149
	v_max_f32_e32 v148, v148, v149
	s_nop 1
	v_mov_b32_dpp v149, v148 row_ror:8 row_mask:0xf bank_mask:0xf bound_ctrl:1
	v_max3_f32 v195, v170, v148, v149
	v_sub_f32_e32 v115, v115, v195
	v_exp_f32_e32 v115, v115
	s_and_saveexec_b64 s[4:5], vcc
	ds_write_b128 v191, v[112:115] offset:34816
	s_or_b64 exec, exec, s[4:5]
	s_cmp_eq_u32 s53, 0
	s_cbranch_scc1 .LBB0_433
	ds_read_b128 v[196:199], v173 offset:35328
	ds_read_b128 v[200:203], v173 offset:35344
	ds_read_b128 v[204:207], v173 offset:35392
	ds_read_b128 v[208:211], v173 offset:35408
	ds_read_b128 v[212:215], v173 offset:35456
	ds_read_b128 v[216:219], v173 offset:35472
	ds_read_b128 v[220:223], v173 offset:35520
	ds_read_b128 v[164:167], v173 offset:35536
	ds_read_b128 v[224:227], v173 offset:35584
	ds_read_b128 v[160:163], v173 offset:35600
	ds_read_b128 v[228:231], v173 offset:35648
	ds_read_b128 v[156:159], v173 offset:35664
	ds_read_b128 v[232:235], v173 offset:35712
	ds_read_b128 v[152:155], v173 offset:35728
	ds_read_b128 v[236:239], v173 offset:35776
	ds_read_b128 v[148:151], v173 offset:35792
	s_waitcnt lgkmcnt(14)
	v_fmac_f32_e32 v10, v200, v110
	v_fmac_f32_e32 v11, v200, v111
	v_fmac_f32_e32 v8, v200, v108
	v_fmac_f32_e32 v9, v200, v109
	v_fmac_f32_e32 v22, v201, v110
	v_fmac_f32_e32 v23, v201, v111
	v_fmac_f32_e32 v20, v201, v108
	v_fmac_f32_e32 v21, v201, v109
	s_waitcnt lgkmcnt(12)
	v_fmac_f32_e32 v10, v208, v102
	v_fmac_f32_e32 v11, v208, v103
	v_fmac_f32_e32 v8, v208, v100
	v_fmac_f32_e32 v9, v208, v101
	v_fmac_f32_e32 v22, v209, v102
	v_fmac_f32_e32 v23, v209, v103
	v_fmac_f32_e32 v20, v209, v100
	v_fmac_f32_e32 v21, v209, v101
	s_waitcnt lgkmcnt(10)
	v_fmac_f32_e32 v10, v216, v70
	v_fmac_f32_e32 v11, v216, v71
	v_fmac_f32_e32 v8, v216, v68
	v_fmac_f32_e32 v9, v216, v69
	v_fmac_f32_e32 v22, v217, v70
	v_fmac_f32_e32 v23, v217, v71
	v_fmac_f32_e32 v20, v217, v68
	v_fmac_f32_e32 v21, v217, v69
	s_waitcnt lgkmcnt(8)
	v_fmac_f32_e32 v10, v164, v66
	v_fmac_f32_e32 v11, v164, v67
	v_fmac_f32_e32 v8, v164, v64
	v_fmac_f32_e32 v9, v164, v65
	v_fmac_f32_e32 v22, v165, v66
	v_fmac_f32_e32 v23, v165, v67
	v_fmac_f32_e32 v20, v165, v64
	v_fmac_f32_e32 v21, v165, v65
	s_waitcnt lgkmcnt(6)
	v_fmac_f32_e32 v10, v160, v58
	v_fmac_f32_e32 v11, v160, v59
	v_fmac_f32_e32 v8, v160, v56
	v_fmac_f32_e32 v9, v160, v57
	v_fmac_f32_e32 v22, v161, v58
	v_fmac_f32_e32 v23, v161, v59
	v_fmac_f32_e32 v20, v161, v56
	v_fmac_f32_e32 v21, v161, v57
	s_waitcnt lgkmcnt(4)
	v_fmac_f32_e32 v10, v156, v42
	v_fmac_f32_e32 v11, v156, v43
	v_fmac_f32_e32 v8, v156, v40
	v_fmac_f32_e32 v9, v156, v41
	v_fmac_f32_e32 v22, v157, v42
	v_fmac_f32_e32 v23, v157, v43
	v_fmac_f32_e32 v20, v157, v40
	v_fmac_f32_e32 v21, v157, v41
	s_waitcnt lgkmcnt(2)
	v_fmac_f32_e32 v10, v152, v14
	v_fmac_f32_e32 v11, v152, v15
	v_fmac_f32_e32 v8, v152, v12
	v_fmac_f32_e32 v9, v152, v13
	v_fmac_f32_e32 v22, v153, v14
	v_fmac_f32_e32 v23, v153, v15
	v_fmac_f32_e32 v20, v153, v12
	v_fmac_f32_e32 v21, v153, v13
	s_waitcnt lgkmcnt(0)
	v_fmac_f32_e32 v10, v148, v2
	v_fmac_f32_e32 v11, v148, v3
	v_fmac_f32_e32 v8, v148, v0
	v_fmac_f32_e32 v9, v148, v1
	v_fmac_f32_e32 v22, v149, v2
	v_fmac_f32_e32 v23, v149, v3
	v_fmac_f32_e32 v20, v149, v0
	v_fmac_f32_e32 v21, v149, v1
	v_mov_b32_e32 v148, v199
	v_fmac_f32_e32 v38, v148, v110
	v_fmac_f32_e32 v39, v148, v111
	v_fmac_f32_e32 v36, v148, v108
	v_fmac_f32_e32 v37, v148, v109
	v_mov_b32_e32 v148, v207
	v_fmac_f32_e32 v38, v148, v102
	v_fmac_f32_e32 v39, v148, v103
	v_fmac_f32_e32 v36, v148, v100
	v_fmac_f32_e32 v37, v148, v101
	v_mov_b32_e32 v148, v215
	v_fmac_f32_e32 v38, v148, v70
	v_fmac_f32_e32 v39, v148, v71
	v_fmac_f32_e32 v36, v148, v68
	v_fmac_f32_e32 v37, v148, v69
	v_mov_b32_e32 v148, v223
	v_fmac_f32_e32 v38, v148, v66
	v_fmac_f32_e32 v39, v148, v67
	v_fmac_f32_e32 v36, v148, v64
	v_fmac_f32_e32 v37, v148, v65
	v_mov_b32_e32 v148, v227
	v_fmac_f32_e32 v38, v148, v58
	v_fmac_f32_e32 v39, v148, v59
	v_fmac_f32_e32 v36, v148, v56
	v_fmac_f32_e32 v37, v148, v57
	v_mov_b32_e32 v148, v231
	v_fmac_f32_e32 v38, v148, v42
	v_fmac_f32_e32 v39, v148, v43
	v_fmac_f32_e32 v36, v148, v40
	v_fmac_f32_e32 v37, v148, v41
	v_mov_b32_e32 v148, v235
	v_fmac_f32_e32 v38, v148, v14
	v_fmac_f32_e32 v39, v148, v15
	v_fmac_f32_e32 v36, v148, v12
	v_fmac_f32_e32 v37, v148, v13
	v_mov_b32_e32 v148, v239
	v_fmac_f32_e32 v38, v148, v2
	v_fmac_f32_e32 v39, v148, v3
	v_fmac_f32_e32 v36, v148, v0
	v_fmac_f32_e32 v37, v148, v1
	v_mov_b32_e32 v148, v203
	v_fmac_f32_e32 v6, v196, v110
	v_fmac_f32_e32 v7, v196, v111
	v_fmac_f32_e32 v4, v196, v108
	v_fmac_f32_e32 v5, v196, v109
	v_fmac_f32_e32 v18, v197, v110
	v_fmac_f32_e32 v19, v197, v111
	v_fmac_f32_e32 v16, v197, v108
	v_fmac_f32_e32 v17, v197, v109
	v_fmac_f32_e32 v30, v198, v110
	v_fmac_f32_e32 v31, v198, v111
	v_fmac_f32_e32 v28, v198, v108
	v_fmac_f32_e32 v29, v198, v109
	v_fmac_f32_e32 v34, v202, v110
	v_fmac_f32_e32 v35, v202, v111
	v_fmac_f32_e32 v32, v202, v108
	v_fmac_f32_e32 v33, v202, v109
	v_fmac_f32_e32 v46, v148, v110
	v_fmac_f32_e32 v47, v148, v111
	v_fmac_f32_e32 v44, v148, v108
	v_fmac_f32_e32 v45, v148, v109
	v_mov_b32_e32 v108, v211
	v_fmac_f32_e32 v6, v204, v102
	v_fmac_f32_e32 v7, v204, v103
	v_fmac_f32_e32 v4, v204, v100
	v_fmac_f32_e32 v5, v204, v101
	v_fmac_f32_e32 v18, v205, v102
	v_fmac_f32_e32 v19, v205, v103
	v_fmac_f32_e32 v16, v205, v100
	v_fmac_f32_e32 v17, v205, v101
	v_fmac_f32_e32 v30, v206, v102
	v_fmac_f32_e32 v31, v206, v103
	v_fmac_f32_e32 v28, v206, v100
	v_fmac_f32_e32 v29, v206, v101
	v_fmac_f32_e32 v34, v210, v102
	v_fmac_f32_e32 v35, v210, v103
	v_fmac_f32_e32 v32, v210, v100
	v_fmac_f32_e32 v33, v210, v101
	v_fmac_f32_e32 v46, v108, v102
	v_fmac_f32_e32 v47, v108, v103
	v_fmac_f32_e32 v44, v108, v100
	v_fmac_f32_e32 v45, v108, v101
	v_mov_b32_e32 v100, v219
	v_fmac_f32_e32 v6, v212, v70
	v_fmac_f32_e32 v7, v212, v71
	v_fmac_f32_e32 v4, v212, v68
	v_fmac_f32_e32 v5, v212, v69
	v_fmac_f32_e32 v18, v213, v70
	v_fmac_f32_e32 v19, v213, v71
	v_fmac_f32_e32 v16, v213, v68
	v_fmac_f32_e32 v17, v213, v69
	v_fmac_f32_e32 v30, v214, v70
	v_fmac_f32_e32 v31, v214, v71
	v_fmac_f32_e32 v28, v214, v68
	v_fmac_f32_e32 v29, v214, v69
	v_fmac_f32_e32 v34, v218, v70
	v_fmac_f32_e32 v35, v218, v71
	v_fmac_f32_e32 v32, v218, v68
	v_fmac_f32_e32 v33, v218, v69
	v_fmac_f32_e32 v46, v100, v70
	v_fmac_f32_e32 v47, v100, v71
	v_fmac_f32_e32 v44, v100, v68
	v_fmac_f32_e32 v45, v100, v69
	v_mov_b32_e32 v68, v167
	v_fmac_f32_e32 v6, v220, v66
	v_fmac_f32_e32 v7, v220, v67
	v_fmac_f32_e32 v4, v220, v64
	v_fmac_f32_e32 v5, v220, v65
	v_fmac_f32_e32 v18, v221, v66
	v_fmac_f32_e32 v19, v221, v67
	v_fmac_f32_e32 v16, v221, v64
	v_fmac_f32_e32 v17, v221, v65
	v_fmac_f32_e32 v30, v222, v66
	v_fmac_f32_e32 v31, v222, v67
	v_fmac_f32_e32 v28, v222, v64
	v_fmac_f32_e32 v29, v222, v65
	v_fmac_f32_e32 v34, v166, v66
	v_fmac_f32_e32 v35, v166, v67
	v_fmac_f32_e32 v32, v166, v64
	v_fmac_f32_e32 v33, v166, v65
	v_fmac_f32_e32 v46, v68, v66
	v_fmac_f32_e32 v47, v68, v67
	v_fmac_f32_e32 v44, v68, v64
	v_fmac_f32_e32 v45, v68, v65
	v_mov_b32_e32 v64, v163
	v_fmac_f32_e32 v6, v224, v58
	v_fmac_f32_e32 v7, v224, v59
	v_fmac_f32_e32 v4, v224, v56
	v_fmac_f32_e32 v5, v224, v57
	v_fmac_f32_e32 v18, v225, v58
	v_fmac_f32_e32 v19, v225, v59
	v_fmac_f32_e32 v16, v225, v56
	v_fmac_f32_e32 v17, v225, v57
	v_fmac_f32_e32 v30, v226, v58
	v_fmac_f32_e32 v31, v226, v59
	v_fmac_f32_e32 v28, v226, v56
	v_fmac_f32_e32 v29, v226, v57
	v_fmac_f32_e32 v34, v162, v58
	v_fmac_f32_e32 v35, v162, v59
	v_fmac_f32_e32 v32, v162, v56
	v_fmac_f32_e32 v33, v162, v57
	v_fmac_f32_e32 v46, v64, v58
	v_fmac_f32_e32 v47, v64, v59
	v_fmac_f32_e32 v44, v64, v56
	v_fmac_f32_e32 v45, v64, v57
	v_mov_b32_e32 v56, v159
	v_fmac_f32_e32 v6, v228, v42
	v_fmac_f32_e32 v7, v228, v43
	v_fmac_f32_e32 v4, v228, v40
	v_fmac_f32_e32 v5, v228, v41
	v_fmac_f32_e32 v18, v229, v42
	v_fmac_f32_e32 v19, v229, v43
	v_fmac_f32_e32 v16, v229, v40
	v_fmac_f32_e32 v17, v229, v41
	v_fmac_f32_e32 v30, v230, v42
	v_fmac_f32_e32 v31, v230, v43
	v_fmac_f32_e32 v28, v230, v40
	v_fmac_f32_e32 v29, v230, v41
	v_fmac_f32_e32 v34, v158, v42
	v_fmac_f32_e32 v35, v158, v43
	v_fmac_f32_e32 v32, v158, v40
	v_fmac_f32_e32 v33, v158, v41
	v_fma_f32 v42, v56, v42, v46
	v_fma_f32 v43, v56, v43, v47
	v_fma_f32 v40, v56, v40, v44
	v_fma_f32 v41, v56, v41, v45
	v_mov_b32_e32 v44, v155
	v_fmac_f32_e32 v6, v232, v14
	v_fmac_f32_e32 v7, v232, v15
	v_fmac_f32_e32 v4, v232, v12
	v_fmac_f32_e32 v5, v232, v13
	v_fmac_f32_e32 v18, v233, v14
	v_fmac_f32_e32 v19, v233, v15
	v_fmac_f32_e32 v16, v233, v12
	v_fmac_f32_e32 v17, v233, v13
	v_fmac_f32_e32 v30, v234, v14
	v_fmac_f32_e32 v31, v234, v15
	v_fmac_f32_e32 v28, v234, v12
	v_fmac_f32_e32 v29, v234, v13
	v_fmac_f32_e32 v34, v154, v14
	v_fmac_f32_e32 v35, v154, v15
	v_fmac_f32_e32 v32, v154, v12
	v_fmac_f32_e32 v33, v154, v13
	v_fma_f32 v14, v44, v14, v42
	v_fma_f32 v15, v44, v15, v43
	v_fma_f32 v12, v44, v12, v40
	v_fma_f32 v13, v44, v13, v41
	v_mov_b32_e32 v40, v151
	v_fmac_f32_e32 v6, v236, v2
	v_fmac_f32_e32 v7, v236, v3
	v_fmac_f32_e32 v4, v236, v0
	v_fmac_f32_e32 v5, v236, v1
	v_fmac_f32_e32 v18, v237, v2
	v_fmac_f32_e32 v19, v237, v3
	v_fmac_f32_e32 v16, v237, v0
	v_fmac_f32_e32 v17, v237, v1
	v_fmac_f32_e32 v30, v238, v2
	v_fmac_f32_e32 v31, v238, v3
	v_fmac_f32_e32 v28, v238, v0
	v_fmac_f32_e32 v29, v238, v1
	v_fmac_f32_e32 v34, v150, v2
	v_fmac_f32_e32 v35, v150, v3
	v_fmac_f32_e32 v32, v150, v0
	v_fmac_f32_e32 v33, v150, v1
	v_fma_f32 v46, v40, v2, v14
	v_fma_f32 v47, v40, v3, v15
	v_fma_f32 v44, v40, v0, v12
	v_fma_f32 v45, v40, v1, v13
.LBB0_433:
	s_add_u32 s4, s10, s42
	v_sub_f32_e32 v0, v172, v192
	s_addc_u32 s5, s11, s43
	v_exp_f32_e32 v152, v0
	v_sub_f32_e32 v0, v178, v193
	s_add_u32 s42, s4, s46
	v_exp_f32_e32 v153, v0
	v_sub_f32_e32 v0, v180, v194
	s_addc_u32 s43, s5, 0
	v_exp_f32_e32 v154, v0
	v_lshl_add_u64 v[0:1], s[42:43], 0, v[168:169]
	v_add_co_u32_e64 v2, s[4:5], s13, v0
	v_mov_b32_e32 v183, v182
	s_nop 0
	v_addc_co_u32_e64 v3, s[4:5], 0, v1, s[4:5]
	global_load_dwordx4 v[100:103], v[2:3], off offset:-4096 nt
	global_load_dwordx4 v[68:71], v[2:3], off nt
	v_add_co_u32_e64 v2, s[4:5], s14, v0
	v_sub_f32_e32 v155, v170, v195
	s_nop 0
	v_addc_co_u32_e64 v3, s[4:5], 0, v1, s[4:5]
	global_load_dwordx4 v[64:67], v[2:3], off offset:-4096 nt
	global_load_dwordx4 v[56:59], v[2:3], off nt
	v_add_co_u32_e64 v2, s[4:5], s15, v0
	v_exp_f32_e32 v155, v155
	s_nop 0
	v_addc_co_u32_e64 v3, s[4:5], 0, v1, s[4:5]
	v_add_co_u32_e64 v0, s[4:5], s26, v0
	global_load_dwordx4 v[40:43], v[2:3], off offset:-4096 nt
	global_load_dwordx4 v[12:15], v[2:3], off nt
	v_addc_co_u32_e64 v1, s[4:5], 0, v1, s[4:5]
	s_min_u32 s4, s53, 29
	global_load_dwordx4 v[108:111], v168, s[42:43] nt
	s_nop 0
	global_load_dwordx4 v[0:3], v[0:1], off nt
	s_add_i32 s42, s4, 2
	s_lshr_b32 s4, s42, 3
	s_cmp_eq_u32 s4, 2
	s_cselect_b32 s5, s47, s49
	s_cmp_eq_u32 s4, 1
	s_cselect_b32 s4, s41, s5
	s_cmp_lt_u32 s53, 6
	s_cselect_b32 s4, s40, s4
	s_ashr_i32 s5, s4, 31
	s_lshl_b32 s42, s42, 15
	s_and_b32 s55, s42, 0x38000
	s_lshl_b64 s[42:43], s[4:5], 18
	s_add_u32 s4, s8, s42
	s_addc_u32 s5, s9, s43
	s_add_u32 s56, s4, s55
	s_waitcnt lgkmcnt(0)
	s_waitcnt vmcnt(9)
	v_cvt_pk_bf16_f32 v144, v144, v145
	v_cvt_pk_bf16_f32 v145, v146, v147
	ds_write_b64 v181, v[144:145] offset:43008
	v_cvt_pk_bf16_f32 v140, v140, v141
	v_cvt_pk_bf16_f32 v141, v142, v143
	ds_write_b64 v181, v[140:141] offset:43552
	v_cvt_pk_bf16_f32 v136, v136, v137
	v_cvt_pk_bf16_f32 v137, v138, v139
	ds_write_b64 v181, v[136:137] offset:44096
	v_cvt_pk_bf16_f32 v132, v132, v133
	v_cvt_pk_bf16_f32 v133, v134, v135
	ds_write_b64 v181, v[132:133] offset:44640
	v_cvt_pk_bf16_f32 v128, v128, v129
	v_cvt_pk_bf16_f32 v129, v130, v131
	ds_write_b64 v181, v[128:129] offset:45184
	v_cvt_pk_bf16_f32 v124, v124, v125
	v_cvt_pk_bf16_f32 v125, v126, v127
	ds_write_b64 v181, v[124:125] offset:45728
	v_cvt_pk_bf16_f32 v120, v120, v121
	v_cvt_pk_bf16_f32 v121, v122, v123
	ds_write_b64 v181, v[120:121] offset:46272
	s_waitcnt vmcnt(8)
	v_cvt_pk_bf16_f32 v116, v116, v117
	v_cvt_pk_bf16_f32 v117, v118, v119
	s_addc_u32 s57, s5, 0
	ds_write_b64 v181, v[116:117] offset:46816
	v_lshl_add_u64 v[116:117], s[56:57], 0, v[168:169]
	v_add_co_u32_e64 v118, s[4:5], s13, v116
	v_readlane_b32 s48, v152, 0
	s_nop 0
	v_addc_co_u32_e64 v119, s[4:5], 0, v117, s[4:5]
	global_load_dwordx4 v[140:143], v[118:119], off offset:-4096 nt
	global_load_dwordx4 v[136:139], v[118:119], off nt
	v_add_co_u32_e64 v118, s[4:5], s14, v116
	v_readlane_b32 s46, v152, 16
	s_nop 0
	v_addc_co_u32_e64 v119, s[4:5], 0, v117, s[4:5]
	global_load_dwordx4 v[132:135], v[118:119], off offset:-4096 nt
	global_load_dwordx4 v[128:131], v[118:119], off nt
	v_add_co_u32_e64 v118, s[4:5], s15, v116
	v_readlane_b32 s54, v154, 16
	s_nop 0
	v_addc_co_u32_e64 v119, s[4:5], 0, v117, s[4:5]
	v_add_co_u32_e64 v116, s[4:5], s26, v116
	global_load_dwordx4 v[124:127], v[118:119], off offset:-4096 nt
	global_load_dwordx4 v[120:123], v[118:119], off nt
	v_addc_co_u32_e64 v117, s[4:5], 0, v117, s[4:5]
	global_load_dwordx4 v[144:147], v168, s[56:57] nt
	s_nop 0
	global_load_dwordx4 v[116:119], v[116:117], off nt
	s_or_b32 s4, s44, s16
	v_add_u32_e32 v148, s4, v179
	v_add_u32_e32 v149, -1, v148
	v_add_u32_e32 v150, -2, v148
	v_add_u32_e32 v151, -3, v148
	s_waitcnt lgkmcnt(0)
	v_cvt_f32_i32_e32 v160, v148
	v_cvt_f32_i32_e32 v161, v149
	v_cvt_f32_i32_e32 v163, v151
	v_cvt_f32_i32_e32 v162, v150
	ds_read_b128 v[148:151], v190 offset:43008
	ds_read_b128 v[156:159], v190 offset:43072
	v_mul_f32_e32 v160, v184, v160
	v_mul_f32_e32 v161, v185, v161
	v_readlane_b32 s44, v153, 0
	v_mul_f32_e32 v162, v182, v162
	v_mul_f32_e32 v163, v183, v163
	v_readlane_b32 s16, v153, 16
	v_readlane_b32 s4, v154, 0
	s_waitcnt lgkmcnt(1)
	v_mfma_f32_16x16x32_bf16 v[148:151], v[24:27], v[148:151], v[160:163]
	v_readlane_b32 s52, v155, 0
	v_readlane_b32 s50, v155, 16
	s_nop 0
	ds_read_b128 v[160:163], v190 offset:43136
	s_waitcnt lgkmcnt(1)
	v_mfma_f32_16x16x32_bf16 v[148:151], v[48:51], v[156:159], v[148:151]
	ds_read_b128 v[156:159], v190 offset:43200
	s_waitcnt lgkmcnt(1)
	v_mfma_f32_16x16x32_bf16 v[148:151], v[52:55], v[160:163], v[148:151]
	s_waitcnt lgkmcnt(0)
	v_mfma_f32_16x16x32_bf16 v[148:151], v[60:63], v[156:159], v[148:151]
	s_nop 7
	v_mov_b32_dpp v156, v148 quad_perm:[1,0,3,2] row_mask:0xf bank_mask:0xf bound_ctrl:1
	v_max_f32_e32 v157, v148, v148
	v_max_f32_e32 v156, v156, v156
	v_max_f32_e32 v156, v157, v156
	s_nop 1
	v_mov_b32_dpp v157, v156 quad_perm:[2,3,0,1] row_mask:0xf bank_mask:0xf bound_ctrl:1
	v_max_f32_e32 v157, v157, v157
	v_max_f32_e32 v156, v156, v157
	s_nop 1
	v_mov_b32_dpp v157, v156 row_half_mirror row_mask:0xf bank_mask:0xf bound_ctrl:1
	v_max_f32_e32 v157, v157, v157
	v_max_f32_e32 v156, v156, v157
	s_nop 1
	v_mov_b32_dpp v157, v156 row_ror:8 row_mask:0xf bank_mask:0xf bound_ctrl:1
	v_max3_f32 v172, v192, v156, v157
	v_mov_b32_dpp v156, v149 quad_perm:[1,0,3,2] row_mask:0xf bank_mask:0xf bound_ctrl:1
	v_max_f32_e32 v157, v149, v149
	v_max_f32_e32 v156, v156, v156
	v_max_f32_e32 v156, v157, v156
	v_sub_f32_e32 v148, v148, v172
	v_exp_f32_e32 v148, v148
	v_mov_b32_dpp v157, v156 quad_perm:[2,3,0,1] row_mask:0xf bank_mask:0xf bound_ctrl:1
	v_max_f32_e32 v157, v157, v157
	v_max_f32_e32 v156, v156, v157
	s_nop 1
	v_mov_b32_dpp v157, v156 row_half_mirror row_mask:0xf bank_mask:0xf bound_ctrl:1
	v_max_f32_e32 v157, v157, v157
	v_max_f32_e32 v156, v156, v157
	s_nop 1
	v_mov_b32_dpp v157, v156 row_ror:8 row_mask:0xf bank_mask:0xf bound_ctrl:1
	v_max3_f32 v178, v193, v156, v157
	v_mov_b32_dpp v156, v150 quad_perm:[1,0,3,2] row_mask:0xf bank_mask:0xf bound_ctrl:1
	v_max_f32_e32 v157, v150, v150
	v_max_f32_e32 v156, v156, v156
	v_max_f32_e32 v156, v157, v156
	v_sub_f32_e32 v149, v149, v178
	v_exp_f32_e32 v149, v149
	v_mov_b32_dpp v157, v156 quad_perm:[2,3,0,1] row_mask:0xf bank_mask:0xf bound_ctrl:1
	v_max_f32_e32 v157, v157, v157
	v_max_f32_e32 v156, v156, v157
	s_nop 1
	v_mov_b32_dpp v157, v156 row_half_mirror row_mask:0xf bank_mask:0xf bound_ctrl:1
	v_max_f32_e32 v157, v157, v157
	v_max_f32_e32 v156, v156, v157
	s_nop 1
	v_mov_b32_dpp v157, v156 row_ror:8 row_mask:0xf bank_mask:0xf bound_ctrl:1
	v_max3_f32 v180, v194, v156, v157
	v_mov_b32_dpp v156, v151 quad_perm:[1,0,3,2] row_mask:0xf bank_mask:0xf bound_ctrl:1
	v_max_f32_e32 v157, v151, v151
	v_max_f32_e32 v156, v156, v156
	v_max_f32_e32 v156, v157, v156
	v_sub_f32_e32 v150, v150, v180
	v_exp_f32_e32 v150, v150
	v_mov_b32_dpp v157, v156 quad_perm:[2,3,0,1] row_mask:0xf bank_mask:0xf bound_ctrl:1
	v_max_f32_e32 v157, v157, v157
	v_max_f32_e32 v156, v156, v157
	s_nop 1
	v_mov_b32_dpp v157, v156 row_half_mirror row_mask:0xf bank_mask:0xf bound_ctrl:1
	v_max_f32_e32 v157, v157, v157
	v_max_f32_e32 v156, v156, v157
	s_nop 1
	v_mov_b32_dpp v157, v156 row_ror:8 row_mask:0xf bank_mask:0xf bound_ctrl:1
	v_max3_f32 v170, v195, v156, v157
	v_sub_f32_e32 v151, v151, v170
	v_exp_f32_e32 v151, v151
	s_and_saveexec_b64 s[56:57], vcc
	ds_write_b128 v191, v[148:151] offset:35328
	s_or_b64 exec, exec, s[56:57]
	v_mul_f32_e32 v216, s48, v6
	v_mul_f32_e32 v217, s48, v7
	v_mul_f32_e32 v218, s48, v4
	v_mul_f32_e32 v219, s48, v5
	v_mul_f32_e32 v220, s46, v10
	v_mul_f32_e32 v221, s46, v11
	v_mul_f32_e32 v222, s46, v8
	v_mul_f32_e32 v223, s46, v9
	v_mul_f32_e32 v224, s44, v18
	v_mul_f32_e32 v225, s44, v19
	v_mul_f32_e32 v226, s44, v16
	v_mul_f32_e32 v227, s44, v17
	v_mul_f32_e32 v228, s16, v22
	v_mul_f32_e32 v229, s16, v23
	v_mul_f32_e32 v230, s16, v20
	v_mul_f32_e32 v231, s16, v21
	v_mul_f32_e32 v232, s4, v30
	v_mul_f32_e32 v233, s4, v31
	v_mul_f32_e32 v234, s4, v28
	v_mul_f32_e32 v235, s4, v29
	v_mul_f32_e32 v236, s54, v34
	v_mul_f32_e32 v237, s54, v35
	v_mul_f32_e32 v238, s54, v32
	v_mul_f32_e32 v239, s54, v33
	v_mul_f32_e32 v240, s52, v38
	v_mul_f32_e32 v241, s52, v39
	v_mul_f32_e32 v242, s52, v36
	v_mul_f32_e32 v243, s52, v37
	v_mul_f32_e32 v244, s50, v46
	v_mul_f32_e32 v245, s50, v47
	v_mul_f32_e32 v246, s50, v44
	v_mul_f32_e32 v247, s50, v45
	ds_read_b128 v[4:7], v173 offset:34816
	ds_read_b128 v[8:11], v173 offset:34832
	ds_read_b128 v[16:19], v173 offset:34880
	ds_read_b128 v[20:23], v173 offset:34896
	ds_read_b128 v[28:31], v173 offset:34944
	ds_read_b128 v[32:35], v173 offset:34960
	ds_read_b128 v[36:39], v173 offset:35008
	ds_read_b128 v[44:47], v173 offset:35024
	ds_read_b128 v[156:159], v173 offset:35072
	ds_read_b128 v[160:163], v173 offset:35088
	ds_read_b128 v[164:167], v173 offset:35136
	ds_read_b128 v[196:199], v173 offset:35152
	ds_read_b128 v[200:203], v173 offset:35200
	ds_read_b128 v[204:207], v173 offset:35216
	ds_read_b128 v[208:211], v173 offset:35264
	ds_read_b128 v[212:215], v173 offset:35280
	s_waitcnt lgkmcnt(14)
	v_fmac_f32_e32 v216, v4, v74
	v_fmac_f32_e32 v217, v4, v75
	v_fmac_f32_e32 v218, v4, v72
	v_fmac_f32_e32 v219, v4, v73
	v_fmac_f32_e32 v224, v5, v74
	v_fmac_f32_e32 v225, v5, v75
	v_fma_f32 v4, v5, v72, v226
	v_fma_f32 v5, v5, v73, v227
	s_waitcnt lgkmcnt(13)
	v_fmac_f32_e32 v218, v16, v80
	v_fmac_f32_e32 v219, v16, v81
	v_fmac_f32_e32 v4, v17, v80
	v_fmac_f32_e32 v5, v17, v81
	v_fmac_f32_e32 v216, v16, v82
	v_fmac_f32_e32 v217, v16, v83
	s_waitcnt lgkmcnt(11)
	v_fmac_f32_e32 v4, v29, v76
	v_fmac_f32_e32 v5, v29, v77
	v_fma_f32 v16, v17, v82, v224
	v_fma_f32 v17, v17, v83, v225
	s_waitcnt lgkmcnt(9)
	v_fmac_f32_e32 v4, v37, v88
	v_fmac_f32_e32 v5, v37, v89
	v_fmac_f32_e32 v216, v28, v78
	v_fmac_f32_e32 v217, v28, v79
	s_waitcnt lgkmcnt(7)
	v_fmac_f32_e32 v4, v157, v84
	v_fmac_f32_e32 v5, v157, v85
	v_fmac_f32_e32 v218, v28, v76
	v_fmac_f32_e32 v219, v28, v77
	s_waitcnt lgkmcnt(5)
	v_fmac_f32_e32 v4, v165, v96
	v_fmac_f32_e32 v5, v165, v97
	v_fmac_f32_e32 v16, v29, v78
	v_fmac_f32_e32 v17, v29, v79
	s_waitcnt lgkmcnt(3)
	v_fmac_f32_e32 v4, v201, v92
	v_fmac_f32_e32 v5, v201, v93
	v_fmac_f32_e32 v220, v8, v74
	v_fmac_f32_e32 v221, v8, v75
	s_waitcnt lgkmcnt(1)
	v_fma_f32 v28, v209, v104, v4
	v_fma_f32 v29, v209, v105, v5
	v_fma_f32 v4, v9, v74, v228
	v_fma_f32 v5, v9, v75, v229
	v_fmac_f32_e32 v222, v8, v72
	v_fmac_f32_e32 v223, v8, v73
	v_fma_f32 v8, v9, v72, v230
	v_fma_f32 v9, v9, v73, v231
	v_fmac_f32_e32 v4, v21, v82
	v_fmac_f32_e32 v5, v21, v83
	v_fmac_f32_e32 v8, v21, v80
	v_fmac_f32_e32 v9, v21, v81
	v_fmac_f32_e32 v4, v33, v78
	v_fmac_f32_e32 v5, v33, v79
	v_fmac_f32_e32 v8, v33, v76
	v_fmac_f32_e32 v9, v33, v77
	v_fmac_f32_e32 v4, v45, v90
	v_fmac_f32_e32 v5, v45, v91
	v_fmac_f32_e32 v8, v45, v88
	v_fmac_f32_e32 v9, v45, v89
	v_fmac_f32_e32 v4, v161, v86
	v_fmac_f32_e32 v5, v161, v87
	v_fmac_f32_e32 v8, v161, v84
	v_fmac_f32_e32 v9, v161, v85
	v_fmac_f32_e32 v4, v197, v98
	v_fmac_f32_e32 v5, v197, v99
	v_fmac_f32_e32 v222, v20, v80
	v_fmac_f32_e32 v223, v20, v81
	v_fmac_f32_e32 v220, v20, v82
	v_fmac_f32_e32 v221, v20, v83
	v_fmac_f32_e32 v8, v197, v96
	v_fmac_f32_e32 v9, v197, v97
	v_fmac_f32_e32 v4, v205, v94
	v_fmac_f32_e32 v5, v205, v95
	v_fmac_f32_e32 v220, v32, v78
	v_fmac_f32_e32 v221, v32, v79
	v_fmac_f32_e32 v222, v32, v76
	v_fmac_f32_e32 v223, v32, v77
	v_fmac_f32_e32 v8, v205, v92
	v_fmac_f32_e32 v9, v205, v93
	s_waitcnt lgkmcnt(0)
	v_fma_f32 v32, v213, v106, v4
	v_fma_f32 v33, v213, v107, v5
	v_fma_f32 v4, v6, v74, v232
	v_fma_f32 v5, v6, v75, v233
	v_fma_f32 v20, v213, v104, v8
	v_fma_f32 v21, v213, v105, v9
	v_fma_f32 v8, v6, v72, v234
	v_fma_f32 v9, v6, v73, v235
	v_fmac_f32_e32 v4, v18, v82
	v_fmac_f32_e32 v5, v18, v83
	v_fmac_f32_e32 v8, v18, v80
	v_fmac_f32_e32 v9, v18, v81
	v_fmac_f32_e32 v4, v30, v78
	v_fmac_f32_e32 v5, v30, v79
	v_fmac_f32_e32 v8, v30, v76
	v_fmac_f32_e32 v9, v30, v77
	v_fmac_f32_e32 v4, v38, v90
	v_fmac_f32_e32 v5, v38, v91
	v_fmac_f32_e32 v8, v38, v88
	v_fmac_f32_e32 v9, v38, v89
	v_fmac_f32_e32 v4, v158, v86
	v_fmac_f32_e32 v5, v158, v87
	v_fmac_f32_e32 v8, v158, v84
	v_fmac_f32_e32 v9, v158, v85
	v_fmac_f32_e32 v4, v166, v98
	v_fmac_f32_e32 v5, v166, v99
	v_fmac_f32_e32 v8, v166, v96
	v_fmac_f32_e32 v9, v166, v97
	v_fmac_f32_e32 v4, v202, v94
	v_fmac_f32_e32 v5, v202, v95
	v_fmac_f32_e32 v222, v44, v88
	v_fmac_f32_e32 v223, v44, v89
	v_fmac_f32_e32 v220, v44, v90
	v_fmac_f32_e32 v221, v44, v91
	v_fmac_f32_e32 v8, v202, v92
	v_fmac_f32_e32 v9, v202, v93
	v_fma_f32 v44, v210, v106, v4
	v_fma_f32 v45, v210, v107, v5
	v_fma_f32 v4, v10, v74, v236
	v_fma_f32 v5, v10, v75, v237
	v_fmac_f32_e32 v218, v36, v88
	v_fmac_f32_e32 v219, v36, v89
	v_fmac_f32_e32 v216, v36, v90
	v_fmac_f32_e32 v217, v36, v91
	v_fmac_f32_e32 v16, v37, v90
	v_fmac_f32_e32 v17, v37, v91
	v_fma_f32 v36, v210, v104, v8
	v_fma_f32 v37, v210, v105, v9
	v_fma_f32 v8, v10, v72, v238
	v_fma_f32 v9, v10, v73, v239
	v_fmac_f32_e32 v4, v22, v82
	v_fmac_f32_e32 v5, v22, v83
	v_fmac_f32_e32 v8, v22, v80
	v_fmac_f32_e32 v9, v22, v81
	v_fmac_f32_e32 v4, v34, v78
	v_fmac_f32_e32 v5, v34, v79
	v_fmac_f32_e32 v8, v34, v76
	v_fmac_f32_e32 v9, v34, v77
	v_fmac_f32_e32 v4, v46, v90
	v_fmac_f32_e32 v5, v46, v91
	v_fmac_f32_e32 v8, v46, v88
	v_fmac_f32_e32 v9, v46, v89
	v_fmac_f32_e32 v4, v162, v86
	v_fmac_f32_e32 v5, v162, v87
	v_fmac_f32_e32 v8, v162, v84
	v_fmac_f32_e32 v9, v162, v85
	v_fmac_f32_e32 v4, v198, v98
	v_fmac_f32_e32 v5, v198, v99
	v_fmac_f32_e32 v8, v198, v96
	v_fmac_f32_e32 v9, v198, v97
	v_fmac_f32_e32 v4, v206, v94
	v_fmac_f32_e32 v5, v206, v95
	v_fmac_f32_e32 v220, v160, v86
	v_fmac_f32_e32 v221, v160, v87
	v_fmac_f32_e32 v222, v160, v84
	v_fmac_f32_e32 v223, v160, v85
	v_fmac_f32_e32 v8, v206, v92
	v_fmac_f32_e32 v9, v206, v93
	v_fma_f32 v160, v214, v106, v4
	v_fma_f32 v161, v214, v107, v5
	v_mov_b32_e32 v4, v7
	v_fmac_f32_e32 v216, v156, v86
	v_fmac_f32_e32 v217, v156, v87
	v_fmac_f32_e32 v218, v156, v84
	v_fmac_f32_e32 v219, v156, v85
	v_fmac_f32_e32 v16, v157, v86
	v_fmac_f32_e32 v17, v157, v87
	v_fma_f32 v156, v214, v104, v8
	v_fma_f32 v157, v214, v105, v9
	v_fma_f32 v6, v4, v74, v240
	v_fma_f32 v7, v4, v75, v241
	v_fma_f32 v5, v4, v73, v243
	v_fma_f32 v4, v4, v72, v242
	v_mov_b32_e32 v8, v19
	v_fmac_f32_e32 v4, v8, v80
	v_fmac_f32_e32 v5, v8, v81
	v_fmac_f32_e32 v6, v8, v82
	v_fmac_f32_e32 v7, v8, v83
	v_mov_b32_e32 v8, v31
	v_fmac_f32_e32 v6, v8, v78
	v_fmac_f32_e32 v7, v8, v79
	v_fmac_f32_e32 v4, v8, v76
	v_fmac_f32_e32 v5, v8, v77
	v_mov_b32_e32 v8, v39
	v_fmac_f32_e32 v4, v8, v88
	v_fmac_f32_e32 v5, v8, v89
	v_fmac_f32_e32 v6, v8, v90
	v_fmac_f32_e32 v7, v8, v91
	v_mov_b32_e32 v8, v159
	v_fmac_f32_e32 v6, v8, v86
	v_fmac_f32_e32 v7, v8, v87
	v_fmac_f32_e32 v4, v8, v84
	v_fmac_f32_e32 v5, v8, v85
	v_mov_b32_e32 v8, v167
	v_fmac_f32_e32 v4, v8, v96
	v_fmac_f32_e32 v5, v8, v97
	v_fmac_f32_e32 v6, v8, v98
	v_fmac_f32_e32 v7, v8, v99
	v_mov_b32_e32 v8, v203
	v_fmac_f32_e32 v6, v8, v94
	v_fmac_f32_e32 v7, v8, v95
	v_fmac_f32_e32 v4, v8, v92
	v_fmac_f32_e32 v5, v8, v93
	v_mov_b32_e32 v8, v211
	v_fma_f32 v158, v8, v104, v4
	v_fma_f32 v159, v8, v105, v5
	v_mov_b32_e32 v4, v11
	v_fma_f32 v38, v8, v106, v6
	v_fma_f32 v39, v8, v107, v7
	v_fma_f32 v6, v4, v74, v244
	v_fma_f32 v7, v4, v75, v245
	v_fma_f32 v5, v4, v73, v247
	v_fma_f32 v4, v4, v72, v246
	v_mov_b32_e32 v8, v23
	v_fmac_f32_e32 v4, v8, v80
	v_fmac_f32_e32 v5, v8, v81
	v_fmac_f32_e32 v6, v8, v82
	v_fmac_f32_e32 v7, v8, v83
	v_mov_b32_e32 v8, v35
	v_fmac_f32_e32 v6, v8, v78
	v_fmac_f32_e32 v7, v8, v79
	v_fmac_f32_e32 v4, v8, v76
	v_fmac_f32_e32 v5, v8, v77
	v_mov_b32_e32 v8, v47
	v_fmac_f32_e32 v4, v8, v88
	v_fmac_f32_e32 v5, v8, v89
	v_fmac_f32_e32 v6, v8, v90
	v_fmac_f32_e32 v7, v8, v91
	v_mov_b32_e32 v8, v163
	s_add_u32 s4, s10, s42
	v_fmac_f32_e32 v6, v8, v86
	v_fmac_f32_e32 v7, v8, v87
	v_fmac_f32_e32 v4, v8, v84
	v_fmac_f32_e32 v5, v8, v85
	v_mov_b32_e32 v8, v199
	s_addc_u32 s5, s11, s43
	v_fmac_f32_e32 v4, v8, v96
	v_fmac_f32_e32 v5, v8, v97
	v_fmac_f32_e32 v6, v8, v98
	v_fmac_f32_e32 v7, v8, v99
	v_mov_b32_e32 v8, v207
	s_add_u32 s42, s4, s55
	v_fmac_f32_e32 v6, v8, v94
	v_fmac_f32_e32 v7, v8, v95
	v_fmac_f32_e32 v4, v8, v92
	v_fmac_f32_e32 v5, v8, v93
	v_mov_b32_e32 v8, v215
	s_addc_u32 s43, s5, 0
	v_fma_f32 v162, v8, v104, v4
	v_fma_f32 v163, v8, v105, v5
	v_lshl_add_u64 v[4:5], s[42:43], 0, v[168:169]
	v_fma_f32 v46, v8, v106, v6
	v_fma_f32 v47, v8, v107, v7
	v_add_co_u32_e64 v6, s[4:5], s13, v4
	v_fmac_f32_e32 v218, v164, v96
	v_fmac_f32_e32 v219, v164, v97
	s_nop 0
	v_addc_co_u32_e64 v7, s[4:5], 0, v5, s[4:5]
	global_load_dwordx4 v[80:83], v[6:7], off offset:-4096 nt
	global_load_dwordx4 v[76:79], v[6:7], off nt
	v_add_co_u32_e64 v6, s[4:5], s14, v4
	v_fmac_f32_e32 v216, v164, v98
	v_fmac_f32_e32 v217, v164, v99
	s_nop 0
	v_addc_co_u32_e64 v7, s[4:5], 0, v5, s[4:5]
	global_load_dwordx4 v[88:91], v[6:7], off offset:-4096 nt
	global_load_dwordx4 v[84:87], v[6:7], off nt
	v_add_co_u32_e64 v6, s[4:5], s15, v4
	v_fmac_f32_e32 v222, v196, v96
	v_fmac_f32_e32 v223, v196, v97
	v_fmac_f32_e32 v220, v196, v98
	v_fmac_f32_e32 v221, v196, v99
	v_fmac_f32_e32 v16, v165, v98
	v_fmac_f32_e32 v17, v165, v99
	v_addc_co_u32_e64 v7, s[4:5], 0, v5, s[4:5]
	v_fmac_f32_e32 v216, v200, v94
	v_fmac_f32_e32 v217, v200, v95
	v_fmac_f32_e32 v218, v200, v92
	v_fmac_f32_e32 v219, v200, v93
	v_fmac_f32_e32 v220, v204, v94
	v_fmac_f32_e32 v221, v204, v95
	v_fmac_f32_e32 v222, v204, v92
	v_fmac_f32_e32 v223, v204, v93
	v_fmac_f32_e32 v16, v201, v94
	v_fmac_f32_e32 v17, v201, v95
	v_add_co_u32_e64 v4, s[4:5], s26, v4
	v_fmac_f32_e32 v218, v208, v104
	v_fmac_f32_e32 v219, v208, v105
	v_fmac_f32_e32 v216, v208, v106
	v_fmac_f32_e32 v217, v208, v107
	v_fmac_f32_e32 v222, v212, v104
	v_fmac_f32_e32 v223, v212, v105
	v_fmac_f32_e32 v220, v212, v106
	v_fmac_f32_e32 v221, v212, v107
	v_fmac_f32_e32 v16, v209, v106
	v_fmac_f32_e32 v17, v209, v107
	global_load_dwordx4 v[96:99], v[6:7], off offset:-4096 nt
	global_load_dwordx4 v[92:95], v[6:7], off nt
	v_addc_co_u32_e64 v5, s[4:5], 0, v5, s[4:5]
	global_load_dwordx4 v[72:75], v168, s[42:43] nt
	global_load_dwordx4 v[104:107], v[4:5], off nt
	v_sub_f32_e32 v4, v192, v172
	v_exp_f32_e32 v18, v4
	v_sub_f32_e32 v4, v193, v178
	v_exp_f32_e32 v19, v4
	v_sub_f32_e32 v4, v194, v180
	v_exp_f32_e32 v164, v4
	v_sub_f32_e32 v4, v195, v170
	v_exp_f32_e32 v165, v4
	v_fma_f32 v4, v174, v152, v112
	v_fma_f32 v5, v175, v153, v113
	v_fma_f32 v6, v176, v154, v114
	v_fma_f32 v7, v177, v155, v115
	v_readlane_b32 s4, v18, 0
	v_fma_f32 v174, v4, v18, v148
	v_fma_f32 v175, v5, v19, v149
	v_fma_f32 v176, v6, v164, v150
	v_fma_f32 v177, v7, v165, v151
	v_readlane_b32 s16, v18, 16
	v_mul_f32_e32 v6, s4, v216
	v_mul_f32_e32 v7, s4, v217
	v_mul_f32_e32 v4, s4, v218
	v_mul_f32_e32 v5, s4, v219
	v_readlane_b32 s4, v19, 0
	v_mul_f32_e32 v10, s16, v220
	v_mul_f32_e32 v11, s16, v221
	v_mul_f32_e32 v8, s16, v222
	v_mul_f32_e32 v9, s16, v223
	v_readlane_b32 s16, v19, 16
	v_mul_f32_e32 v18, s4, v16
	v_mul_f32_e32 v19, s4, v17
	v_mul_f32_e32 v16, s4, v28
	v_mul_f32_e32 v17, s4, v29
	v_readlane_b32 s4, v164, 0
	v_mul_f32_e32 v22, s16, v32
	v_mul_f32_e32 v23, s16, v33
	v_mul_f32_e32 v20, s16, v20
	v_mul_f32_e32 v21, s16, v21
	v_readlane_b32 s16, v164, 16
	v_mul_f32_e32 v30, s4, v44
	v_mul_f32_e32 v31, s4, v45
	v_mul_f32_e32 v28, s4, v36
	v_mul_f32_e32 v29, s4, v37
	v_readlane_b32 s4, v165, 0
	s_waitcnt lgkmcnt(0)
	v_mul_f32_e32 v34, s16, v160
	v_mul_f32_e32 v35, s16, v161
	v_mul_f32_e32 v32, s16, v156
	v_mul_f32_e32 v33, s16, v157
	v_readlane_b32 s16, v165, 16
	v_mul_f32_e32 v38, s4, v38
	v_mul_f32_e32 v39, s4, v39
	v_mul_f32_e32 v36, s4, v158
	v_mul_f32_e32 v37, s4, v159
	s_add_i32 s4, s53, 2
	s_add_i32 s51, s51, 32
	v_mul_f32_e32 v46, s16, v46
	v_mul_f32_e32 v47, s16, v47
	v_mul_f32_e32 v44, s16, v162
	v_mul_f32_e32 v45, s16, v163
	s_cmp_gt_u32 s53, 29
	s_cbranch_scc1 .LBB0_437
	s_mov_b32 s53, s4
	s_branch .LBB0_429
.LBB0_437:
	ds_read_b128 v[24:27], v173 offset:35328
	ds_read_b128 v[48:51], v173 offset:35344
	s_waitcnt vmcnt(17) lgkmcnt(1)
	v_fma_f32 v4, v24, v108, v4
	v_fmac_f32_e32 v5, v24, v109
	v_fma_f32 v6, v24, v110, v6
	v_fmac_f32_e32 v7, v24, v111
	s_waitcnt lgkmcnt(0)
	v_fma_f32 v8, v48, v108, v8
	v_fmac_f32_e32 v9, v48, v109
	v_fma_f32 v10, v48, v110, v10
	v_fmac_f32_e32 v11, v48, v111
	v_fma_f32 v16, v25, v108, v16
	v_fmac_f32_e32 v17, v25, v109
	v_fma_f32 v18, v25, v110, v18
	v_fmac_f32_e32 v19, v25, v111
	v_fma_f32 v20, v49, v108, v20
	v_fmac_f32_e32 v21, v49, v109
	v_fma_f32 v22, v49, v110, v22
	v_fmac_f32_e32 v23, v49, v111
	v_fma_f32 v28, v26, v108, v28
	v_fmac_f32_e32 v29, v26, v109
	v_fma_f32 v30, v26, v110, v30
	v_fmac_f32_e32 v31, v26, v111
	v_fma_f32 v32, v50, v108, v32
	v_fmac_f32_e32 v33, v50, v109
	v_fma_f32 v34, v50, v110, v34
	v_fmac_f32_e32 v35, v50, v111
	v_fma_f32 v36, v27, v108, v36
	v_fmac_f32_e32 v37, v27, v109
	v_fma_f32 v38, v27, v110, v38
	v_fmac_f32_e32 v39, v27, v111
	v_fma_f32 v44, v51, v108, v44
	ds_read_b128 v[24:27], v173 offset:35392
	v_fmac_f32_e32 v45, v51, v109
	v_fma_f32 v46, v51, v110, v46
	v_fmac_f32_e32 v47, v51, v111
	ds_read_b128 v[48:51], v173 offset:35408
	s_waitcnt lgkmcnt(1)
	v_fmac_f32_e32 v4, v24, v100
	v_fmac_f32_e32 v5, v24, v101
	v_fmac_f32_e32 v6, v24, v102
	v_fmac_f32_e32 v7, v24, v103
	s_waitcnt lgkmcnt(0)
	v_fmac_f32_e32 v8, v48, v100
	v_fmac_f32_e32 v9, v48, v101
	v_fmac_f32_e32 v10, v48, v102
	v_fmac_f32_e32 v11, v48, v103
	v_fmac_f32_e32 v16, v25, v100
	v_fmac_f32_e32 v17, v25, v101
	v_fmac_f32_e32 v18, v25, v102
	v_fmac_f32_e32 v19, v25, v103
	v_fmac_f32_e32 v20, v49, v100
	v_fmac_f32_e32 v21, v49, v101
	v_fmac_f32_e32 v22, v49, v102
	v_fmac_f32_e32 v23, v49, v103
	v_fmac_f32_e32 v28, v26, v100
	v_fmac_f32_e32 v29, v26, v101
	v_fmac_f32_e32 v30, v26, v102
	v_fmac_f32_e32 v31, v26, v103
	v_fmac_f32_e32 v32, v50, v100
	v_fmac_f32_e32 v33, v50, v101
	v_fmac_f32_e32 v34, v50, v102
	v_fmac_f32_e32 v35, v50, v103
	v_fmac_f32_e32 v36, v27, v100
	v_fmac_f32_e32 v37, v27, v101
	v_fmac_f32_e32 v38, v27, v102
	v_fmac_f32_e32 v39, v27, v103
	v_fmac_f32_e32 v44, v51, v100
	ds_read_b128 v[24:27], v173 offset:35456
	v_fmac_f32_e32 v45, v51, v101
	v_fmac_f32_e32 v46, v51, v102
	v_fmac_f32_e32 v47, v51, v103
	ds_read_b128 v[48:51], v173 offset:35472
	s_waitcnt lgkmcnt(1)
	v_fmac_f32_e32 v4, v24, v68
	v_fmac_f32_e32 v5, v24, v69
	v_fmac_f32_e32 v6, v24, v70
	v_fmac_f32_e32 v7, v24, v71
	s_waitcnt lgkmcnt(0)
	v_fmac_f32_e32 v8, v48, v68
	v_fmac_f32_e32 v9, v48, v69
	v_fmac_f32_e32 v10, v48, v70
	v_fmac_f32_e32 v11, v48, v71
	v_fmac_f32_e32 v16, v25, v68
	v_fmac_f32_e32 v17, v25, v69
	v_fmac_f32_e32 v18, v25, v70
	v_fmac_f32_e32 v19, v25, v71
	v_fmac_f32_e32 v20, v49, v68
	v_fmac_f32_e32 v21, v49, v69
	v_fmac_f32_e32 v22, v49, v70
	v_fmac_f32_e32 v23, v49, v71
	v_fmac_f32_e32 v28, v26, v68
	v_fmac_f32_e32 v29, v26, v69
	v_fmac_f32_e32 v30, v26, v70
	v_fmac_f32_e32 v31, v26, v71
	v_fmac_f32_e32 v32, v50, v68
	v_fmac_f32_e32 v33, v50, v69
	v_fmac_f32_e32 v34, v50, v70
	v_fmac_f32_e32 v35, v50, v71
	v_fmac_f32_e32 v36, v27, v68
	v_fmac_f32_e32 v37, v27, v69
	v_fmac_f32_e32 v38, v27, v70
	v_fmac_f32_e32 v39, v27, v71
	v_fmac_f32_e32 v44, v51, v68
	ds_read_b128 v[24:27], v173 offset:35520
	v_fmac_f32_e32 v45, v51, v69
	v_fmac_f32_e32 v46, v51, v70
	v_fmac_f32_e32 v47, v51, v71
	ds_read_b128 v[48:51], v173 offset:35536
	s_waitcnt lgkmcnt(1)
	v_fmac_f32_e32 v4, v24, v64
	v_fmac_f32_e32 v5, v24, v65
	v_fmac_f32_e32 v6, v24, v66
	v_fmac_f32_e32 v7, v24, v67
	s_waitcnt lgkmcnt(0)
	v_fmac_f32_e32 v8, v48, v64
	v_fmac_f32_e32 v9, v48, v65
	v_fmac_f32_e32 v10, v48, v66
	v_fmac_f32_e32 v11, v48, v67
	v_fmac_f32_e32 v16, v25, v64
	v_fmac_f32_e32 v17, v25, v65
	v_fmac_f32_e32 v18, v25, v66
	v_fmac_f32_e32 v19, v25, v67
	v_fmac_f32_e32 v20, v49, v64
	v_fmac_f32_e32 v21, v49, v65
	v_fmac_f32_e32 v22, v49, v66
	v_fmac_f32_e32 v23, v49, v67
	v_fmac_f32_e32 v28, v26, v64
	v_fmac_f32_e32 v29, v26, v65
	v_fmac_f32_e32 v30, v26, v66
	v_fmac_f32_e32 v31, v26, v67
	v_fmac_f32_e32 v32, v50, v64
	v_fmac_f32_e32 v33, v50, v65
	v_fmac_f32_e32 v34, v50, v66
	v_fmac_f32_e32 v35, v50, v67
	v_fmac_f32_e32 v36, v27, v64
	v_fmac_f32_e32 v37, v27, v65
	v_fmac_f32_e32 v38, v27, v66
	v_fmac_f32_e32 v39, v27, v67
	v_fmac_f32_e32 v44, v51, v64
	ds_read_b128 v[24:27], v173 offset:35584
	v_fmac_f32_e32 v45, v51, v65
	v_fmac_f32_e32 v46, v51, v66
	v_fmac_f32_e32 v47, v51, v67
	ds_read_b128 v[48:51], v173 offset:35600
	s_waitcnt lgkmcnt(1)
	v_fmac_f32_e32 v4, v24, v56
	v_fmac_f32_e32 v5, v24, v57
	v_fmac_f32_e32 v6, v24, v58
	v_fmac_f32_e32 v7, v24, v59
	s_waitcnt lgkmcnt(0)
	v_fmac_f32_e32 v8, v48, v56
	v_fmac_f32_e32 v9, v48, v57
	v_fmac_f32_e32 v10, v48, v58
	v_fmac_f32_e32 v11, v48, v59
	v_fmac_f32_e32 v16, v25, v56
	v_fmac_f32_e32 v17, v25, v57
	v_fmac_f32_e32 v18, v25, v58
	v_fmac_f32_e32 v19, v25, v59
	v_fmac_f32_e32 v20, v49, v56
	v_fmac_f32_e32 v21, v49, v57
	v_fmac_f32_e32 v22, v49, v58
	v_fmac_f32_e32 v23, v49, v59
	v_fmac_f32_e32 v28, v26, v56
	v_fmac_f32_e32 v29, v26, v57
	v_fmac_f32_e32 v30, v26, v58
	v_fmac_f32_e32 v31, v26, v59
	v_fmac_f32_e32 v32, v50, v56
	v_fmac_f32_e32 v33, v50, v57
	v_fmac_f32_e32 v34, v50, v58
	v_fmac_f32_e32 v35, v50, v59
	v_fmac_f32_e32 v36, v27, v56
	v_fmac_f32_e32 v37, v27, v57
	v_fmac_f32_e32 v38, v27, v58
	v_fmac_f32_e32 v39, v27, v59
	v_fmac_f32_e32 v44, v51, v56
	ds_read_b128 v[24:27], v173 offset:35648
	v_fmac_f32_e32 v45, v51, v57
	v_fmac_f32_e32 v46, v51, v58
	v_fmac_f32_e32 v47, v51, v59
	ds_read_b128 v[48:51], v173 offset:35664
	s_waitcnt lgkmcnt(1)
	v_fmac_f32_e32 v4, v24, v40
	v_fmac_f32_e32 v5, v24, v41
	v_fmac_f32_e32 v6, v24, v42
	v_fmac_f32_e32 v7, v24, v43
	s_waitcnt lgkmcnt(0)
	v_fmac_f32_e32 v8, v48, v40
	v_fmac_f32_e32 v9, v48, v41
	v_fmac_f32_e32 v10, v48, v42
	v_fmac_f32_e32 v11, v48, v43
	v_fmac_f32_e32 v16, v25, v40
	v_fmac_f32_e32 v17, v25, v41
	v_fmac_f32_e32 v18, v25, v42
	v_fmac_f32_e32 v19, v25, v43
	v_fmac_f32_e32 v20, v49, v40
	v_fmac_f32_e32 v21, v49, v41
	v_fmac_f32_e32 v22, v49, v42
	v_fmac_f32_e32 v23, v49, v43
	v_fmac_f32_e32 v28, v26, v40
	v_fmac_f32_e32 v29, v26, v41
	v_fmac_f32_e32 v30, v26, v42
	v_fmac_f32_e32 v31, v26, v43
	v_fmac_f32_e32 v32, v50, v40
	v_fmac_f32_e32 v33, v50, v41
	v_fmac_f32_e32 v34, v50, v42
	v_fmac_f32_e32 v35, v50, v43
	v_fmac_f32_e32 v36, v27, v40
	v_fmac_f32_e32 v37, v27, v41
	v_fmac_f32_e32 v38, v27, v42
	v_fmac_f32_e32 v39, v27, v43
	v_fmac_f32_e32 v44, v51, v40
	ds_read_b128 v[24:27], v173 offset:35712
	v_fmac_f32_e32 v45, v51, v41
	v_fmac_f32_e32 v46, v51, v42
	v_fmac_f32_e32 v47, v51, v43
	ds_read_b128 v[40:43], v173 offset:35728
	s_waitcnt lgkmcnt(1)
	v_fmac_f32_e32 v4, v24, v12
	v_fmac_f32_e32 v5, v24, v13
	v_fmac_f32_e32 v6, v24, v14
	v_fmac_f32_e32 v7, v24, v15
	s_waitcnt lgkmcnt(0)
	v_fmac_f32_e32 v8, v40, v12
	v_fmac_f32_e32 v9, v40, v13
	v_fmac_f32_e32 v10, v40, v14
	v_fmac_f32_e32 v11, v40, v15
	v_fmac_f32_e32 v16, v25, v12
	v_fmac_f32_e32 v17, v25, v13
	v_fmac_f32_e32 v18, v25, v14
	v_fmac_f32_e32 v19, v25, v15
	v_fmac_f32_e32 v20, v41, v12
	v_fmac_f32_e32 v21, v41, v13
	v_fmac_f32_e32 v22, v41, v14
	v_fmac_f32_e32 v23, v41, v15
	v_fmac_f32_e32 v28, v26, v12
	v_fmac_f32_e32 v29, v26, v13
	v_fmac_f32_e32 v30, v26, v14
	v_fmac_f32_e32 v31, v26, v15
	v_fmac_f32_e32 v32, v42, v12
	v_fmac_f32_e32 v33, v42, v13
	v_fmac_f32_e32 v34, v42, v14
	v_fmac_f32_e32 v35, v42, v15
	v_fmac_f32_e32 v36, v27, v12
	v_fmac_f32_e32 v37, v27, v13
	v_fmac_f32_e32 v38, v27, v14
	v_fmac_f32_e32 v39, v27, v15
	v_fmac_f32_e32 v44, v43, v12
	ds_read_b128 v[24:27], v173 offset:35776
	v_fmac_f32_e32 v45, v43, v13
	v_fmac_f32_e32 v46, v43, v14
	v_fmac_f32_e32 v47, v43, v15
	ds_read_b128 v[12:15], v173 offset:35792
	s_waitcnt vmcnt(16) lgkmcnt(1)
	v_fmac_f32_e32 v4, v24, v0
	v_fmac_f32_e32 v5, v24, v1
	v_fmac_f32_e32 v6, v24, v2
	v_fmac_f32_e32 v7, v24, v3
	s_waitcnt lgkmcnt(0)
	v_fmac_f32_e32 v8, v12, v0
	v_fmac_f32_e32 v16, v25, v0
	v_fmac_f32_e32 v20, v13, v0
	v_fmac_f32_e32 v28, v26, v0
	v_fmac_f32_e32 v32, v14, v0
	v_fmac_f32_e32 v36, v27, v0
	v_fmac_f32_e32 v44, v15, v0
	v_add_f32_dpp v0, v174, v174 quad_perm:[1,0,3,2] row_mask:0xf bank_mask:0xf bound_ctrl:1
	v_add_f32_dpp v24, v175, v175 quad_perm:[1,0,3,2] row_mask:0xf bank_mask:0xf bound_ctrl:1
	v_add_f32_dpp v48, v176, v176 quad_perm:[1,0,3,2] row_mask:0xf bank_mask:0xf bound_ctrl:1
	v_add_f32_dpp v56, v177, v177 quad_perm:[1,0,3,2] row_mask:0xf bank_mask:0xf bound_ctrl:1
	v_fmac_f32_e32 v9, v12, v1
	v_fmac_f32_e32 v10, v12, v2
	v_fmac_f32_e32 v11, v12, v3
	v_fmac_f32_e32 v17, v25, v1
	v_fmac_f32_e32 v18, v25, v2
	v_fmac_f32_e32 v19, v25, v3
	v_fmac_f32_e32 v21, v13, v1
	v_fmac_f32_e32 v22, v13, v2
	v_fmac_f32_e32 v23, v13, v3
	v_fmac_f32_e32 v29, v26, v1
	v_fmac_f32_e32 v30, v26, v2
	v_fmac_f32_e32 v31, v26, v3
	v_fmac_f32_e32 v33, v14, v1
	v_fmac_f32_e32 v34, v14, v2
	v_fmac_f32_e32 v35, v14, v3
	v_fmac_f32_e32 v37, v27, v1
	v_fmac_f32_e32 v38, v27, v2
	v_fmac_f32_e32 v39, v27, v3
	v_fmac_f32_e32 v45, v15, v1
	v_fmac_f32_e32 v46, v15, v2
	v_fmac_f32_e32 v47, v15, v3
	v_add_f32_dpp v0, v0, v0 quad_perm:[2,3,0,1] row_mask:0xf bank_mask:0xf bound_ctrl:1
	v_add_f32_dpp v24, v24, v24 quad_perm:[2,3,0,1] row_mask:0xf bank_mask:0xf bound_ctrl:1
	v_add_f32_dpp v48, v48, v48 quad_perm:[2,3,0,1] row_mask:0xf bank_mask:0xf bound_ctrl:1
	v_add_f32_dpp v56, v56, v56 quad_perm:[2,3,0,1] row_mask:0xf bank_mask:0xf bound_ctrl:1
	v_add_f32_dpp v64, v0, v0 row_half_mirror row_mask:0xf bank_mask:0xf bound_ctrl:1
	v_mov_b32_e32 v0, v4
	v_mov_b32_e32 v1, v5
	v_mov_b32_e32 v2, v6
	v_mov_b32_e32 v3, v7
	v_mov_b32_e32 v12, v8
	v_mov_b32_e32 v13, v9
	v_mov_b32_e32 v14, v10
	v_mov_b32_e32 v15, v11
	v_add_f32_dpp v66, v24, v24 row_half_mirror row_mask:0xf bank_mask:0xf bound_ctrl:1
	v_mov_b32_e32 v24, v16
	v_mov_b32_e32 v25, v17
	v_mov_b32_e32 v26, v18
	v_mov_b32_e32 v27, v19
	v_mov_b32_e32 v40, v20
	v_mov_b32_e32 v41, v21
	v_mov_b32_e32 v42, v22
	v_mov_b32_e32 v43, v23
	v_add_f32_dpp v68, v48, v48 row_half_mirror row_mask:0xf bank_mask:0xf bound_ctrl:1
	v_mov_b32_e32 v48, v28
	v_mov_b32_e32 v49, v29
	v_mov_b32_e32 v50, v30
	v_mov_b32_e32 v51, v31
	v_mov_b32_e32 v52, v32
	v_mov_b32_e32 v53, v33
	v_mov_b32_e32 v54, v34
	v_mov_b32_e32 v55, v35
	v_add_f32_dpp v70, v56, v56 row_half_mirror row_mask:0xf bank_mask:0xf bound_ctrl:1
	v_mov_b32_e32 v56, v36
	v_mov_b32_e32 v57, v37
	v_mov_b32_e32 v58, v38
	v_mov_b32_e32 v59, v39
	v_mov_b32_e32 v60, v44
	v_mov_b32_e32 v61, v45
	v_mov_b32_e32 v62, v46
	v_mov_b32_e32 v63, v47
	v_mov_b32_dpp v65, v64 row_ror:8 row_mask:0xf bank_mask:0xf bound_ctrl:1
	v_permlane32_swap_b32_e32 v4, v0
	v_permlane32_swap_b32_e32 v5, v1
	v_permlane32_swap_b32_e32 v6, v2
	v_permlane32_swap_b32_e32 v7, v3
	v_permlane32_swap_b32_e32 v8, v12
	v_permlane32_swap_b32_e32 v9, v13
	v_permlane32_swap_b32_e32 v10, v14
	v_permlane32_swap_b32_e32 v11, v15
	v_mov_b32_dpp v67, v66 row_ror:8 row_mask:0xf bank_mask:0xf bound_ctrl:1
	v_permlane32_swap_b32_e32 v16, v24
	v_permlane32_swap_b32_e32 v17, v25
	v_permlane32_swap_b32_e32 v18, v26
	v_permlane32_swap_b32_e32 v19, v27
	v_permlane32_swap_b32_e32 v20, v40
	v_permlane32_swap_b32_e32 v21, v41
	v_permlane32_swap_b32_e32 v22, v42
	v_permlane32_swap_b32_e32 v23, v43
	v_mov_b32_dpp v69, v68 row_ror:8 row_mask:0xf bank_mask:0xf bound_ctrl:1
	v_permlane32_swap_b32_e32 v28, v48
	v_permlane32_swap_b32_e32 v29, v49
	v_permlane32_swap_b32_e32 v30, v50
	v_permlane32_swap_b32_e32 v31, v51
	v_permlane32_swap_b32_e32 v32, v52
	v_permlane32_swap_b32_e32 v33, v53
	v_permlane32_swap_b32_e32 v34, v54
	v_permlane32_swap_b32_e32 v35, v55
	v_mov_b32_dpp v71, v70 row_ror:8 row_mask:0xf bank_mask:0xf bound_ctrl:1
	v_permlane32_swap_b32_e32 v36, v56
	v_permlane32_swap_b32_e32 v37, v57
	v_permlane32_swap_b32_e32 v38, v58
	v_permlane32_swap_b32_e32 v39, v59
	v_permlane32_swap_b32_e32 v44, v60
	v_permlane32_swap_b32_e32 v45, v61
	v_permlane32_swap_b32_e32 v46, v62
	v_permlane32_swap_b32_e32 v47, v63
	s_and_saveexec_b64 s[4:5], vcc
	s_cbranch_execz .LBB0_439
	v_add_f32_e32 v2, v6, v2
	v_add_f32_e32 v3, v7, v3
	v_add_f32_e32 v0, v4, v0
	v_add_f32_e32 v1, v5, v1
	v_lshl_add_u32 v4, v171, 2, s25
	v_add_f32_e32 v46, v46, v62
	v_add_f32_e32 v47, v47, v63
	v_add_f32_e32 v44, v44, v60
	v_add_f32_e32 v45, v45, v61
	v_add_f32_e32 v38, v38, v58
	v_add_f32_e32 v39, v39, v59
	v_add_f32_e32 v36, v36, v56
	v_add_f32_e32 v37, v37, v57
	v_add_f32_e32 v34, v34, v54
	v_add_f32_e32 v35, v35, v55
	v_add_f32_e32 v32, v32, v52
	v_add_f32_e32 v33, v33, v53
	v_add_f32_e32 v30, v30, v50
	v_add_f32_e32 v31, v31, v51
	v_add_f32_e32 v28, v28, v48
	v_add_f32_e32 v29, v29, v49
	v_add_f32_e32 v22, v22, v42
	v_add_f32_e32 v23, v23, v43
	v_add_f32_e32 v20, v20, v40
	v_add_f32_e32 v21, v21, v41
	v_add_f32_e32 v18, v18, v26
	v_add_f32_e32 v19, v19, v27
	v_add_f32_e32 v16, v16, v24
	v_add_f32_e32 v17, v17, v25
	v_add_f32_e32 v10, v10, v14
	v_add_f32_e32 v11, v11, v15
	v_add_f32_e32 v8, v8, v12
	v_add_f32_e32 v9, v9, v13
	ds_write_b128 v4, v[0:3] offset:32
	ds_write_b128 v4, v[8:11] offset:2208
	ds_write_b128 v4, v[16:19] offset:576
	ds_write_b128 v4, v[20:23] offset:2752
	ds_write_b128 v4, v[28:31] offset:1120
	ds_write_b128 v4, v[32:35] offset:3296
	ds_write_b128 v4, v[36:39] offset:1664
	ds_write_b128 v4, v[44:47] offset:3840

.LBB0_507:
	s_mov_b32 s5, s48
	s_add_i32 s48, s25, s48
	s_ashr_i32 s49, s48, 31
	s_add_u32 s50, s44, s48
	s_addc_u32 s51, s45, s49
	s_lshl_b64 s[50:51], s[50:51], 10
	v_lshl_add_u64 v[72:73], v[118:119], 0, s[50:51]
	ds_read_b128 v[10:13], v46 offset:14336
	ds_read_b128 v[6:9], v46 offset:14352
	ds_read_b128 v[18:21], v46 offset:12288
	ds_read_b128 v[14:17], v46 offset:12304
	ds_read_b128 v[26:29], v46 offset:10240
	ds_read_b128 v[22:25], v46 offset:10256
	ds_read_b128 v[34:37], v46 offset:8192
	ds_read_b128 v[30:33], v46 offset:8208
	ds_read_b128 v[42:45], v46 offset:6144
	ds_read_b128 v[38:41], v46 offset:6160
	ds_read_b128 v[48:51], v46 offset:4096
	ds_read_b128 v[52:55], v46 offset:4112
	ds_read_b128 v[56:59], v46 offset:2048
	ds_read_b128 v[60:63], v46 offset:2064
	ds_read_b128 v[64:67], v46
	ds_read_b128 v[68:71], v46 offset:16
	global_load_dwordx4 v[72:75], v[72:73], off
	v_add_u32_e32 v47, 0x800, v46
	s_add_i32 s48, s5, 1
	s_add_i32 s4, s4, -1
	s_waitcnt lgkmcnt(14)
	v_mov_b32_e32 v76, v10
	v_mov_b32_e32 v77, v12
	v_mov_b32_e32 v12, v11
	v_mov_b32_e32 v10, v6
	v_mov_b32_e32 v11, v8
	v_mov_b32_e32 v8, v7
	s_waitcnt lgkmcnt(13)
	v_mov_b32_e32 v6, v18
	v_mov_b32_e32 v7, v20
	v_mov_b32_e32 v20, v19
	s_waitcnt lgkmcnt(12)
	v_mov_b32_e32 v18, v14
	v_mov_b32_e32 v19, v16
	v_mov_b32_e32 v16, v15
	s_waitcnt lgkmcnt(11)
	v_mov_b32_e32 v14, v26
	v_mov_b32_e32 v15, v28
	v_mov_b32_e32 v28, v27
	s_waitcnt lgkmcnt(10)
	v_mov_b32_e32 v26, v22
	v_mov_b32_e32 v27, v24
	v_mov_b32_e32 v24, v23
	s_waitcnt lgkmcnt(9)
	v_mov_b32_e32 v22, v34
	v_mov_b32_e32 v23, v36
	v_mov_b32_e32 v36, v35
	s_waitcnt lgkmcnt(8)
	v_mov_b32_e32 v34, v30
	v_mov_b32_e32 v35, v32
	v_mov_b32_e32 v32, v31
	s_waitcnt lgkmcnt(7)
	v_mov_b32_e32 v30, v42
	v_mov_b32_e32 v31, v44
	v_mov_b32_e32 v44, v43
	s_waitcnt lgkmcnt(6)
	v_mov_b32_e32 v42, v38
	v_mov_b32_e32 v43, v40
	v_mov_b32_e32 v40, v39
	s_waitcnt lgkmcnt(5)
	v_mov_b32_e32 v38, v48
	v_mov_b32_e32 v39, v50
	v_mov_b32_e32 v50, v49
	s_waitcnt lgkmcnt(4)
	v_mov_b32_e32 v48, v52
	v_mov_b32_e32 v49, v54
	v_mov_b32_e32 v54, v53
	s_waitcnt lgkmcnt(3)
	v_mov_b32_e32 v52, v56
	v_mov_b32_e32 v53, v58
	v_mov_b32_e32 v58, v57
	s_waitcnt lgkmcnt(2)
	v_mov_b32_e32 v56, v60
	v_mov_b32_e32 v57, v62
	v_mov_b32_e32 v62, v61
	s_waitcnt lgkmcnt(1)
	v_mov_b32_e32 v60, v64
	v_mov_b32_e32 v61, v66
	v_mov_b32_e32 v66, v65
	s_waitcnt lgkmcnt(0)
	v_mov_b32_e32 v64, v68
	v_mov_b32_e32 v65, v70
	v_mov_b32_e32 v70, v69
	v_mov_b32_e32 v46, v47
	s_cmp_lg_u32 s4, 0
	s_waitcnt vmcnt(0)
	v_lshlrev_b32_e32 v69, 16, v73
	v_lshlrev_b32_e32 v68, 16, v72
	v_and_b32_e32 v73, 0xffff0000, v73
	v_and_b32_e32 v72, 0xffff0000, v72
	v_lshlrev_b32_e32 v79, 16, v75
	v_lshlrev_b32_e32 v78, 16, v74
	v_and_b32_e32 v75, 0xffff0000, v75
	v_and_b32_e32 v74, 0xffff0000, v74
	v_fmac_f32_e32 v182, v76, v68
	v_fmac_f32_e32 v183, v77, v69
	v_fmac_f32_e32 v180, v12, v72
	v_fmac_f32_e32 v181, v13, v73
	v_fmac_f32_e32 v178, v10, v78
	v_fmac_f32_e32 v179, v11, v79
	v_fmac_f32_e32 v176, v8, v74
	v_fmac_f32_e32 v177, v9, v75
	v_fmac_f32_e32 v174, v6, v68
	v_fmac_f32_e32 v175, v7, v69
	v_fmac_f32_e32 v172, v20, v72
	v_fmac_f32_e32 v173, v21, v73
	v_fmac_f32_e32 v170, v18, v78
	v_fmac_f32_e32 v171, v19, v79
	v_fmac_f32_e32 v168, v16, v74
	v_fmac_f32_e32 v169, v17, v75
	v_fmac_f32_e32 v166, v14, v68
	v_fmac_f32_e32 v167, v15, v69
	v_fmac_f32_e32 v164, v28, v72
	v_fmac_f32_e32 v165, v29, v73
	v_fmac_f32_e32 v162, v26, v78
	v_fmac_f32_e32 v163, v27, v79
	v_fmac_f32_e32 v160, v24, v74
	v_fmac_f32_e32 v161, v25, v75
	v_fmac_f32_e32 v158, v22, v68
	v_fmac_f32_e32 v159, v23, v69
	v_fmac_f32_e32 v156, v36, v72
	v_fmac_f32_e32 v157, v37, v73
	v_fmac_f32_e32 v154, v34, v78
	v_fmac_f32_e32 v155, v35, v79
	v_fmac_f32_e32 v152, v32, v74
	v_fmac_f32_e32 v153, v33, v75
	v_fmac_f32_e32 v150, v30, v68
	v_fmac_f32_e32 v151, v31, v69
	v_fmac_f32_e32 v148, v44, v72
	v_fmac_f32_e32 v149, v45, v73
	v_fmac_f32_e32 v146, v42, v78
	v_fmac_f32_e32 v147, v43, v79
	v_fmac_f32_e32 v144, v40, v74
	v_fmac_f32_e32 v145, v41, v75
	v_fmac_f32_e32 v4, v38, v68
	v_fmac_f32_e32 v5, v39, v69
	v_fmac_f32_e32 v142, v50, v72
	v_fmac_f32_e32 v143, v51, v73
	v_fmac_f32_e32 v0, v48, v78
	v_fmac_f32_e32 v1, v49, v79
	v_fmac_f32_e32 v140, v54, v74
	v_fmac_f32_e32 v141, v55, v75
	v_fmac_f32_e32 v138, v52, v68
	v_fmac_f32_e32 v139, v53, v69
	v_fmac_f32_e32 v136, v58, v72
	v_fmac_f32_e32 v137, v59, v73
	v_fmac_f32_e32 v134, v56, v78
	v_fmac_f32_e32 v135, v57, v79
	v_fmac_f32_e32 v132, v62, v74
	v_fmac_f32_e32 v133, v63, v75
	v_fmac_f32_e32 v130, v60, v68
	v_fmac_f32_e32 v131, v61, v69
	v_fmac_f32_e32 v128, v66, v72
	v_fmac_f32_e32 v129, v67, v73
	v_fmac_f32_e32 v126, v64, v78
	v_fmac_f32_e32 v127, v65, v79
	v_fmac_f32_e32 v2, v70, v74
	v_fmac_f32_e32 v3, v71, v75
	s_cbranch_scc1 .LBB0_507
	s_add_i32 s48, s5, 31
	s_branch .LBB0_510

.LBB0_511:
	s_add_i32 s5, s25, s4
	s_sub_i32 s48, s5, 24
	s_ashr_i32 s49, s48, 31
	s_add_u32 s48, s44, s48
	s_addc_u32 s49, s45, s49
	ds_read_b128 v[10:13], v187 offset:14336
	ds_read_b128 v[6:9], v187 offset:14352
	ds_read_b128 v[18:21], v187 offset:12288
	ds_read_b128 v[14:17], v187 offset:12304
	ds_read_b128 v[26:29], v187 offset:10240
	ds_read_b128 v[22:25], v187 offset:10256
	ds_read_b128 v[34:37], v187 offset:8192
	ds_read_b128 v[30:33], v187 offset:8208
	ds_read_b128 v[42:45], v187 offset:6144
	ds_read_b128 v[38:41], v187 offset:6160
	ds_read_b128 v[58:61], v187 offset:4096
	ds_read_b128 v[54:57], v187 offset:4112
	ds_read_b128 v[66:69], v187 offset:2048
	ds_read_b128 v[62:65], v187 offset:2064
	ds_read_b128 v[82:85], v187
	ds_read_b128 v[78:81], v187 offset:16
	ds_read_b128 v[50:53], v187 offset:16384
	ds_read_b128 v[46:49], v187 offset:16400
	ds_read_b128 v[74:77], v187 offset:18432
	ds_read_b128 v[70:73], v187 offset:18448
	ds_read_b128 v[90:93], v187 offset:20480
	ds_read_b128 v[86:89], v187 offset:20496
	ds_read_b128 v[98:101], v187 offset:22528
	ds_read_b128 v[94:97], v187 offset:22544
	ds_read_b128 v[106:109], v187 offset:24576
	ds_read_b128 v[102:105], v187 offset:24592
	s_lshl_b64 s[48:49], s[48:49], 10
	s_waitcnt lgkmcnt(11)
	v_mov_b32_e32 v218, v82
	v_mov_b32_e32 v219, v84
	v_mov_b32_e32 v84, v83
	s_waitcnt lgkmcnt(10)
	v_mov_b32_e32 v82, v78
	v_mov_b32_e32 v83, v80
	v_mov_b32_e32 v80, v79
	v_lshl_add_u64 v[78:79], v[118:119], 0, s[48:49]
	global_load_dwordx4 v[188:191], v[78:79], off
	s_sub_i32 s50, s5, 23
	s_ashr_i32 s51, s50, 31
	s_add_u32 s48, s44, s50
	s_addc_u32 s49, s45, s51
	s_sub_i32 s50, s5, 22
	s_lshl_b64 s[48:49], s[48:49], 10
	s_ashr_i32 s51, s50, 31
	v_lshl_add_u64 v[78:79], v[118:119], 0, s[48:49]
	s_add_u32 s48, s44, s50
	s_addc_u32 s49, s45, s51
	s_sub_i32 s50, s5, 21
	s_lshl_b64 s[48:49], s[48:49], 10
	s_ashr_i32 s51, s50, 31
	global_load_dwordx4 v[192:195], v[78:79], off
	v_lshl_add_u64 v[78:79], v[118:119], 0, s[48:49]
	s_add_u32 s48, s44, s50
	s_addc_u32 s49, s45, s51
	s_sub_i32 s50, s5, 20
	s_lshl_b64 s[48:49], s[48:49], 10
	s_ashr_i32 s51, s50, 31
	global_load_dwordx4 v[196:199], v[78:79], off
	v_lshl_add_u64 v[78:79], v[118:119], 0, s[48:49]
	s_add_u32 s48, s44, s50
	s_addc_u32 s49, s45, s51
	s_sub_i32 s5, s5, 19
	s_lshl_b64 s[48:49], s[48:49], 10
	s_ashr_i32 s50, s5, 31
	v_mov_b32_e32 v212, v58
	v_mov_b32_e32 v213, v60
	v_mov_b32_e32 v60, v59
	s_waitcnt lgkmcnt(3)
	v_mov_b32_e32 v58, v98
	v_mov_b32_e32 v59, v100
	v_mov_b32_e32 v100, v99
	v_lshl_add_u64 v[98:99], v[118:119], 0, s[48:49]
	s_add_u32 s48, s44, s5
	s_addc_u32 s49, s45, s50
	v_add_u32_e32 v184, 0x3000, v187
	global_load_dwordx4 v[200:203], v[78:79], off
	s_lshl_b64 s[48:49], s[48:49], 10
	v_mov_b32_e32 v187, v184
	v_mov_b32_e32 v184, v10
	v_mov_b32_e32 v185, v12
	v_mov_b32_e32 v12, v11
	v_mov_b32_e32 v10, v6
	v_mov_b32_e32 v11, v8
	v_mov_b32_e32 v8, v7
	v_mov_b32_e32 v6, v18
	v_mov_b32_e32 v7, v20
	v_mov_b32_e32 v20, v19
	v_mov_b32_e32 v18, v14
	v_mov_b32_e32 v19, v16
	v_mov_b32_e32 v16, v15
	v_mov_b32_e32 v14, v26
	v_mov_b32_e32 v15, v28
	v_mov_b32_e32 v28, v27
	v_mov_b32_e32 v26, v22
	v_mov_b32_e32 v27, v24
	v_mov_b32_e32 v24, v23
	v_mov_b32_e32 v22, v34
	v_mov_b32_e32 v23, v36
	v_mov_b32_e32 v36, v35
	v_mov_b32_e32 v34, v30
	v_mov_b32_e32 v35, v32
	v_mov_b32_e32 v32, v31
	v_mov_b32_e32 v214, v54
	v_mov_b32_e32 v215, v56
	v_mov_b32_e32 v56, v55
	v_mov_b32_e32 v216, v66
	v_mov_b32_e32 v217, v68
	v_mov_b32_e32 v68, v67
	v_mov_b32_e32 v66, v62
	v_mov_b32_e32 v67, v64
	v_mov_b32_e32 v64, v63
	v_mov_b32_e32 v30, v50
	v_mov_b32_e32 v31, v52
	v_mov_b32_e32 v52, v51
	v_mov_b32_e32 v50, v90
	v_mov_b32_e32 v51, v92
	v_mov_b32_e32 v92, v91
	v_mov_b32_e32 v54, v86
	v_mov_b32_e32 v55, v88
	v_mov_b32_e32 v88, v87
	s_waitcnt lgkmcnt(2)
	v_mov_b32_e32 v62, v94
	v_mov_b32_e32 v63, v96
	v_mov_b32_e32 v96, v95
	s_waitcnt vmcnt(3)
	v_lshlrev_b32_e32 v79, 16, v189
	v_lshlrev_b32_e32 v78, 16, v188
	v_and_b32_e32 v87, 0xffff0000, v189
	v_and_b32_e32 v86, 0xffff0000, v188
	v_lshlrev_b32_e32 v91, 16, v191
	v_lshlrev_b32_e32 v90, 16, v190
	v_and_b32_e32 v95, 0xffff0000, v191
	v_and_b32_e32 v94, 0xffff0000, v190
	global_load_dwordx4 v[188:191], v[98:99], off
	v_lshl_add_u64 v[98:99], v[118:119], 0, s[48:49]
	global_load_dwordx4 v[204:207], v[98:99], off
	v_mov_b32_e32 v208, v42
	v_mov_b32_e32 v209, v44
	v_mov_b32_e32 v44, v43
	v_mov_b32_e32 v210, v38
	v_mov_b32_e32 v211, v40
	v_mov_b32_e32 v40, v39
	v_mov_b32_e32 v38, v46
	v_mov_b32_e32 v39, v48
	v_mov_b32_e32 v48, v47
	v_mov_b32_e32 v42, v74
	v_mov_b32_e32 v43, v76
	v_mov_b32_e32 v76, v75
	v_mov_b32_e32 v46, v70
	v_mov_b32_e32 v47, v72
	v_mov_b32_e32 v72, v71
	s_waitcnt lgkmcnt(1)
	v_mov_b32_e32 v70, v106
	v_mov_b32_e32 v71, v108
	v_mov_b32_e32 v108, v107
	s_waitcnt lgkmcnt(0)
	v_mov_b32_e32 v74, v102
	v_mov_b32_e32 v75, v104
	v_mov_b32_e32 v104, v103
	v_fmac_f32_e32 v4, v212, v78
	v_fmac_f32_e32 v5, v213, v79
	v_fmac_f32_e32 v0, v214, v90
	v_fmac_f32_e32 v1, v215, v91
	v_fma_f32 v98, v184, v78, v182
	v_fma_f32 v99, v185, v79, v183
	v_fma_f32 v102, v12, v86, v180
	v_fma_f32 v103, v13, v87, v181
	v_fma_f32 v106, v10, v90, v178
	v_fma_f32 v107, v11, v91, v179
	v_fmac_f32_e32 v176, v8, v94
	v_fmac_f32_e32 v177, v9, v95
	v_fmac_f32_e32 v174, v6, v78
	v_fmac_f32_e32 v175, v7, v79
	v_fmac_f32_e32 v172, v20, v86
	v_fmac_f32_e32 v173, v21, v87
	v_fmac_f32_e32 v170, v18, v90
	v_fmac_f32_e32 v171, v19, v91
	v_fmac_f32_e32 v168, v16, v94
	v_fmac_f32_e32 v169, v17, v95
	v_fmac_f32_e32 v166, v14, v78
	v_fmac_f32_e32 v167, v15, v79
	v_fmac_f32_e32 v164, v28, v86
	v_fmac_f32_e32 v165, v29, v87
	v_fmac_f32_e32 v162, v26, v90
	v_fmac_f32_e32 v163, v27, v91
	v_fmac_f32_e32 v160, v24, v94
	v_fmac_f32_e32 v161, v25, v95
	v_fmac_f32_e32 v158, v22, v78
	v_fmac_f32_e32 v159, v23, v79
	v_fmac_f32_e32 v156, v36, v86
	v_fmac_f32_e32 v157, v37, v87
	v_fmac_f32_e32 v154, v34, v90
	v_fmac_f32_e32 v155, v35, v91
	v_fmac_f32_e32 v152, v32, v94
	v_fmac_f32_e32 v153, v33, v95
	v_fmac_f32_e32 v150, v208, v78
	v_fmac_f32_e32 v151, v209, v79
	v_fmac_f32_e32 v148, v44, v86
	v_fmac_f32_e32 v149, v45, v87
	v_fmac_f32_e32 v146, v210, v90
	v_fmac_f32_e32 v147, v211, v91
	v_fmac_f32_e32 v144, v40, v94
	v_fmac_f32_e32 v145, v41, v95
	v_fmac_f32_e32 v142, v60, v86
	v_fmac_f32_e32 v143, v61, v87
	v_fmac_f32_e32 v140, v56, v94
	v_fmac_f32_e32 v141, v57, v95
	v_fmac_f32_e32 v138, v216, v78
	v_fmac_f32_e32 v139, v217, v79
	v_fmac_f32_e32 v136, v68, v86
	v_fmac_f32_e32 v137, v69, v87
	v_fmac_f32_e32 v134, v66, v90
	v_fmac_f32_e32 v135, v67, v91
	v_fmac_f32_e32 v132, v64, v94
	v_fmac_f32_e32 v133, v65, v95
	v_fma_f32 v78, v218, v78, v130
	v_fma_f32 v79, v219, v79, v131
	v_fma_f32 v84, v84, v86, v128
	v_fma_f32 v85, v85, v87, v129
	v_fma_f32 v82, v82, v90, v126
	v_fma_f32 v83, v83, v91, v127
	v_fmac_f32_e32 v2, v80, v94
	v_fmac_f32_e32 v3, v81, v95
	s_waitcnt vmcnt(4)
	v_lshlrev_b32_e32 v81, 16, v193
	v_lshlrev_b32_e32 v80, 16, v192
	v_and_b32_e32 v87, 0xffff0000, v193
	v_and_b32_e32 v86, 0xffff0000, v192
	v_lshlrev_b32_e32 v91, 16, v195
	v_lshlrev_b32_e32 v90, 16, v194
	v_and_b32_e32 v95, 0xffff0000, v195
	v_and_b32_e32 v94, 0xffff0000, v194
	v_fmac_f32_e32 v98, v30, v80
	v_fmac_f32_e32 v99, v31, v81
	v_fmac_f32_e32 v102, v52, v86
	v_fmac_f32_e32 v103, v53, v87
	v_fmac_f32_e32 v106, v38, v90
	v_fmac_f32_e32 v107, v39, v91
	v_fma_f32 v126, v48, v94, v176
	v_fma_f32 v127, v49, v95, v177
	v_fma_f32 v128, v184, v80, v174
	v_fma_f32 v129, v185, v81, v175
	v_fma_f32 v130, v12, v86, v172
	v_fma_f32 v131, v13, v87, v173
	v_fmac_f32_e32 v170, v10, v90
	v_fmac_f32_e32 v171, v11, v91
	v_fmac_f32_e32 v168, v8, v94
	v_fmac_f32_e32 v169, v9, v95
	v_fmac_f32_e32 v166, v6, v80
	v_fmac_f32_e32 v167, v7, v81
	v_fmac_f32_e32 v164, v20, v86
	v_fmac_f32_e32 v165, v21, v87
	v_fmac_f32_e32 v162, v18, v90
	v_fmac_f32_e32 v163, v19, v91
	v_fmac_f32_e32 v160, v16, v94
	v_fmac_f32_e32 v161, v17, v95
	v_fmac_f32_e32 v158, v14, v80
	v_fmac_f32_e32 v159, v15, v81
	v_fmac_f32_e32 v156, v28, v86
	v_fmac_f32_e32 v157, v29, v87
	v_fmac_f32_e32 v154, v26, v90
	v_fmac_f32_e32 v155, v27, v91
	v_fmac_f32_e32 v152, v24, v94
	v_fmac_f32_e32 v153, v25, v95
	v_fmac_f32_e32 v150, v22, v80
	v_fmac_f32_e32 v151, v23, v81
	v_fmac_f32_e32 v148, v36, v86
	v_fmac_f32_e32 v149, v37, v87
	v_fmac_f32_e32 v146, v34, v90
	v_fmac_f32_e32 v147, v35, v91
	v_fmac_f32_e32 v144, v32, v94
	v_fmac_f32_e32 v145, v33, v95
	v_fmac_f32_e32 v4, v208, v80
	v_fmac_f32_e32 v5, v209, v81
	v_fmac_f32_e32 v142, v44, v86
	v_fmac_f32_e32 v143, v45, v87
	v_fmac_f32_e32 v0, v210, v90
	v_fmac_f32_e32 v1, v211, v91
	v_fmac_f32_e32 v140, v40, v94
	v_fmac_f32_e32 v141, v41, v95
	v_fmac_f32_e32 v138, v212, v80
	v_fmac_f32_e32 v139, v213, v81
	v_fmac_f32_e32 v136, v60, v86
	v_fmac_f32_e32 v137, v61, v87
	v_fmac_f32_e32 v134, v214, v90
	v_fmac_f32_e32 v135, v215, v91
	v_fmac_f32_e32 v132, v56, v94
	v_fmac_f32_e32 v133, v57, v95
	v_fmac_f32_e32 v78, v216, v80
	v_fmac_f32_e32 v79, v217, v81
	v_fma_f32 v68, v68, v86, v84
	v_fma_f32 v69, v69, v87, v85
	v_fma_f32 v66, v66, v90, v82
	v_fma_f32 v67, v67, v91, v83
	v_fmac_f32_e32 v2, v64, v94
	v_fmac_f32_e32 v3, v65, v95
	s_waitcnt vmcnt(3)
	v_lshlrev_b32_e32 v65, 16, v197
	v_lshlrev_b32_e32 v64, 16, v196
	v_and_b32_e32 v81, 0xffff0000, v197
	v_and_b32_e32 v80, 0xffff0000, v196
	v_lshlrev_b32_e32 v83, 16, v199
	v_lshlrev_b32_e32 v82, 16, v198
	v_and_b32_e32 v85, 0xffff0000, v199
	v_and_b32_e32 v84, 0xffff0000, v198
	v_fma_f32 v86, v42, v64, v98
	v_fma_f32 v87, v43, v65, v99
	v_fma_f32 v90, v76, v80, v102
	v_fma_f32 v91, v77, v81, v103
	v_fma_f32 v94, v46, v82, v106
	v_fma_f32 v95, v47, v83, v107
	v_fma_f32 v98, v72, v84, v126
	v_fma_f32 v99, v73, v85, v127
	v_fma_f32 v102, v30, v64, v128
	v_fma_f32 v103, v31, v65, v129
	v_fma_f32 v106, v52, v80, v130
	v_fma_f32 v107, v53, v81, v131
	v_fma_f32 v126, v38, v82, v170
	v_fma_f32 v127, v39, v83, v171
	v_fma_f32 v128, v48, v84, v168
	v_fma_f32 v129, v49, v85, v169
	v_fma_f32 v130, v184, v64, v166
	v_fma_f32 v131, v185, v65, v167
	v_fmac_f32_e32 v164, v12, v80
	v_fmac_f32_e32 v165, v13, v81
	v_fmac_f32_e32 v162, v10, v82
	v_fmac_f32_e32 v163, v11, v83
	v_fmac_f32_e32 v160, v8, v84
	v_fmac_f32_e32 v161, v9, v85
	v_fmac_f32_e32 v158, v6, v64
	v_fmac_f32_e32 v159, v7, v65
	v_fmac_f32_e32 v156, v20, v80
	v_fmac_f32_e32 v157, v21, v81
	v_fmac_f32_e32 v154, v18, v82
	v_fmac_f32_e32 v155, v19, v83
	v_fmac_f32_e32 v152, v16, v84
	v_fmac_f32_e32 v153, v17, v85
	v_fmac_f32_e32 v150, v14, v64
	v_fmac_f32_e32 v151, v15, v65
	v_fmac_f32_e32 v148, v28, v80
	v_fmac_f32_e32 v149, v29, v81
	v_fmac_f32_e32 v146, v26, v82
	v_fmac_f32_e32 v147, v27, v83
	v_fmac_f32_e32 v144, v24, v84
	v_fmac_f32_e32 v145, v25, v85
	v_fmac_f32_e32 v4, v22, v64
	v_fmac_f32_e32 v5, v23, v65
	v_fmac_f32_e32 v142, v36, v80
	v_fmac_f32_e32 v143, v37, v81
	v_fmac_f32_e32 v0, v34, v82
	v_fmac_f32_e32 v1, v35, v83
	v_fmac_f32_e32 v140, v32, v84
	v_fmac_f32_e32 v141, v33, v85
	v_fmac_f32_e32 v138, v208, v64
	v_fmac_f32_e32 v139, v209, v65
	v_fmac_f32_e32 v136, v44, v80
	v_fmac_f32_e32 v137, v45, v81
	v_fmac_f32_e32 v134, v210, v82
	v_fmac_f32_e32 v135, v211, v83
	v_fmac_f32_e32 v132, v40, v84
	v_fmac_f32_e32 v133, v41, v85
	v_fma_f32 v64, v212, v64, v78
	v_fma_f32 v65, v213, v65, v79
	v_fma_f32 v60, v60, v80, v68
	v_fma_f32 v61, v61, v81, v69
	v_fmac_f32_e32 v66, v214, v82
	v_fmac_f32_e32 v67, v215, v83
	v_fmac_f32_e32 v2, v56, v84
	v_fmac_f32_e32 v3, v57, v85
	s_waitcnt vmcnt(2)
	v_lshlrev_b32_e32 v57, 16, v201
	v_lshlrev_b32_e32 v56, 16, v200
	v_and_b32_e32 v69, 0xffff0000, v201
	v_and_b32_e32 v68, 0xffff0000, v200
	v_lshlrev_b32_e32 v79, 16, v203
	v_lshlrev_b32_e32 v78, 16, v202
	v_and_b32_e32 v81, 0xffff0000, v203
	v_and_b32_e32 v80, 0xffff0000, v202
	v_fma_f32 v82, v50, v56, v86
	v_fma_f32 v83, v51, v57, v87
	v_fma_f32 v84, v92, v68, v90
	v_fma_f32 v85, v93, v69, v91
	v_fma_f32 v86, v54, v78, v94
	v_fma_f32 v87, v55, v79, v95
	v_fma_f32 v90, v88, v80, v98
	v_fma_f32 v91, v89, v81, v99
	v_fma_f32 v94, v42, v56, v102
	v_fma_f32 v95, v43, v57, v103
	v_fma_f32 v98, v76, v68, v106
	v_fma_f32 v99, v77, v69, v107
	v_fma_f32 v102, v46, v78, v126
	v_fma_f32 v103, v47, v79, v127
	v_fma_f32 v106, v72, v80, v128
	v_fma_f32 v107, v73, v81, v129
	v_fma_f32 v126, v30, v56, v130
	v_fma_f32 v127, v31, v57, v131
	v_fma_f32 v128, v52, v68, v164
	v_fma_f32 v129, v53, v69, v165
	v_fma_f32 v130, v38, v78, v162
	v_fma_f32 v131, v39, v79, v163
	v_fmac_f32_e32 v160, v48, v80
	v_fmac_f32_e32 v161, v49, v81
	v_fmac_f32_e32 v158, v184, v56
	v_fmac_f32_e32 v159, v185, v57
	v_fmac_f32_e32 v156, v12, v68
	v_fmac_f32_e32 v157, v13, v69
	v_fmac_f32_e32 v154, v10, v78
	v_fmac_f32_e32 v155, v11, v79
	v_fmac_f32_e32 v152, v8, v80
	v_fmac_f32_e32 v153, v9, v81
	v_fmac_f32_e32 v150, v6, v56
	v_fmac_f32_e32 v151, v7, v57
	v_fmac_f32_e32 v148, v20, v68
	v_fmac_f32_e32 v149, v21, v69
	v_fmac_f32_e32 v146, v18, v78
	v_fmac_f32_e32 v147, v19, v79
	v_fmac_f32_e32 v144, v16, v80
	v_fmac_f32_e32 v145, v17, v81
	v_fmac_f32_e32 v4, v14, v56
	v_fmac_f32_e32 v5, v15, v57
	v_fmac_f32_e32 v142, v28, v68
	v_fmac_f32_e32 v143, v29, v69
	v_fmac_f32_e32 v0, v26, v78
	v_fmac_f32_e32 v1, v27, v79
	v_fmac_f32_e32 v140, v24, v80
	v_fmac_f32_e32 v141, v25, v81
	v_fmac_f32_e32 v138, v22, v56
	v_fmac_f32_e32 v139, v23, v57
	v_fmac_f32_e32 v136, v36, v68
	v_fmac_f32_e32 v137, v37, v69
	v_fmac_f32_e32 v134, v34, v78
	v_fmac_f32_e32 v135, v35, v79
	v_fmac_f32_e32 v132, v32, v80
	v_fmac_f32_e32 v133, v33, v81
	v_fma_f32 v56, v208, v56, v64
	v_fma_f32 v57, v209, v57, v65
	v_fma_f32 v44, v44, v68, v60
	v_fma_f32 v45, v45, v69, v61
	v_fma_f32 v60, v210, v78, v66
	v_fma_f32 v61, v211, v79, v67
	v_fmac_f32_e32 v2, v40, v80
	v_fmac_f32_e32 v3, v41, v81
	s_waitcnt vmcnt(1)
	v_lshlrev_b32_e32 v41, 16, v189
	v_lshlrev_b32_e32 v40, 16, v188
	v_and_b32_e32 v65, 0xffff0000, v189
	v_and_b32_e32 v64, 0xffff0000, v188
	v_lshlrev_b32_e32 v67, 16, v191
	v_lshlrev_b32_e32 v66, 16, v190
	v_and_b32_e32 v69, 0xffff0000, v191
	v_and_b32_e32 v68, 0xffff0000, v190
	s_add_i32 s4, s4, 6
	v_fma_f32 v78, v58, v40, v82
	v_fma_f32 v79, v59, v41, v83
	v_fma_f32 v80, v100, v64, v84
	v_fma_f32 v81, v101, v65, v85
	v_fma_f32 v82, v62, v66, v86
	v_fma_f32 v83, v63, v67, v87
	v_fma_f32 v84, v96, v68, v90
	v_fma_f32 v85, v97, v69, v91
	v_fma_f32 v86, v50, v40, v94
	v_fma_f32 v87, v51, v41, v95
	v_fma_f32 v90, v92, v64, v98
	v_fma_f32 v91, v93, v65, v99
	v_fma_f32 v94, v54, v66, v102
	v_fma_f32 v95, v55, v67, v103
	v_fma_f32 v98, v88, v68, v106
	v_fma_f32 v99, v89, v69, v107
	v_fma_f32 v102, v42, v40, v126
	v_fma_f32 v103, v43, v41, v127
	v_fma_f32 v106, v76, v64, v128
	v_fma_f32 v107, v77, v65, v129
	v_fma_f32 v126, v46, v66, v130
	v_fma_f32 v127, v47, v67, v131
	v_fma_f32 v128, v72, v68, v160
	v_fma_f32 v129, v73, v69, v161
	v_fma_f32 v130, v30, v40, v158
	v_fma_f32 v131, v31, v41, v159
	v_fmac_f32_e32 v156, v52, v64
	v_fmac_f32_e32 v157, v53, v65
	v_fmac_f32_e32 v154, v38, v66
	v_fmac_f32_e32 v155, v39, v67
	v_fmac_f32_e32 v152, v48, v68
	v_fmac_f32_e32 v153, v49, v69
	v_fmac_f32_e32 v150, v184, v40
	v_fmac_f32_e32 v151, v185, v41
	v_fmac_f32_e32 v148, v12, v64
	v_fmac_f32_e32 v149, v13, v65
	v_fmac_f32_e32 v146, v10, v66
	v_fmac_f32_e32 v147, v11, v67
	v_fmac_f32_e32 v144, v8, v68
	v_fmac_f32_e32 v145, v9, v69
	v_fmac_f32_e32 v4, v6, v40
	v_fmac_f32_e32 v5, v7, v41
	v_fmac_f32_e32 v142, v20, v64
	v_fmac_f32_e32 v143, v21, v65
	v_fmac_f32_e32 v0, v18, v66
	v_fmac_f32_e32 v1, v19, v67
	v_fmac_f32_e32 v140, v16, v68
	v_fmac_f32_e32 v141, v17, v69
	v_fmac_f32_e32 v138, v14, v40
	v_fmac_f32_e32 v139, v15, v41
	v_fmac_f32_e32 v136, v28, v64
	v_fmac_f32_e32 v137, v29, v65
	v_fmac_f32_e32 v134, v26, v66
	v_fmac_f32_e32 v135, v27, v67
	v_fmac_f32_e32 v132, v24, v68
	v_fmac_f32_e32 v133, v25, v69
	v_fma_f32 v22, v22, v40, v56
	v_fma_f32 v23, v23, v41, v57
	v_fma_f32 v36, v36, v64, v44
	v_fma_f32 v37, v37, v65, v45
	v_fma_f32 v34, v34, v66, v60
	v_fma_f32 v35, v35, v67, v61
	v_fmac_f32_e32 v2, v32, v68
	v_fmac_f32_e32 v3, v33, v69
	s_waitcnt vmcnt(0)
	v_lshlrev_b32_e32 v33, 16, v205
	v_lshlrev_b32_e32 v32, 16, v204
	v_and_b32_e32 v41, 0xffff0000, v205
	v_and_b32_e32 v40, 0xffff0000, v204
	v_lshlrev_b32_e32 v45, 16, v207
	v_lshlrev_b32_e32 v44, 16, v206
	v_and_b32_e32 v57, 0xffff0000, v207
	v_and_b32_e32 v56, 0xffff0000, v206
	s_cmp_lt_u32 s4, 32
	v_fma_f32 v182, v70, v32, v78
	v_fma_f32 v183, v71, v33, v79
	v_fma_f32 v180, v108, v40, v80
	v_fma_f32 v181, v109, v41, v81
	v_fma_f32 v178, v74, v44, v82
	v_fma_f32 v179, v75, v45, v83
	v_fma_f32 v176, v104, v56, v84
	v_fma_f32 v177, v105, v57, v85
	v_fma_f32 v174, v58, v32, v86
	v_fma_f32 v175, v59, v33, v87
	v_fma_f32 v172, v100, v40, v90
	v_fma_f32 v173, v101, v41, v91
	v_fma_f32 v170, v62, v44, v94
	v_fma_f32 v171, v63, v45, v95
	v_fma_f32 v168, v96, v56, v98
	v_fma_f32 v169, v97, v57, v99
	v_fma_f32 v166, v50, v32, v102
	v_fma_f32 v167, v51, v33, v103
	v_fma_f32 v164, v92, v40, v106
	v_fma_f32 v165, v93, v41, v107
	v_fma_f32 v162, v54, v44, v126
	v_fma_f32 v163, v55, v45, v127
	v_fma_f32 v160, v88, v56, v128
	v_fma_f32 v161, v89, v57, v129
	v_fma_f32 v158, v42, v32, v130
	v_fma_f32 v159, v43, v33, v131
	v_fmac_f32_e32 v156, v76, v40
	v_fmac_f32_e32 v157, v77, v41
	v_fmac_f32_e32 v154, v46, v44
	v_fmac_f32_e32 v155, v47, v45
	v_fmac_f32_e32 v152, v72, v56
	v_fmac_f32_e32 v153, v73, v57
	v_fmac_f32_e32 v150, v30, v32
	v_fmac_f32_e32 v151, v31, v33
	v_fmac_f32_e32 v148, v52, v40
	v_fmac_f32_e32 v149, v53, v41
	v_fmac_f32_e32 v146, v38, v44
	v_fmac_f32_e32 v147, v39, v45
	v_fmac_f32_e32 v144, v48, v56
	v_fmac_f32_e32 v145, v49, v57
	v_fmac_f32_e32 v4, v184, v32
	v_fmac_f32_e32 v5, v185, v33
	v_fmac_f32_e32 v142, v12, v40
	v_fmac_f32_e32 v143, v13, v41
	v_fmac_f32_e32 v0, v10, v44
	v_fmac_f32_e32 v1, v11, v45
	v_fmac_f32_e32 v140, v8, v56
	v_fmac_f32_e32 v141, v9, v57
	v_fmac_f32_e32 v138, v6, v32
	v_fmac_f32_e32 v139, v7, v33
	v_fmac_f32_e32 v136, v20, v40
	v_fmac_f32_e32 v137, v21, v41
	v_fmac_f32_e32 v134, v18, v44
	v_fmac_f32_e32 v135, v19, v45
	v_fmac_f32_e32 v132, v16, v56
	v_fmac_f32_e32 v133, v17, v57
	v_fma_f32 v130, v14, v32, v22
	v_fma_f32 v131, v15, v33, v23
	v_fma_f32 v128, v28, v40, v36
	v_fma_f32 v129, v29, v41, v37
	v_fma_f32 v126, v26, v44, v34
	v_fma_f32 v127, v27, v45, v35
	v_fmac_f32_e32 v2, v24, v56
	v_fmac_f32_e32 v3, v25, v57
	s_cbranch_scc1 .LBB0_511
	v_add_f32_e32 v6, 0, v182
	v_add_f32_e32 v6, v180, v6
	v_add_f32_e32 v6, v183, v6
	v_add_f32_e32 v6, v181, v6
	v_add_f32_e32 v6, v178, v6
	v_add_f32_e32 v6, v176, v6
	v_add_f32_e32 v6, v179, v6
	v_add_f32_e32 v22, v177, v6
	v_add_f32_e32 v6, 0, v174
	v_add_f32_e32 v6, v172, v6
	v_add_f32_e32 v6, v175, v6
	v_add_f32_e32 v6, v173, v6
	v_add_f32_e32 v6, v170, v6
	v_add_f32_e32 v6, v168, v6
	v_add_f32_e32 v6, v171, v6
	v_add_f32_e32 v31, v169, v6
	v_add_f32_e32 v6, 0, v166
	v_add_f32_e32 v6, v164, v6
	v_add_f32_e32 v6, v167, v6
	v_add_f32_e32 v6, v165, v6
	v_add_f32_e32 v6, v162, v6
	v_add_f32_e32 v6, v160, v6
	v_add_f32_e32 v6, v163, v6
	v_add_f32_e32 v46, v161, v6
	v_add_f32_e32 v6, 0, v158
	v_add_f32_e32 v6, v156, v6
	v_add_f32_e32 v6, v159, v6
	v_add_f32_e32 v6, v157, v6
	v_add_f32_e32 v6, v154, v6
	v_add_f32_e32 v23, v152, v6
	global_load_dwordx4 v[6:9], v[122:123], off offset:16
	global_load_dwordx4 v[14:17], v[122:123], off
	global_load_dwordx4 v[10:13], v[124:125], off offset:16
	global_load_dwordx4 v[18:21], v[124:125], off
	v_add_f32_e32 v23, v155, v23
	v_add_f32_e32 v30, v153, v23
	v_add_f32_e32 v23, 0, v150
	v_add_f32_e32 v23, v148, v23
	v_add_f32_e32 v23, v151, v23
	v_add_f32_e32 v23, v149, v23
	v_add_f32_e32 v23, v146, v23
	v_add_f32_e32 v23, v144, v23
	v_add_f32_e32 v23, v147, v23
	v_add_f32_e32 v29, v145, v23
	v_add_f32_e32 v23, 0, v4
	v_add_f32_e32 v23, v142, v23
	v_add_f32_e32 v23, v5, v23
	v_add_f32_e32 v23, v143, v23
	v_add_f32_e32 v23, v0, v23
	v_add_f32_e32 v23, v140, v23
	v_add_f32_e32 v23, v1, v23
	v_add_f32_e32 v28, v141, v23
	v_add_f32_e32 v23, 0, v138
	v_add_f32_e32 v23, v136, v23
	v_add_f32_e32 v23, v139, v23
	v_add_f32_e32 v23, v137, v23
	v_add_f32_e32 v23, v134, v23
	v_add_f32_e32 v23, v132, v23
	v_add_f32_e32 v23, v135, v23
	v_add_f32_e32 v27, v133, v23
	v_add_f32_e32 v23, 0, v130
	v_add_f32_e32 v23, v128, v23
	v_add_f32_e32 v23, v131, v23
	v_add_f32_e32 v23, v129, v23
	v_add_f32_dpp v22, v22, v22 quad_perm:[1,0,3,2] row_mask:0xf bank_mask:0xf bound_ctrl:1
	v_add_f32_e32 v23, v126, v23
	v_add_f32_e32 v23, v2, v23
	v_add_f32_dpp v22, v22, v22 quad_perm:[2,3,0,1] row_mask:0xf bank_mask:0xf bound_ctrl:1
	v_add_f32_e32 v23, v127, v23
	v_add_f32_e32 v26, v3, v23
	v_add_f32_dpp v22, v22, v22 row_half_mirror row_mask:0xf bank_mask:0xf bound_ctrl:1
	s_add_u32 s44, s44, s24
	s_addc_u32 s45, s45, 0
	v_add_f32_dpp v22, v22, v22 row_ror:8 row_mask:0xf bank_mask:0xf bound_ctrl:1
	v_mov_b32_e32 v23, v22
	s_nop 1
	v_permlane16_swap_b32_e32 v22, v23
	v_add_f32_e32 v22, v22, v23
	v_mov_b32_e32 v23, v22
	s_nop 1
	v_permlane32_swap_b32_e32 v22, v23
	v_add_f32_e32 v22, v22, v23
	v_mul_f32_e32 v22, 0x3b000000, v22
	v_add_f32_e64 v32, v182, -v22
	v_add_f32_e64 v33, v183, -v22
	s_lshl_b64 s[24:25], s[44:45], 11
	v_fma_f32 v23, v32, v32, 0
	v_add_f32_e64 v34, v180, -v22
	v_add_f32_e64 v35, v181, -v22
	s_add_u32 s44, s18, s24
	v_fmac_f32_e32 v23, v34, v34
	v_fmac_f32_e32 v23, v33, v33
	v_fmac_f32_e32 v23, v35, v35
	v_add_f32_e64 v36, v178, -v22
	v_add_f32_e64 v37, v179, -v22
	v_add_f32_e64 v38, v176, -v22
	v_add_f32_e64 v39, v177, -v22
	v_fmac_f32_e32 v23, v36, v36
	v_fmac_f32_e32 v23, v38, v38
	v_fmac_f32_e32 v23, v37, v37
	v_fmac_f32_e32 v23, v39, v39
	s_addc_u32 s45, s19, s25
	s_add_i32 s47, s47, s33
	v_add_f32_dpp v22, v23, v23 quad_perm:[1,0,3,2] row_mask:0xf bank_mask:0xf bound_ctrl:1
	s_add_i32 s26, s26, 1
	s_add_i32 s46, s46, s14
	v_add_f32_dpp v22, v22, v22 quad_perm:[2,3,0,1] row_mask:0xf bank_mask:0xf bound_ctrl:1
	s_cmpk_gt_i32 s47, 0xff
	s_waitcnt vmcnt(0)
	v_mov_b32_e32 v24, v18
	v_add_f32_dpp v22, v22, v22 row_half_mirror row_mask:0xf bank_mask:0xf bound_ctrl:1
	s_nop 1
	v_add_f32_dpp v22, v22, v22 row_ror:8 row_mask:0xf bank_mask:0xf bound_ctrl:1
	v_mov_b32_e32 v23, v22
	s_nop 1
	v_permlane16_swap_b32_e32 v22, v23
	v_add_f32_e32 v22, v22, v23
	v_mov_b32_e32 v23, v22
	s_nop 1
	v_permlane32_swap_b32_e32 v22, v23
	v_add_f32_e32 v22, v22, v23
	v_fmamk_f32 v22, v22, 0x3b000000, v115
	v_mul_f32_e32 v23, 0x4f800000, v22
	v_cmp_gt_f32_e32 vcc, s29, v22
	s_nop 1
	v_cndmask_b32_e32 v25, v22, v23, vcc
	v_sqrt_f32_e32 v40, v25
	v_mov_b32_e32 v22, v14
	v_mov_b32_e32 v23, v16
	v_add_u32_e32 v14, -1, v40
	v_fma_f32 v16, -v14, v40, v25
	v_cmp_ge_f32_e64 s[4:5], 0, v16
	v_add_u32_e32 v16, 1, v40
	v_fma_f32 v18, -v16, v40, v25
	v_cndmask_b32_e64 v14, v40, v14, s[4:5]
	v_cmp_lt_f32_e64 s[4:5], 0, v18
	s_nop 1
	v_cndmask_b32_e64 v14, v14, v16, s[4:5]
	v_mul_f32_e32 v16, 0x37800000, v14
	v_cndmask_b32_e32 v14, v14, v16, vcc
	v_cmp_class_f32_e32 vcc, v25, v186
	v_mov_b32_e32 v16, v15
	s_nop 0
	v_cndmask_b32_e32 v14, v14, v25, vcc
	v_div_scale_f32 v18, s[4:5], v14, v14, 1.0
	v_rcp_f32_e32 v40, v18
	v_mov_b32_e32 v25, v20
	v_mov_b32_e32 v20, v19
	v_fma_f32 v15, -v18, v40, 1.0
	v_fmac_f32_e32 v40, v15, v40
	v_div_scale_f32 v15, vcc, 1.0, v14, 1.0
	v_mul_f32_e32 v19, v15, v40
	v_fma_f32 v41, -v18, v19, v15
	v_fmac_f32_e32 v19, v41, v40
	v_fma_f32 v15, -v18, v19, v15
	v_div_fmas_f32 v15, v15, v40, v19
	v_div_fixup_f32 v40, v15, v14, 1.0
	v_mul_f32_e32 v14, v32, v40
	v_mul_f32_e32 v15, v33, v40
	v_mov_b32_e32 v19, v12
	v_fma_f32 v32, v22, v14, v24
	v_fma_f32 v33, v23, v15, v25
	v_mov_b32_e32 v12, v11
	v_mul_f32_e32 v14, 0xbfb8aa3b, v32
	v_exp_f32_e32 v18, v14
	v_mul_f32_e32 v14, v34, v40
	v_mul_f32_e32 v15, v35, v40
	s_nop 0
	v_fma_f32 v34, v16, v14, v20
	v_fma_f32 v35, v17, v15, v21
	v_add_f32_e32 v15, 1.0, v18
	v_mul_f32_e32 v14, 0xbfb8aa3b, v34
	v_exp_f32_e32 v14, v14
	v_rcp_f32_e32 v42, v15
	v_mul_f32_e32 v15, 0xbfb8aa3b, v33
	v_mul_f32_e32 v18, 0xbfb8aa3b, v35
	v_exp_f32_e32 v15, v15
	v_exp_f32_e32 v18, v18
	v_add_f32_e32 v14, 1.0, v14
	v_rcp_f32_e32 v44, v14
	v_add_f32_e32 v14, 1.0, v15
	v_add_f32_e32 v41, 1.0, v18
	v_rcp_f32_e32 v43, v14
	v_mul_f32_e32 v36, v36, v40
	v_mul_f32_e32 v37, v37, v40
	v_mov_b32_e32 v14, v6
	v_mov_b32_e32 v15, v8
	v_mov_b32_e32 v18, v10
	v_fma_f32 v36, v14, v36, v18
	v_fma_f32 v37, v15, v37, v19
	v_mul_f32_e32 v38, v38, v40
	v_mul_f32_e32 v39, v39, v40
	v_mul_f32_e32 v6, 0xbfb8aa3b, v36
	v_mov_b32_e32 v8, v7
	v_exp_f32_e32 v10, v6
	v_fma_f32 v6, v8, v38, v12
	v_fma_f32 v7, v9, v39, v13
	v_mul_f32_e32 v38, 0xbfb8aa3b, v37
	v_mul_f32_e32 v11, 0xbfb8aa3b, v6
	v_exp_f32_e32 v11, v11
	v_exp_f32_e32 v39, v38
	v_mul_f32_e32 v38, 0xbfb8aa3b, v7
	v_exp_f32_e32 v40, v38
	v_add_f32_e32 v11, 1.0, v11
	v_rcp_f32_e32 v38, v11
	v_add_f32_e32 v11, 1.0, v39
	v_add_f32_e32 v39, 1.0, v40
	v_add_f32_e32 v10, 1.0, v10
	v_rcp_f32_e32 v39, v39
	v_rcp_f32_e32 v10, v10
	v_rcp_f32_e32 v11, v11
	v_rcp_f32_e32 v45, v41
	v_mul_f32_e32 v6, v6, v38
	v_mul_f32_e32 v7, v7, v39
	v_mul_f32_e32 v32, v32, v42
	v_mul_f32_e32 v33, v33, v43
	v_mul_f32_e32 v10, v36, v10
	v_mul_f32_e32 v11, v37, v11
	v_bfe_u32 v36, v7, 16, 1
	v_mul_f32_e32 v34, v34, v44
	v_mul_f32_e32 v35, v35, v45
	v_add3_u32 v7, v7, v36, s30
	v_bfe_u32 v36, v10, 16, 1
	v_bfe_u32 v37, v6, 16, 1
	v_bfe_u32 v39, v34, 16, 1
	v_add3_u32 v10, v10, v36, s30
	v_add3_u32 v42, v34, v39, s30
	v_add3_u32 v6, v6, v37, s30
	v_bfe_u32 v34, v32, 16, 1
	v_lshrrev_b32_e32 v10, 16, v10
	v_add3_u32 v32, v32, v34, s30
	v_and_or_b32 v34, v6, s27, v10
	v_add_f32_dpp v6, v31, v31 quad_perm:[1,0,3,2] row_mask:0xf bank_mask:0xf bound_ctrl:1
	v_bfe_u32 v37, v11, 16, 1
	v_bfe_u32 v38, v35, 16, 1
	v_add_f32_dpp v6, v6, v6 quad_perm:[2,3,0,1] row_mask:0xf bank_mask:0xf bound_ctrl:1
	v_add3_u32 v11, v11, v37, s30
	v_add3_u32 v43, v35, v38, s30
	v_add_f32_dpp v6, v6, v6 row_half_mirror row_mask:0xf bank_mask:0xf bound_ctrl:1
	v_bfe_u32 v35, v33, 16, 1
	v_lshrrev_b32_e32 v11, 16, v11
	v_add_f32_dpp v6, v6, v6 row_ror:8 row_mask:0xf bank_mask:0xf bound_ctrl:1
	v_add3_u32 v33, v33, v35, s30
	v_and_or_b32 v35, v7, s27, v11
	v_mov_b32_e32 v7, v6
	s_nop 1
	v_permlane16_swap_b32_e32 v6, v7
	v_add_f32_e32 v6, v6, v7
	v_mov_b32_e32 v7, v6
	s_nop 1
	v_permlane32_swap_b32_e32 v6, v7
	v_add_f32_e32 v6, v6, v7
	v_mul_f32_e32 v6, 0x3b000000, v6
	v_add_f32_e64 v10, v174, -v6
	v_add_f32_e64 v11, v175, -v6
	v_lshrrev_b32_e32 v32, 16, v32
	v_fma_f32 v7, v10, v10, 0
	v_add_f32_e64 v36, v172, -v6
	v_add_f32_e64 v37, v173, -v6
	v_and_or_b32 v32, v42, s27, v32
	v_fmac_f32_e32 v7, v36, v36
	v_fmac_f32_e32 v7, v11, v11
	v_fmac_f32_e32 v7, v37, v37
	v_add_f32_e64 v38, v170, -v6
	v_add_f32_e64 v39, v171, -v6
	v_add_f32_e64 v40, v168, -v6
	v_add_f32_e64 v41, v169, -v6
	v_fmac_f32_e32 v7, v38, v38
	v_fmac_f32_e32 v7, v40, v40
	v_fmac_f32_e32 v7, v39, v39
	v_fmac_f32_e32 v7, v41, v41
	v_lshrrev_b32_e32 v33, 16, v33
	v_and_or_b32 v33, v43, s27, v33
	v_add_f32_dpp v6, v7, v7 quad_perm:[1,0,3,2] row_mask:0xf bank_mask:0xf bound_ctrl:1
	global_store_dwordx4 v116, v[32:35], s[44:45] offset:1024
	s_nop 0
	v_add_f32_dpp v6, v6, v6 quad_perm:[2,3,0,1] row_mask:0xf bank_mask:0xf bound_ctrl:1
	s_nop 1
	v_add_f32_dpp v6, v6, v6 row_half_mirror row_mask:0xf bank_mask:0xf bound_ctrl:1
	s_nop 1
	v_add_f32_dpp v6, v6, v6 row_ror:8 row_mask:0xf bank_mask:0xf bound_ctrl:1
	v_mov_b32_e32 v7, v6
	s_nop 1
	v_permlane16_swap_b32_e32 v6, v7
	v_add_f32_e32 v6, v6, v7
	v_mov_b32_e32 v7, v6
	s_nop 1
	v_permlane32_swap_b32_e32 v6, v7
	v_add_f32_e32 v6, v6, v7
	v_fmamk_f32 v6, v6, 0x3b000000, v115
	v_mul_f32_e32 v7, 0x4f800000, v6
	v_cmp_gt_f32_e32 vcc, s29, v6
	s_nop 1
	v_cndmask_b32_e32 v6, v6, v7, vcc
	v_sqrt_f32_e32 v7, v6
	s_nop 0
	v_add_u32_e32 v31, -1, v7
	v_fma_f32 v42, -v31, v7, v6
	v_cmp_ge_f32_e64 s[4:5], 0, v42
	v_add_u32_e32 v42, 1, v7
	s_nop 0
	v_cndmask_b32_e64 v31, v7, v31, s[4:5]
	v_fma_f32 v7, -v42, v7, v6
	v_cmp_lt_f32_e64 s[4:5], 0, v7
	s_nop 1
	v_cndmask_b32_e64 v7, v31, v42, s[4:5]
	v_mul_f32_e32 v31, 0x37800000, v7
	v_cndmask_b32_e32 v7, v7, v31, vcc
	v_cmp_class_f32_e32 vcc, v6, v186
	s_nop 1
	v_cndmask_b32_e32 v31, v7, v6, vcc
	v_div_scale_f32 v42, s[4:5], v31, v31, 1.0
	v_rcp_f32_e32 v43, v42
	v_lshl_add_u64 v[6:7], s[44:45], 0, v[116:117]
	v_fma_f32 v44, -v42, v43, 1.0
	v_fmac_f32_e32 v43, v44, v43
	v_div_scale_f32 v44, vcc, 1.0, v31, 1.0
	v_mul_f32_e32 v45, v44, v43
	v_fma_f32 v47, -v42, v45, v44
	v_fmac_f32_e32 v45, v47, v43
	v_fma_f32 v42, -v42, v45, v44
	v_div_fmas_f32 v42, v42, v43, v45
	v_div_fixup_f32 v42, v42, v31, 1.0
	v_mul_f32_e32 v10, v10, v42
	v_mul_f32_e32 v11, v11, v42
	v_mul_f32_e32 v36, v36, v42
	v_mul_f32_e32 v37, v37, v42
	v_fma_f32 v10, v22, v10, v24
	v_fma_f32 v11, v23, v11, v25
	v_fma_f32 v36, v16, v36, v20
	v_fma_f32 v37, v17, v37, v21
	v_mul_f32_e32 v31, 0xbfb8aa3b, v10
	v_exp_f32_e32 v31, v31
	v_mul_f32_e32 v43, 0xbfb8aa3b, v36
	v_exp_f32_e32 v43, v43
	v_mul_f32_e32 v33, 0xbfb8aa3b, v11
	v_exp_f32_e32 v33, v33
	v_mul_f32_e32 v34, 0xbfb8aa3b, v37
	v_exp_f32_e32 v35, v34
	v_add_f32_e32 v31, 1.0, v31
	v_rcp_f32_e32 v32, v31
	v_add_f32_e32 v31, 1.0, v43
	v_mul_f32_e32 v38, v38, v42
	v_mul_f32_e32 v39, v39, v42
	v_rcp_f32_e32 v34, v31
	v_add_f32_e32 v31, 1.0, v33
	v_fma_f32 v38, v14, v38, v18
	v_fma_f32 v39, v15, v39, v19
	v_rcp_f32_e32 v33, v31
	v_add_f32_e32 v31, 1.0, v35
	v_mul_f32_e32 v35, 0xbfb8aa3b, v38
	v_exp_f32_e32 v43, v35
	v_mul_f32_e32 v10, v10, v32
	v_mul_f32_e32 v11, v11, v33
	v_mul_f32_e32 v40, v40, v42
	v_mul_f32_e32 v41, v41, v42
	s_nop 0
	v_fma_f32 v40, v8, v40, v12
	v_fma_f32 v41, v9, v41, v13
	s_nop 0
	v_mul_f32_e32 v35, 0xbfb8aa3b, v40
	v_exp_f32_e32 v44, v35
	v_rcp_f32_e32 v35, v31
	v_add_f32_e32 v31, 1.0, v43
	v_mul_f32_e32 v43, 0xbfb8aa3b, v39
	v_rcp_f32_e32 v42, v31
	v_add_f32_e32 v31, 1.0, v44
	v_exp_f32_e32 v43, v43
	v_mul_f32_e32 v44, 0xbfb8aa3b, v41
	v_exp_f32_e32 v45, v44
	v_rcp_f32_e32 v44, v31
	v_add_f32_e32 v31, 1.0, v43
	v_rcp_f32_e32 v43, v31
	v_add_f32_e32 v31, 1.0, v45
	v_rcp_f32_e32 v45, v31
	v_mul_f32_e32 v32, v36, v34
	v_mul_f32_e32 v33, v37, v35
	v_mul_f32_e32 v34, v38, v42
	v_mul_f32_e32 v35, v39, v43
	v_bfe_u32 v39, v33, 16, 1
	v_mul_f32_e32 v36, v40, v44
	v_mul_f32_e32 v37, v41, v45
	v_add3_u32 v33, v33, v39, s30
	v_bfe_u32 v38, v36, 16, 1
	v_add3_u32 v42, v36, v38, s30
	v_bfe_u32 v36, v10, 16, 1
	v_add3_u32 v10, v10, v36, s30
	v_lshrrev_b32_e32 v43, 16, v10
	v_bfe_u32 v31, v37, 16, 1
	v_add_f32_dpp v10, v46, v46 quad_perm:[1,0,3,2] row_mask:0xf bank_mask:0xf bound_ctrl:1
	v_add3_u32 v31, v37, v31, s30
	v_bfe_u32 v37, v11, 16, 1
	v_add_f32_dpp v10, v10, v10 quad_perm:[2,3,0,1] row_mask:0xf bank_mask:0xf bound_ctrl:1
	v_add3_u32 v11, v11, v37, s30
	v_lshrrev_b32_e32 v44, 16, v11
	v_add_f32_dpp v10, v10, v10 row_half_mirror row_mask:0xf bank_mask:0xf bound_ctrl:1
	v_bfe_u32 v38, v34, 16, 1
	v_bfe_u32 v39, v35, 16, 1
	v_add_f32_dpp v10, v10, v10 row_ror:8 row_mask:0xf bank_mask:0xf bound_ctrl:1
	v_mov_b32_e32 v11, v10
	s_nop 1
	v_permlane16_swap_b32_e32 v10, v11
	v_add_f32_e32 v10, v10, v11
	v_mov_b32_e32 v11, v10
	s_nop 1
	v_permlane32_swap_b32_e32 v10, v11
	v_add_f32_e32 v10, v10, v11
	v_mul_f32_e32 v10, 0x3b000000, v10
	v_add_f32_e64 v36, v166, -v10
	v_add_f32_e64 v37, v167, -v10
	v_add3_u32 v35, v35, v39, s30
	v_add3_u32 v34, v34, v38, s30
	v_fma_f32 v45, v36, v36, 0
	v_add_f32_e64 v38, v164, -v10
	v_add_f32_e64 v39, v165, -v10
	v_bfe_u32 v40, v32, 16, 1
	v_fmac_f32_e32 v45, v38, v38
	v_fmac_f32_e32 v45, v37, v37
	v_add3_u32 v32, v32, v40, s30
	v_fmac_f32_e32 v45, v39, v39
	v_add_f32_e64 v40, v162, -v10
	v_add_f32_e64 v41, v163, -v10
	v_add_f32_e64 v11, v161, -v10
	v_add_f32_e64 v10, v160, -v10
	v_fmac_f32_e32 v45, v40, v40
	v_fmac_f32_e32 v45, v10, v10
	v_fmac_f32_e32 v45, v41, v41
	v_fmac_f32_e32 v45, v11, v11
	v_lshrrev_b32_e32 v35, 16, v35
	v_and_or_b32 v35, v31, s27, v35
	v_add_f32_dpp v45, v45, v45 quad_perm:[1,0,3,2] row_mask:0xf bank_mask:0xf bound_ctrl:1
	v_lshrrev_b32_e32 v34, 16, v34
	v_and_or_b32 v34, v42, s27, v34
	v_add_f32_dpp v45, v45, v45 quad_perm:[2,3,0,1] row_mask:0xf bank_mask:0xf bound_ctrl:1
	v_and_or_b32 v32, v32, s27, v43
	v_and_or_b32 v33, v33, s27, v44
	v_add_f32_dpp v45, v45, v45 row_half_mirror row_mask:0xf bank_mask:0xf bound_ctrl:1
	global_store_dwordx4 v116, v[32:35], s[44:45] offset:3072
	s_nop 0
	v_add_f32_dpp v45, v45, v45 row_ror:8 row_mask:0xf bank_mask:0xf bound_ctrl:1
	v_mov_b32_e32 v46, v45
	s_nop 1
	v_permlane16_swap_b32_e32 v45, v46
	v_add_f32_e32 v45, v45, v46
	v_mov_b32_e32 v46, v45
	s_nop 1
	v_permlane32_swap_b32_e32 v45, v46
	v_add_f32_e32 v45, v45, v46
	v_fmamk_f32 v45, v45, 0x3b000000, v115
	v_mul_f32_e32 v46, 0x4f800000, v45
	v_cmp_gt_f32_e32 vcc, s29, v45
	s_nop 1
	v_cndmask_b32_e32 v45, v45, v46, vcc
	v_sqrt_f32_e32 v46, v45
	s_nop 0
	v_add_u32_e32 v31, -1, v46
	v_fma_f32 v47, -v31, v46, v45
	v_cmp_ge_f32_e64 s[4:5], 0, v47
	v_add_u32_e32 v47, 1, v46
	s_nop 0
	v_cndmask_b32_e64 v31, v46, v31, s[4:5]
	v_fma_f32 v46, -v47, v46, v45
	v_cmp_lt_f32_e64 s[4:5], 0, v46
	s_nop 1
	v_cndmask_b32_e64 v31, v31, v47, s[4:5]
	v_mul_f32_e32 v46, 0x37800000, v31
	v_cndmask_b32_e32 v31, v31, v46, vcc
	v_cmp_class_f32_e32 vcc, v45, v186
	s_nop 1
	v_cndmask_b32_e32 v31, v31, v45, vcc
	v_div_scale_f32 v45, s[4:5], v31, v31, 1.0
	v_rcp_f32_e32 v46, v45
	s_nop 0
	v_fma_f32 v42, -v45, v46, 1.0
	v_fmac_f32_e32 v46, v42, v46
	v_div_scale_f32 v42, vcc, 1.0, v31, 1.0
	v_mul_f32_e32 v43, v42, v46
	v_fma_f32 v44, -v45, v43, v42
	v_fmac_f32_e32 v43, v44, v46
	v_fma_f32 v42, -v45, v43, v42
	v_div_fmas_f32 v42, v42, v46, v43
	v_div_fixup_f32 v42, v42, v31, 1.0
	v_mul_f32_e32 v36, v36, v42
	v_mul_f32_e32 v37, v37, v42
	v_mul_f32_e32 v38, v38, v42
	v_mul_f32_e32 v39, v39, v42
	v_fma_f32 v36, v22, v36, v24
	v_fma_f32 v37, v23, v37, v25
	v_fma_f32 v38, v16, v38, v20
	v_fma_f32 v39, v17, v39, v21
	v_mul_f32_e32 v31, 0xbfb8aa3b, v36
	v_exp_f32_e32 v31, v31
	v_mul_f32_e32 v43, 0xbfb8aa3b, v38
	v_exp_f32_e32 v43, v43
	v_mul_f32_e32 v33, 0xbfb8aa3b, v37
	v_exp_f32_e32 v33, v33
	v_mul_f32_e32 v34, 0xbfb8aa3b, v39
	v_exp_f32_e32 v35, v34
	v_add_f32_e32 v31, 1.0, v31
	v_rcp_f32_e32 v32, v31
	v_add_f32_e32 v31, 1.0, v43
	v_mul_f32_e32 v40, v40, v42
	v_mul_f32_e32 v41, v41, v42
	v_rcp_f32_e32 v34, v31
	v_add_f32_e32 v31, 1.0, v33
	v_fma_f32 v40, v14, v40, v18
	v_fma_f32 v41, v15, v41, v19
	v_rcp_f32_e32 v33, v31
	v_add_f32_e32 v31, 1.0, v35
	v_mul_f32_e32 v35, 0xbfb8aa3b, v40
	v_exp_f32_e32 v43, v35
	v_mul_f32_e32 v32, v36, v32
	v_mul_f32_e32 v33, v37, v33
	v_mul_f32_e32 v10, v10, v42
	v_mul_f32_e32 v11, v11, v42
	s_nop 0
	v_fma_f32 v10, v8, v10, v12
	v_fma_f32 v11, v9, v11, v13
	s_nop 0
	v_mul_f32_e32 v35, 0xbfb8aa3b, v10
	v_exp_f32_e32 v44, v35
	v_rcp_f32_e32 v35, v31
	v_add_f32_e32 v31, 1.0, v43
	v_mul_f32_e32 v43, 0xbfb8aa3b, v41
	v_rcp_f32_e32 v42, v31
	v_add_f32_e32 v31, 1.0, v44
	v_exp_f32_e32 v43, v43
	v_mul_f32_e32 v44, 0xbfb8aa3b, v11
	v_exp_f32_e32 v45, v44
	v_rcp_f32_e32 v44, v31
	v_add_f32_e32 v31, 1.0, v43
	v_rcp_f32_e32 v43, v31
	v_add_f32_e32 v31, 1.0, v45
	v_rcp_f32_e32 v45, v31
	v_mul_f32_e32 v34, v38, v34
	v_mul_f32_e32 v35, v39, v35
	v_mul_f32_e32 v36, v40, v42
	v_mul_f32_e32 v37, v41, v43
	v_bfe_u32 v39, v35, 16, 1
	v_mul_f32_e32 v10, v10, v44
	v_mul_f32_e32 v11, v11, v45
	v_add3_u32 v41, v35, v39, s30
	v_bfe_u32 v31, v11, 16, 1
	v_bfe_u32 v38, v10, 16, 1
	v_add3_u32 v42, v10, v38, s30
	v_add3_u32 v10, v11, v31, s30
	v_bfe_u32 v11, v32, 16, 1
	v_bfe_u32 v35, v37, 16, 1
	v_add3_u32 v35, v37, v35, s30
	v_add3_u32 v11, v32, v11, s30
	v_bfe_u32 v31, v33, 16, 1
	v_lshrrev_b32_e32 v43, 16, v11
	v_lshrrev_b32_e32 v11, 16, v35
	v_add3_u32 v31, v33, v31, s30
	v_and_or_b32 v33, v10, s27, v11
	v_add_f32_dpp v10, v30, v30 quad_perm:[1,0,3,2] row_mask:0xf bank_mask:0xf bound_ctrl:1
	v_bfe_u32 v40, v34, 16, 1
	v_add3_u32 v40, v34, v40, s30
	v_add_f32_dpp v10, v10, v10 quad_perm:[2,3,0,1] row_mask:0xf bank_mask:0xf bound_ctrl:1
	v_bfe_u32 v34, v36, 16, 1
	v_add3_u32 v34, v36, v34, s30
	v_add_f32_dpp v10, v10, v10 row_half_mirror row_mask:0xf bank_mask:0xf bound_ctrl:1
	v_lshrrev_b32_e32 v32, 16, v34
	v_lshrrev_b32_e32 v31, 16, v31
	v_add_f32_dpp v10, v10, v10 row_ror:8 row_mask:0xf bank_mask:0xf bound_ctrl:1
	v_mov_b32_e32 v11, v10
	s_nop 1
	v_permlane16_swap_b32_e32 v10, v11
	v_add_f32_e32 v10, v10, v11
	v_mov_b32_e32 v11, v10
	s_nop 1
	v_permlane32_swap_b32_e32 v10, v11
	v_add_f32_e32 v10, v10, v11
	v_mul_f32_e32 v10, 0x3b000000, v10
	v_add_f32_e64 v34, v158, -v10
	v_add_f32_e64 v35, v159, -v10
	v_add_f32_e64 v36, v156, -v10
	v_add_f32_e64 v37, v157, -v10
	v_fma_f32 v30, v34, v34, 0
	v_fmac_f32_e32 v30, v36, v36
	v_fmac_f32_e32 v30, v35, v35
	v_fmac_f32_e32 v30, v37, v37
	v_add_f32_e64 v38, v154, -v10
	v_add_f32_e64 v39, v155, -v10
	v_add_f32_e64 v11, v153, -v10
	v_add_f32_e64 v10, v152, -v10
	v_fmac_f32_e32 v30, v38, v38
	v_fmac_f32_e32 v30, v10, v10
	v_fmac_f32_e32 v30, v39, v39
	v_fmac_f32_e32 v30, v11, v11
	v_and_or_b32 v31, v41, s27, v31
	v_and_or_b32 v32, v42, s27, v32
	v_add_f32_dpp v30, v30, v30 quad_perm:[1,0,3,2] row_mask:0xf bank_mask:0xf bound_ctrl:1
	s_nop 1
	v_add_f32_dpp v30, v30, v30 quad_perm:[2,3,0,1] row_mask:0xf bank_mask:0xf bound_ctrl:1
	s_nop 1
	v_add_f32_dpp v30, v30, v30 row_half_mirror row_mask:0xf bank_mask:0xf bound_ctrl:1
	s_nop 1
	v_add_f32_dpp v30, v30, v30 row_ror:8 row_mask:0xf bank_mask:0xf bound_ctrl:1
	v_mov_b32_e32 v44, v30
	s_nop 1
	v_permlane16_swap_b32_e32 v30, v44
	v_add_f32_e32 v30, v30, v44
	v_mov_b32_e32 v44, v30
	s_nop 1
	v_permlane32_swap_b32_e32 v30, v44
	v_add_f32_e32 v30, v30, v44
	v_fmamk_f32 v30, v30, 0x3b000000, v115
	v_mul_f32_e32 v44, 0x4f800000, v30
	v_cmp_gt_f32_e32 vcc, s29, v30
	s_nop 1
	v_cndmask_b32_e32 v44, v30, v44, vcc
	v_sqrt_f32_e32 v45, v44
	v_and_or_b32 v30, v40, s27, v43
	v_add_u32_e32 v40, -1, v45
	v_fma_f32 v41, -v40, v45, v44
	v_cmp_ge_f32_e64 s[4:5], 0, v41
	v_add_u32_e32 v41, 1, v45
	v_fma_f32 v42, -v41, v45, v44
	v_cndmask_b32_e64 v40, v45, v40, s[4:5]
	v_cmp_lt_f32_e64 s[4:5], 0, v42
	s_nop 1
	v_cndmask_b32_e64 v40, v40, v41, s[4:5]
	v_mul_f32_e32 v41, 0x37800000, v40
	v_cndmask_b32_e32 v40, v40, v41, vcc
	v_cmp_class_f32_e32 vcc, v44, v186
	s_nop 1
	v_cndmask_b32_e32 v42, v40, v44, vcc
	v_div_scale_f32 v43, s[4:5], v42, v42, 1.0
	v_rcp_f32_e32 v44, v43
	v_add_co_u32_e32 v40, vcc, s31, v6
	v_fma_f32 v45, -v43, v44, 1.0
	s_nop 0
	v_addc_co_u32_e32 v41, vcc, 0, v7, vcc
	v_fmac_f32_e32 v44, v45, v44
	v_div_scale_f32 v45, vcc, 1.0, v42, 1.0
	v_mul_f32_e32 v46, v45, v44
	v_fma_f32 v47, -v43, v46, v45
	v_fmac_f32_e32 v46, v47, v44
	v_fma_f32 v43, -v43, v46, v45
	v_div_fmas_f32 v43, v43, v44, v46
	v_div_fixup_f32 v42, v43, v42, 1.0
	v_mul_f32_e32 v34, v34, v42
	v_mul_f32_e32 v35, v35, v42
	global_store_dwordx4 v[40:41], v[30:33], off offset:1024
	v_fma_f32 v34, v22, v34, v24
	v_fma_f32 v35, v23, v35, v25
	s_nop 0
	v_mul_f32_e32 v43, 0xbfb8aa3b, v34
	v_exp_f32_e32 v43, v43
	v_mul_f32_e32 v32, 0xbfb8aa3b, v35
	v_exp_f32_e32 v33, v32
	v_mul_f32_e32 v36, v36, v42
	v_mul_f32_e32 v37, v37, v42
	s_nop 0
	v_fma_f32 v36, v16, v36, v20
	v_fma_f32 v37, v17, v37, v21
	v_add_f32_e32 v30, 1.0, v43
	v_mul_f32_e32 v32, 0xbfb8aa3b, v37
	v_mul_f32_e32 v44, 0xbfb8aa3b, v36
	v_exp_f32_e32 v43, v32
	v_exp_f32_e32 v44, v44
	v_rcp_f32_e32 v30, v30
	v_mul_f32_e32 v38, v38, v42
	v_mul_f32_e32 v39, v39, v42
	v_add_f32_e32 v31, 1.0, v44
	v_fma_f32 v38, v14, v38, v18
	v_fma_f32 v39, v15, v39, v19
	v_rcp_f32_e32 v32, v31
	v_add_f32_e32 v31, 1.0, v33
	v_add_f32_e32 v33, 1.0, v43
	v_mul_f32_e32 v43, 0xbfb8aa3b, v38
	v_exp_f32_e32 v43, v43
	v_rcp_f32_e32 v33, v33
	v_rcp_f32_e32 v31, v31
	v_mul_f32_e32 v10, v10, v42
	v_mul_f32_e32 v11, v11, v42
	s_nop 0
	v_fma_f32 v10, v8, v10, v12
	v_fma_f32 v11, v9, v11, v13
	v_mul_f32_e32 v32, v36, v32
	v_mul_f32_e32 v33, v37, v33
	v_mul_f32_e32 v42, 0xbfb8aa3b, v10
	v_exp_f32_e32 v44, v42
	v_add_f32_e32 v42, 1.0, v43
	v_rcp_f32_e32 v42, v42
	v_mul_f32_e32 v30, v34, v30
	v_mul_f32_e32 v31, v35, v31
	v_add_f32_e32 v43, 1.0, v44
	v_mul_f32_e32 v44, 0xbfb8aa3b, v39
	v_exp_f32_e32 v45, v44
	v_mul_f32_e32 v44, 0xbfb8aa3b, v11
	v_exp_f32_e32 v46, v44
	v_rcp_f32_e32 v44, v43
	v_add_f32_e32 v43, 1.0, v45
	v_rcp_f32_e32 v43, v43
	v_add_f32_e32 v45, 1.0, v46
	v_rcp_f32_e32 v45, v45
	v_mul_f32_e32 v34, v38, v42
	v_mul_f32_e32 v35, v39, v43
	v_bfe_u32 v39, v32, 16, 1
	v_mul_f32_e32 v10, v10, v44
	v_mul_f32_e32 v11, v11, v45
	v_add3_u32 v42, v32, v39, s30
	v_bfe_u32 v37, v10, 16, 1
	v_add3_u32 v32, v10, v37, s30
	v_bfe_u32 v10, v30, 16, 1
	v_add3_u32 v10, v30, v10, s30
	v_lshrrev_b32_e32 v30, 16, v10
	v_bfe_u32 v36, v11, 16, 1
	v_add_f32_dpp v10, v29, v29 quad_perm:[1,0,3,2] row_mask:0xf bank_mask:0xf bound_ctrl:1
	v_bfe_u32 v38, v33, 16, 1
	v_add3_u32 v43, v33, v38, s30
	v_add_f32_dpp v10, v10, v10 quad_perm:[2,3,0,1] row_mask:0xf bank_mask:0xf bound_ctrl:1
	v_add3_u32 v33, v11, v36, s30
	v_bfe_u32 v11, v31, 16, 1
	v_add_f32_dpp v10, v10, v10 row_half_mirror row_mask:0xf bank_mask:0xf bound_ctrl:1
	v_add3_u32 v11, v31, v11, s30
	v_lshrrev_b32_e32 v31, 16, v11
	v_add_f32_dpp v10, v10, v10 row_ror:8 row_mask:0xf bank_mask:0xf bound_ctrl:1
	v_mov_b32_e32 v11, v10
	s_nop 1
	v_permlane16_swap_b32_e32 v10, v11
	v_add_f32_e32 v10, v10, v11
	v_mov_b32_e32 v11, v10
	s_nop 1
	v_permlane32_swap_b32_e32 v10, v11
	v_add_f32_e32 v10, v10, v11
	v_bfe_u32 v36, v34, 16, 1
	v_bfe_u32 v37, v35, 16, 1
	v_mul_f32_e32 v10, 0x3b000000, v10
	v_add3_u32 v44, v35, v37, s30
	v_add3_u32 v45, v34, v36, s30
	v_add_f32_e64 v34, v150, -v10
	v_add_f32_e64 v35, v151, -v10
	v_add_f32_e64 v36, v148, -v10
	v_add_f32_e64 v37, v149, -v10
	v_fma_f32 v29, v34, v34, 0
	v_fmac_f32_e32 v29, v36, v36
	v_fmac_f32_e32 v29, v35, v35
	v_fmac_f32_e32 v29, v37, v37
	v_add_f32_e64 v38, v146, -v10
	v_add_f32_e64 v39, v147, -v10
	v_add_f32_e64 v11, v145, -v10
	v_add_f32_e64 v10, v144, -v10
	v_fmac_f32_e32 v29, v38, v38
	v_fmac_f32_e32 v29, v10, v10
	v_fmac_f32_e32 v29, v39, v39
	v_fmac_f32_e32 v29, v11, v11
	v_lshrrev_b32_e32 v44, 16, v44
	v_and_or_b32 v33, v33, s27, v44
	v_add_f32_dpp v29, v29, v29 quad_perm:[1,0,3,2] row_mask:0xf bank_mask:0xf bound_ctrl:1
	v_and_or_b32 v30, v42, s27, v30
	v_lshrrev_b32_e32 v45, 16, v45
	v_add_f32_dpp v29, v29, v29 quad_perm:[2,3,0,1] row_mask:0xf bank_mask:0xf bound_ctrl:1
	v_and_or_b32 v31, v43, s27, v31
	v_and_or_b32 v32, v32, s27, v45
	v_add_f32_dpp v29, v29, v29 row_half_mirror row_mask:0xf bank_mask:0xf bound_ctrl:1
	global_store_dwordx4 v[40:41], v[30:33], off offset:3072
	s_nop 0
	v_add_f32_dpp v29, v29, v29 row_ror:8 row_mask:0xf bank_mask:0xf bound_ctrl:1
	v_mov_b32_e32 v46, v29
	s_nop 1
	v_permlane16_swap_b32_e32 v29, v46
	v_add_f32_e32 v29, v29, v46
	v_mov_b32_e32 v46, v29
	s_nop 1
	v_permlane32_swap_b32_e32 v29, v46
	v_add_f32_e32 v29, v29, v46
	v_fmamk_f32 v29, v29, 0x3b000000, v115
	v_mul_f32_e32 v46, 0x4f800000, v29
	v_cmp_gt_f32_e32 vcc, s29, v29
	s_nop 1
	v_cndmask_b32_e32 v29, v29, v46, vcc
	v_sqrt_f32_e32 v46, v29
	s_nop 0
	v_add_u32_e32 v44, -1, v46
	v_fma_f32 v47, -v44, v46, v29
	v_cmp_ge_f32_e64 s[4:5], 0, v47
	v_add_u32_e32 v47, 1, v46
	s_nop 0
	v_cndmask_b32_e64 v44, v46, v44, s[4:5]
	v_fma_f32 v46, -v47, v46, v29
	v_cmp_lt_f32_e64 s[4:5], 0, v46
	s_nop 1
	v_cndmask_b32_e64 v44, v44, v47, s[4:5]
	v_mul_f32_e32 v46, 0x37800000, v44
	v_cndmask_b32_e32 v44, v44, v46, vcc
	v_cmp_class_f32_e32 vcc, v29, v186
	s_nop 1
	v_cndmask_b32_e32 v29, v44, v29, vcc
	v_div_scale_f32 v44, s[4:5], v29, v29, 1.0
	v_rcp_f32_e32 v46, v44
	s_nop 0
	v_fma_f32 v42, -v44, v46, 1.0
	v_fmac_f32_e32 v46, v42, v46
	v_div_scale_f32 v42, vcc, 1.0, v29, 1.0
	v_mul_f32_e32 v43, v42, v46
	v_fma_f32 v45, -v44, v43, v42
	v_fmac_f32_e32 v43, v45, v46
	v_fma_f32 v42, -v44, v43, v42
	v_div_fmas_f32 v42, v42, v46, v43
	v_div_fixup_f32 v42, v42, v29, 1.0
	v_mul_f32_e32 v34, v34, v42
	v_mul_f32_e32 v35, v35, v42
	v_mul_f32_e32 v36, v36, v42
	v_mul_f32_e32 v37, v37, v42
	v_fma_f32 v34, v22, v34, v24
	v_fma_f32 v35, v23, v35, v25
	v_fma_f32 v36, v16, v36, v20
	v_fma_f32 v37, v17, v37, v21
	v_mul_f32_e32 v29, 0xbfb8aa3b, v34
	v_exp_f32_e32 v29, v29
	v_mul_f32_e32 v43, 0xbfb8aa3b, v36
	v_exp_f32_e32 v43, v43
	v_mul_f32_e32 v31, 0xbfb8aa3b, v35
	v_exp_f32_e32 v31, v31
	v_mul_f32_e32 v32, 0xbfb8aa3b, v37
	v_exp_f32_e32 v33, v32
	v_add_f32_e32 v29, 1.0, v29
	v_rcp_f32_e32 v30, v29
	v_add_f32_e32 v29, 1.0, v43
	v_mul_f32_e32 v38, v38, v42
	v_mul_f32_e32 v39, v39, v42
	v_rcp_f32_e32 v32, v29
	v_add_f32_e32 v29, 1.0, v31
	v_fma_f32 v38, v14, v38, v18
	v_fma_f32 v39, v15, v39, v19
	v_mul_f32_e32 v10, v10, v42
	v_mul_f32_e32 v11, v11, v42
	v_rcp_f32_e32 v31, v29
	v_add_f32_e32 v29, 1.0, v33
	v_mul_f32_e32 v33, 0xbfb8aa3b, v38
	v_fma_f32 v10, v8, v10, v12
	v_fma_f32 v11, v9, v11, v13
	v_exp_f32_e32 v40, v33
	v_mul_f32_e32 v33, 0xbfb8aa3b, v10
	v_exp_f32_e32 v41, v33
	v_rcp_f32_e32 v33, v29
	v_add_f32_e32 v29, 1.0, v40
	v_rcp_f32_e32 v40, v29
	v_add_f32_e32 v29, 1.0, v41
	v_mul_f32_e32 v41, 0xbfb8aa3b, v39
	v_exp_f32_e32 v41, v41
	v_mul_f32_e32 v42, 0xbfb8aa3b, v11
	v_exp_f32_e32 v43, v42
	v_rcp_f32_e32 v42, v29
	v_add_f32_e32 v29, 1.0, v41
	v_rcp_f32_e32 v41, v29
	v_add_f32_e32 v29, 1.0, v43
	v_rcp_f32_e32 v43, v29
	v_mul_f32_e32 v32, v36, v32
	v_mul_f32_e32 v33, v37, v33
	v_mul_f32_e32 v30, v34, v30
	v_mul_f32_e32 v31, v35, v31
	v_mul_f32_e32 v34, v38, v40
	v_mul_f32_e32 v35, v39, v41
	v_mul_f32_e32 v10, v10, v42
	v_mul_f32_e32 v11, v11, v43
	v_bfe_u32 v37, v33, 16, 1
	v_bfe_u32 v29, v11, 16, 1
	v_bfe_u32 v36, v10, 16, 1
	v_bfe_u32 v38, v32, 16, 1
	v_add3_u32 v37, v33, v37, s30
	v_add3_u32 v36, v10, v36, s30
	v_add3_u32 v10, v11, v29, s30
	v_bfe_u32 v11, v30, 16, 1
	v_bfe_u32 v33, v35, 16, 1
	v_add3_u32 v38, v32, v38, s30
	v_bfe_u32 v32, v34, 16, 1
	v_add3_u32 v33, v35, v33, s30
	v_add3_u32 v11, v30, v11, s30
	v_bfe_u32 v29, v31, 16, 1
	v_add3_u32 v32, v34, v32, s30
	v_lshrrev_b32_e32 v34, 16, v11
	v_lshrrev_b32_e32 v11, 16, v33
	v_add3_u32 v29, v31, v29, s30
	v_and_or_b32 v31, v10, s27, v11
	v_add_f32_dpp v10, v28, v28 quad_perm:[1,0,3,2] row_mask:0xf bank_mask:0xf bound_ctrl:1
	v_lshrrev_b32_e32 v30, 16, v32
	v_and_or_b32 v30, v36, s27, v30
	v_add_f32_dpp v10, v10, v10 quad_perm:[2,3,0,1] row_mask:0xf bank_mask:0xf bound_ctrl:1
	v_lshrrev_b32_e32 v29, 16, v29
	v_and_or_b32 v29, v37, s27, v29
	v_add_f32_dpp v10, v10, v10 row_half_mirror row_mask:0xf bank_mask:0xf bound_ctrl:1
	s_nop 1
	v_add_f32_dpp v10, v10, v10 row_ror:8 row_mask:0xf bank_mask:0xf bound_ctrl:1
	v_mov_b32_e32 v11, v10
	s_nop 1
	v_permlane16_swap_b32_e32 v10, v11
	v_add_f32_e32 v10, v10, v11
	v_mov_b32_e32 v11, v10
	s_nop 1
	v_permlane32_swap_b32_e32 v10, v11
	v_add_f32_e32 v10, v10, v11
	v_mul_f32_e32 v10, 0x3b000000, v10
	v_add_f32_e64 v4, v4, -v10
	v_add_f32_e64 v5, v5, -v10
	v_add_f32_e64 v32, v142, -v10
	v_add_f32_e64 v33, v143, -v10
	v_fma_f32 v28, v4, v4, 0
	v_fmac_f32_e32 v28, v32, v32
	v_fmac_f32_e32 v28, v5, v5
	v_fmac_f32_e32 v28, v33, v33
	v_add_f32_e64 v0, v0, -v10
	v_add_f32_e64 v1, v1, -v10
	v_add_f32_e64 v11, v141, -v10
	v_add_f32_e64 v10, v140, -v10
	v_fmac_f32_e32 v28, v0, v0
	v_fmac_f32_e32 v28, v10, v10
	v_fmac_f32_e32 v28, v1, v1
	v_fmac_f32_e32 v28, v11, v11
	s_nop 1
	v_add_f32_dpp v28, v28, v28 quad_perm:[1,0,3,2] row_mask:0xf bank_mask:0xf bound_ctrl:1
	s_nop 1
	v_add_f32_dpp v28, v28, v28 quad_perm:[2,3,0,1] row_mask:0xf bank_mask:0xf bound_ctrl:1
	s_nop 1
	v_add_f32_dpp v28, v28, v28 row_half_mirror row_mask:0xf bank_mask:0xf bound_ctrl:1
	s_nop 1
	v_add_f32_dpp v28, v28, v28 row_ror:8 row_mask:0xf bank_mask:0xf bound_ctrl:1
	v_mov_b32_e32 v35, v28
	s_nop 1
	v_permlane16_swap_b32_e32 v28, v35
	v_add_f32_e32 v28, v28, v35
	v_mov_b32_e32 v35, v28
	s_nop 1
	v_permlane32_swap_b32_e32 v28, v35
	v_add_f32_e32 v28, v28, v35
	v_fmamk_f32 v28, v28, 0x3b000000, v115
	v_mul_f32_e32 v35, 0x4f800000, v28
	v_cmp_gt_f32_e32 vcc, s29, v28
	s_nop 1
	v_cndmask_b32_e32 v35, v28, v35, vcc
	v_sqrt_f32_e32 v39, v35
	v_and_or_b32 v28, v38, s27, v34
	v_add_u32_e32 v34, -1, v39
	v_fma_f32 v36, -v34, v39, v35
	v_cmp_ge_f32_e64 s[4:5], 0, v36
	v_add_u32_e32 v36, 1, v39
	v_fma_f32 v37, -v36, v39, v35
	v_cndmask_b32_e64 v34, v39, v34, s[4:5]
	v_cmp_lt_f32_e64 s[4:5], 0, v37
	s_nop 1
	v_cndmask_b32_e64 v34, v34, v36, s[4:5]
	v_mul_f32_e32 v36, 0x37800000, v34
	v_cndmask_b32_e32 v34, v34, v36, vcc
	v_cmp_class_f32_e32 vcc, v35, v186
	s_nop 1
	v_cndmask_b32_e32 v36, v34, v35, vcc
	v_div_scale_f32 v37, s[4:5], v36, v36, 1.0
	v_rcp_f32_e32 v38, v37
	v_add_co_u32_e32 v34, vcc, s35, v6
	v_fma_f32 v39, -v37, v38, 1.0
	s_nop 0
	v_addc_co_u32_e32 v35, vcc, 0, v7, vcc
	v_fmac_f32_e32 v38, v39, v38
	v_div_scale_f32 v39, vcc, 1.0, v36, 1.0
	v_mul_f32_e32 v40, v39, v38
	v_fma_f32 v41, -v37, v40, v39
	v_fmac_f32_e32 v40, v41, v38
	v_fma_f32 v37, -v37, v40, v39
	v_div_fmas_f32 v37, v37, v38, v40
	v_div_fixup_f32 v36, v37, v36, 1.0
	v_mul_f32_e32 v4, v4, v36
	v_mul_f32_e32 v5, v5, v36
	global_store_dwordx4 v[34:35], v[28:31], off offset:1024
	v_fma_f32 v4, v22, v4, v24
	v_fma_f32 v5, v23, v5, v25
	s_nop 0
	v_mul_f32_e32 v37, 0xbfb8aa3b, v4
	v_exp_f32_e32 v37, v37
	v_mul_f32_e32 v30, 0xbfb8aa3b, v5
	v_exp_f32_e32 v31, v30
	v_mul_f32_e32 v32, v32, v36
	v_mul_f32_e32 v33, v33, v36
	s_nop 0
	v_fma_f32 v32, v16, v32, v20
	v_fma_f32 v33, v17, v33, v21
	v_add_f32_e32 v28, 1.0, v37
	v_mul_f32_e32 v30, 0xbfb8aa3b, v33
	v_mul_f32_e32 v38, 0xbfb8aa3b, v32
	v_exp_f32_e32 v37, v30
	v_exp_f32_e32 v38, v38
	v_rcp_f32_e32 v28, v28
	v_mul_f32_e32 v0, v0, v36
	v_mul_f32_e32 v1, v1, v36
	v_add_f32_e32 v29, 1.0, v38
	v_fma_f32 v0, v14, v0, v18
	v_fma_f32 v1, v15, v1, v19
	v_rcp_f32_e32 v30, v29
	v_add_f32_e32 v29, 1.0, v31
	v_add_f32_e32 v31, 1.0, v37
	v_mul_f32_e32 v37, 0xbfb8aa3b, v0
	v_exp_f32_e32 v37, v37
	v_rcp_f32_e32 v29, v29
	v_rcp_f32_e32 v31, v31
	v_mul_f32_e32 v10, v10, v36
	v_mul_f32_e32 v11, v11, v36
	s_nop 0
	v_fma_f32 v10, v8, v10, v12
	v_fma_f32 v11, v9, v11, v13
	v_mul_f32_e32 v4, v4, v28
	v_mul_f32_e32 v5, v5, v29
	v_mul_f32_e32 v36, 0xbfb8aa3b, v10
	v_exp_f32_e32 v38, v36
	v_add_f32_e32 v36, 1.0, v37
	v_rcp_f32_e32 v36, v36
	v_mul_f32_e32 v28, v32, v30
	v_mul_f32_e32 v29, v33, v31
	v_add_f32_e32 v37, 1.0, v38
	v_mul_f32_e32 v38, 0xbfb8aa3b, v1
	v_exp_f32_e32 v39, v38
	v_mul_f32_e32 v38, 0xbfb8aa3b, v11
	v_exp_f32_e32 v40, v38
	v_rcp_f32_e32 v38, v37
	v_add_f32_e32 v37, 1.0, v39
	v_rcp_f32_e32 v37, v37
	v_add_f32_e32 v39, 1.0, v40
	v_rcp_f32_e32 v39, v39
	v_bfe_u32 v32, v29, 16, 1
	v_mul_f32_e32 v0, v0, v36
	v_mul_f32_e32 v1, v1, v37
	v_add3_u32 v29, v29, v32, s30
	v_mul_f32_e32 v10, v10, v38
	v_mul_f32_e32 v11, v11, v39
	v_bfe_u32 v32, v1, 16, 1
	v_bfe_u32 v30, v11, 16, 1
	v_bfe_u32 v31, v10, 16, 1
	v_add3_u32 v36, v10, v31, s30
	v_add3_u32 v30, v11, v30, s30
	v_bfe_u32 v11, v5, 16, 1
	v_bfe_u32 v31, v0, 16, 1
	v_add3_u32 v31, v0, v31, s30
	v_add3_u32 v0, v5, v11, s30
	v_lshrrev_b32_e32 v39, 16, v0
	v_bfe_u32 v10, v4, 16, 1
	v_add_f32_dpp v0, v27, v27 quad_perm:[1,0,3,2] row_mask:0xf bank_mask:0xf bound_ctrl:1
	v_add3_u32 v37, v1, v32, s30
	v_add3_u32 v1, v4, v10, s30
	v_add_f32_dpp v0, v0, v0 quad_perm:[2,3,0,1] row_mask:0xf bank_mask:0xf bound_ctrl:1
	v_lshrrev_b32_e32 v38, 16, v1
	v_bfe_u32 v33, v28, 16, 1
	v_add_f32_dpp v0, v0, v0 row_half_mirror row_mask:0xf bank_mask:0xf bound_ctrl:1
	v_add3_u32 v28, v28, v33, s30
	v_lshrrev_b32_e32 v41, 16, v31
	v_add_f32_dpp v0, v0, v0 row_ror:8 row_mask:0xf bank_mask:0xf bound_ctrl:1
	v_mov_b32_e32 v1, v0
	s_nop 1
	v_permlane16_swap_b32_e32 v0, v1
	v_add_f32_e32 v0, v0, v1
	v_mov_b32_e32 v1, v0
	s_nop 1
	v_permlane32_swap_b32_e32 v0, v1
	v_add_f32_e32 v0, v0, v1
	v_mul_f32_e32 v0, 0x3b000000, v0
	v_add_f32_e64 v4, v138, -v0
	v_add_f32_e64 v5, v139, -v0
	v_add_f32_e64 v10, v136, -v0
	v_add_f32_e64 v11, v137, -v0
	v_fma_f32 v27, v4, v4, 0
	v_fmac_f32_e32 v27, v10, v10
	v_fmac_f32_e32 v27, v5, v5
	v_fmac_f32_e32 v27, v11, v11
	v_add_f32_e64 v32, v134, -v0
	v_add_f32_e64 v33, v135, -v0
	v_add_f32_e64 v1, v133, -v0
	v_add_f32_e64 v0, v132, -v0
	v_fmac_f32_e32 v27, v32, v32
	v_fmac_f32_e32 v27, v0, v0
	v_fmac_f32_e32 v27, v33, v33
	v_fmac_f32_e32 v27, v1, v1
	v_lshrrev_b32_e32 v31, 16, v37
	v_and_or_b32 v31, v30, s27, v31
	v_add_f32_dpp v27, v27, v27 quad_perm:[1,0,3,2] row_mask:0xf bank_mask:0xf bound_ctrl:1
	v_and_or_b32 v28, v28, s27, v38
	v_and_or_b32 v29, v29, s27, v39
	v_add_f32_dpp v27, v27, v27 quad_perm:[2,3,0,1] row_mask:0xf bank_mask:0xf bound_ctrl:1
	s_nop 1
	v_add_f32_dpp v27, v27, v27 row_half_mirror row_mask:0xf bank_mask:0xf bound_ctrl:1
	s_nop 1
	v_add_f32_dpp v27, v27, v27 row_ror:8 row_mask:0xf bank_mask:0xf bound_ctrl:1
	v_mov_b32_e32 v40, v27
	s_nop 1
	v_permlane16_swap_b32_e32 v27, v40
	v_add_f32_e32 v27, v27, v40
	v_mov_b32_e32 v40, v27
	s_nop 1
	v_permlane32_swap_b32_e32 v27, v40
	v_add_f32_e32 v27, v27, v40
	v_fmamk_f32 v27, v27, 0x3b000000, v115
	v_mul_f32_e32 v40, 0x4f800000, v27
	v_cmp_gt_f32_e32 vcc, s29, v27
	s_nop 1
	v_cndmask_b32_e32 v27, v27, v40, vcc
	v_sqrt_f32_e32 v40, v27
	s_nop 0
	v_add_u32_e32 v30, -1, v40
	v_fma_f32 v37, -v30, v40, v27
	v_cmp_ge_f32_e64 s[4:5], 0, v37
	v_add_u32_e32 v37, 1, v40
	s_nop 0
	v_cndmask_b32_e64 v30, v40, v30, s[4:5]
	v_fma_f32 v40, -v37, v40, v27
	v_cmp_lt_f32_e64 s[4:5], 0, v40
	s_nop 1
	v_cndmask_b32_e64 v30, v30, v37, s[4:5]
	v_mul_f32_e32 v37, 0x37800000, v30
	v_cndmask_b32_e32 v30, v30, v37, vcc
	v_cmp_class_f32_e32 vcc, v27, v186
	s_nop 1
	v_cndmask_b32_e32 v27, v30, v27, vcc
	v_div_scale_f32 v37, s[4:5], v27, v27, 1.0
	v_rcp_f32_e32 v40, v37
	v_and_or_b32 v30, v36, s27, v41
	global_store_dwordx4 v[34:35], v[28:31], off offset:3072
	v_fma_f32 v36, -v37, v40, 1.0
	v_fmac_f32_e32 v40, v36, v40
	v_div_scale_f32 v36, vcc, 1.0, v27, 1.0
	v_mul_f32_e32 v38, v36, v40
	v_fma_f32 v39, -v37, v38, v36
	v_fmac_f32_e32 v38, v39, v40
	v_fma_f32 v36, -v37, v38, v36
	v_div_fmas_f32 v36, v36, v40, v38
	v_div_fixup_f32 v36, v36, v27, 1.0
	v_mul_f32_e32 v4, v4, v36
	v_mul_f32_e32 v5, v5, v36
	v_mul_f32_e32 v10, v10, v36
	v_mul_f32_e32 v11, v11, v36
	v_fma_f32 v4, v22, v4, v24
	v_fma_f32 v5, v23, v5, v25
	v_fma_f32 v10, v16, v10, v20
	v_fma_f32 v11, v17, v11, v21
	v_mul_f32_e32 v27, 0xbfb8aa3b, v4
	v_exp_f32_e32 v27, v27
	v_mul_f32_e32 v37, 0xbfb8aa3b, v10
	v_exp_f32_e32 v37, v37
	v_mul_f32_e32 v29, 0xbfb8aa3b, v5
	v_exp_f32_e32 v29, v29
	v_mul_f32_e32 v30, 0xbfb8aa3b, v11
	v_exp_f32_e32 v31, v30
	v_add_f32_e32 v27, 1.0, v27
	v_rcp_f32_e32 v28, v27
	v_add_f32_e32 v27, 1.0, v37
	v_mul_f32_e32 v32, v32, v36
	v_mul_f32_e32 v33, v33, v36
	v_rcp_f32_e32 v30, v27
	v_add_f32_e32 v27, 1.0, v29
	v_fma_f32 v32, v14, v32, v18
	v_fma_f32 v33, v15, v33, v19
	v_mul_f32_e32 v0, v0, v36
	v_mul_f32_e32 v1, v1, v36
	v_rcp_f32_e32 v29, v27
	v_add_f32_e32 v27, 1.0, v31
	v_mul_f32_e32 v31, 0xbfb8aa3b, v32
	v_fma_f32 v0, v8, v0, v12
	v_fma_f32 v1, v9, v1, v13
	v_exp_f32_e32 v34, v31
	v_mul_f32_e32 v31, 0xbfb8aa3b, v0
	v_exp_f32_e32 v35, v31
	v_rcp_f32_e32 v31, v27
	v_add_f32_e32 v27, 1.0, v34
	v_rcp_f32_e32 v34, v27
	v_add_f32_e32 v27, 1.0, v35
	v_mul_f32_e32 v35, 0xbfb8aa3b, v33
	v_exp_f32_e32 v35, v35
	v_mul_f32_e32 v36, 0xbfb8aa3b, v1
	v_exp_f32_e32 v37, v36
	v_rcp_f32_e32 v36, v27
	v_add_f32_e32 v27, 1.0, v35
	v_rcp_f32_e32 v35, v27
	v_add_f32_e32 v27, 1.0, v37
	v_rcp_f32_e32 v37, v27
	v_mul_f32_e32 v4, v4, v28
	v_mul_f32_e32 v5, v5, v29
	v_mul_f32_e32 v10, v10, v30
	v_mul_f32_e32 v11, v11, v31
	v_mul_f32_e32 v28, v32, v34
	v_mul_f32_e32 v29, v33, v35
	v_mul_f32_e32 v0, v0, v36
	v_mul_f32_e32 v1, v1, v37
	v_bfe_u32 v32, v10, 16, 1
	v_bfe_u32 v27, v1, 16, 1
	v_bfe_u32 v30, v0, 16, 1
	v_add3_u32 v30, v0, v30, s30
	v_add3_u32 v0, v1, v27, s30
	v_bfe_u32 v1, v4, 16, 1
	v_bfe_u32 v27, v29, 16, 1
	v_add3_u32 v32, v10, v32, s30
	v_bfe_u32 v10, v5, 16, 1
	v_add3_u32 v27, v29, v27, s30
	v_add3_u32 v1, v4, v1, s30
	v_add3_u32 v5, v5, v10, s30
	v_lshrrev_b32_e32 v33, 16, v1
	v_lshrrev_b32_e32 v1, 16, v27
	v_lshrrev_b32_e32 v34, 16, v5
	v_and_or_b32 v5, v0, s27, v1
	v_add_f32_dpp v0, v26, v26 quad_perm:[1,0,3,2] row_mask:0xf bank_mask:0xf bound_ctrl:1
	v_bfe_u32 v31, v11, 16, 1
	v_add3_u32 v31, v11, v31, s30
	v_add_f32_dpp v0, v0, v0 quad_perm:[2,3,0,1] row_mask:0xf bank_mask:0xf bound_ctrl:1
	v_bfe_u32 v11, v28, 16, 1
	v_add3_u32 v11, v28, v11, s30
	v_add_f32_dpp v0, v0, v0 row_half_mirror row_mask:0xf bank_mask:0xf bound_ctrl:1
	v_lshrrev_b32_e32 v4, 16, v11
	v_and_or_b32 v4, v30, s27, v4
	v_add_f32_dpp v0, v0, v0 row_ror:8 row_mask:0xf bank_mask:0xf bound_ctrl:1
	v_mov_b32_e32 v1, v0
	s_nop 1
	v_permlane16_swap_b32_e32 v0, v1
	v_add_f32_e32 v0, v0, v1
	v_mov_b32_e32 v1, v0
	s_nop 1
	v_permlane32_swap_b32_e32 v0, v1
	v_add_f32_e32 v0, v0, v1
	v_mul_f32_e32 v0, 0x3b000000, v0
	v_add_f32_e64 v10, v130, -v0
	v_add_f32_e64 v11, v131, -v0
	v_add_f32_e64 v26, v128, -v0
	v_add_f32_e64 v27, v129, -v0
	v_fma_f32 v35, v10, v10, 0
	v_fmac_f32_e32 v35, v26, v26
	v_fmac_f32_e32 v35, v11, v11
	v_fmac_f32_e32 v35, v27, v27
	v_add_f32_e64 v28, v126, -v0
	v_add_f32_e64 v29, v127, -v0
	v_add_f32_e64 v1, v3, -v0
	v_add_f32_e64 v0, v2, -v0
	v_fmac_f32_e32 v35, v28, v28
	v_fmac_f32_e32 v35, v0, v0
	v_fmac_f32_e32 v35, v29, v29
	v_fmac_f32_e32 v35, v1, v1
	s_nop 1
	v_add_f32_dpp v2, v35, v35 quad_perm:[1,0,3,2] row_mask:0xf bank_mask:0xf bound_ctrl:1
	s_nop 1
	v_add_f32_dpp v2, v2, v2 quad_perm:[2,3,0,1] row_mask:0xf bank_mask:0xf bound_ctrl:1
	s_nop 1
	v_add_f32_dpp v2, v2, v2 row_half_mirror row_mask:0xf bank_mask:0xf bound_ctrl:1
	s_nop 1
	v_add_f32_dpp v2, v2, v2 row_ror:8 row_mask:0xf bank_mask:0xf bound_ctrl:1
	v_mov_b32_e32 v3, v2
	s_nop 1
	v_permlane16_swap_b32_e32 v2, v3
	v_add_f32_e32 v2, v2, v3
	v_mov_b32_e32 v3, v2
	s_nop 1
	v_permlane32_swap_b32_e32 v2, v3
	v_add_f32_e32 v2, v2, v3
	v_fmamk_f32 v2, v2, 0x3b000000, v115
	v_mul_f32_e32 v3, 0x4f800000, v2
	v_cmp_gt_f32_e32 vcc, s29, v2
	s_nop 1
	v_cndmask_b32_e32 v35, v2, v3, vcc
	v_sqrt_f32_e32 v36, v35
	v_and_or_b32 v3, v31, s27, v34
	v_and_or_b32 v2, v32, s27, v33
	v_add_u32_e32 v30, -1, v36
	v_fma_f32 v31, -v30, v36, v35
	v_cmp_ge_f32_e64 s[4:5], 0, v31
	v_add_u32_e32 v31, 1, v36
	v_fma_f32 v32, -v31, v36, v35
	v_cndmask_b32_e64 v30, v36, v30, s[4:5]
	v_cmp_lt_f32_e64 s[4:5], 0, v32
	s_nop 1
	v_cndmask_b32_e64 v30, v30, v31, s[4:5]
	v_mul_f32_e32 v31, 0x37800000, v30
	v_cndmask_b32_e32 v30, v30, v31, vcc
	v_cmp_class_f32_e32 vcc, v35, v186
	s_nop 1
	v_cndmask_b32_e32 v30, v30, v35, vcc
	v_div_scale_f32 v31, s[4:5], v30, v30, 1.0
	v_rcp_f32_e32 v32, v31
	v_add_co_u32_e32 v6, vcc, s28, v6
	v_fma_f32 v33, -v31, v32, 1.0
	s_nop 0
	v_addc_co_u32_e32 v7, vcc, 0, v7, vcc
	v_fmac_f32_e32 v32, v33, v32
	v_div_scale_f32 v33, vcc, 1.0, v30, 1.0
	v_mul_f32_e32 v34, v33, v32
	v_fma_f32 v35, -v31, v34, v33
	v_fmac_f32_e32 v34, v35, v32
	v_fma_f32 v31, -v31, v34, v33
	v_div_fmas_f32 v31, v31, v32, v34
	v_div_fixup_f32 v30, v31, v30, 1.0
	v_mul_f32_e32 v10, v10, v30
	v_mul_f32_e32 v11, v11, v30
	global_store_dwordx4 v[6:7], v[2:5], off offset:1024
	v_fma_f32 v10, v22, v10, v24
	v_fma_f32 v11, v23, v11, v25
	v_mul_f32_e32 v0, v0, v30
	v_mul_f32_e32 v1, v1, v30
	v_mul_f32_e32 v22, 0xbfb8aa3b, v10
	v_exp_f32_e32 v24, v22
	v_mul_f32_e32 v22, v26, v30
	v_mul_f32_e32 v23, v27, v30
	v_mul_f32_e32 v4, 0xbfb8aa3b, v11
	v_fma_f32 v16, v16, v22, v20
	v_fma_f32 v17, v17, v23, v21
	v_exp_f32_e32 v5, v4
	v_mul_f32_e32 v20, 0xbfb8aa3b, v16
	v_exp_f32_e32 v20, v20
	v_mul_f32_e32 v4, 0xbfb8aa3b, v17
	v_fma_f32 v0, v8, v0, v12
	v_fma_f32 v1, v9, v1, v13
	v_add_f32_e32 v2, 1.0, v24
	v_add_f32_e32 v3, 1.0, v20
	v_exp_f32_e32 v20, v4
	v_rcp_f32_e32 v4, v3
	v_add_f32_e32 v3, 1.0, v5
	v_mul_f32_e32 v8, 0xbfb8aa3b, v0
	v_add_f32_e32 v5, 1.0, v20
	v_mul_f32_e32 v20, v28, v30
	v_mul_f32_e32 v21, v29, v30
	v_exp_f32_e32 v9, v8
	v_fma_f32 v14, v14, v20, v18
	v_fma_f32 v15, v15, v21, v19
	v_rcp_f32_e32 v5, v5
	v_mul_f32_e32 v18, 0xbfb8aa3b, v14
	v_exp_f32_e32 v18, v18
	v_mul_f32_e32 v12, 0xbfb8aa3b, v15
	v_exp_f32_e32 v13, v12
	v_mul_f32_e32 v12, 0xbfb8aa3b, v1
	v_add_f32_e32 v8, 1.0, v18
	v_exp_f32_e32 v18, v12
	v_add_f32_e32 v9, 1.0, v9
	v_rcp_f32_e32 v12, v9
	v_add_f32_e32 v9, 1.0, v13
	v_add_f32_e32 v13, 1.0, v18
	v_rcp_f32_e32 v13, v13
	v_rcp_f32_e32 v2, v2
	v_rcp_f32_e32 v3, v3
	v_rcp_f32_e32 v8, v8
	v_rcp_f32_e32 v9, v9
	v_mul_f32_e32 v4, v16, v4
	v_mul_f32_e32 v5, v17, v5
	v_mul_f32_e32 v0, v0, v12
	v_mul_f32_e32 v1, v1, v13
	v_mul_f32_e32 v2, v10, v2
	v_mul_f32_e32 v3, v11, v3
	v_mul_f32_e32 v8, v14, v8
	v_mul_f32_e32 v9, v15, v9
	v_bfe_u32 v10, v1, 16, 1
	v_bfe_u32 v11, v0, 16, 1
	v_bfe_u32 v12, v5, 16, 1
	v_bfe_u32 v13, v4, 16, 1
	v_add3_u32 v4, v4, v13, s30
	v_add3_u32 v5, v5, v12, s30
	v_add3_u32 v0, v0, v11, s30
	v_add3_u32 v1, v1, v10, s30
	v_bfe_u32 v10, v2, 16, 1
	v_bfe_u32 v11, v3, 16, 1
	v_bfe_u32 v12, v8, 16, 1
	v_bfe_u32 v13, v9, 16, 1
	v_add3_u32 v9, v9, v13, s30
	v_add3_u32 v8, v8, v12, s30
	v_add3_u32 v3, v3, v11, s30
	v_add3_u32 v2, v2, v10, s30
	v_lshrrev_b32_e32 v10, 16, v2
	v_lshrrev_b32_e32 v11, 16, v3
	v_lshrrev_b32_e32 v2, 16, v8
	v_lshrrev_b32_e32 v3, 16, v9
	v_and_or_b32 v3, v1, s27, v3
	v_and_or_b32 v2, v0, s27, v2
	v_and_or_b32 v1, v5, s27, v11
	v_and_or_b32 v0, v4, s27, v10
	global_store_dwordx4 v[6:7], v[0:3], off offset:3072
	s_cbranch_scc0 .LBB0_505

.LBB0_515:
	global_load_dwordx4 v[8:11], v[94:95], off
	global_load_dwordx4 v[12:15], v[96:97], off
	global_load_dwordx4 v[0:3], v[94:95], off offset:16
	global_load_dwordx4 v[4:7], v[96:97], off offset:16
	v_add_f32_e32 v18, 0, v66
	v_add_f32_e32 v18, v68, v18
	v_add_f32_e32 v18, v67, v18
	v_add_f32_e32 v18, v69, v18
	v_add_f32_e32 v18, v62, v18
	v_add_f32_e32 v18, v64, v18
	v_add_f32_e32 v18, v63, v18
	v_add_f32_e32 v18, v65, v18
	s_nop 1
	v_add_f32_dpp v18, v18, v18 quad_perm:[1,0,3,2] row_mask:0xf bank_mask:0xf bound_ctrl:1
	s_nop 1
	v_add_f32_dpp v18, v18, v18 quad_perm:[2,3,0,1] row_mask:0xf bank_mask:0xf bound_ctrl:1
	s_nop 1
	v_add_f32_dpp v18, v18, v18 row_half_mirror row_mask:0xf bank_mask:0xf bound_ctrl:1
	s_nop 1
	v_add_f32_dpp v18, v18, v18 row_ror:8 row_mask:0xf bank_mask:0xf bound_ctrl:1
	v_mov_b32_e32 v19, v18
	s_nop 1
	v_permlane16_swap_b32_e32 v18, v19
	v_add_f32_e32 v18, v18, v19
	v_mov_b32_e32 v19, v18
	s_nop 1
	v_permlane32_swap_b32_e32 v18, v19
	v_add_f32_e32 v18, v18, v19
	v_mul_f32_e32 v18, 0x3b000000, v18
	v_add_f32_e64 v24, v66, -v18
	v_add_f32_e64 v25, v67, -v18
	v_add_f32_e64 v26, v68, -v18
	v_add_f32_e64 v27, v69, -v18
	v_add_f32_e64 v28, v62, -v18
	v_add_f32_e64 v29, v63, -v18
	v_add_f32_e64 v30, v64, -v18
	v_add_f32_e64 v31, v65, -v18
	v_fma_f32 v18, v24, v24, 0
	v_fmac_f32_e32 v18, v26, v26
	v_fmac_f32_e32 v18, v25, v25
	v_fmac_f32_e32 v18, v27, v27
	v_fmac_f32_e32 v18, v28, v28
	v_fmac_f32_e32 v18, v30, v30
	v_fmac_f32_e32 v18, v29, v29
	v_fmac_f32_e32 v18, v31, v31
	s_nop 1
	v_add_f32_dpp v18, v18, v18 quad_perm:[1,0,3,2] row_mask:0xf bank_mask:0xf bound_ctrl:1
	s_nop 1
	v_add_f32_dpp v18, v18, v18 quad_perm:[2,3,0,1] row_mask:0xf bank_mask:0xf bound_ctrl:1
	s_nop 1
	v_add_f32_dpp v18, v18, v18 row_half_mirror row_mask:0xf bank_mask:0xf bound_ctrl:1
	s_nop 1
	v_add_f32_dpp v18, v18, v18 row_ror:8 row_mask:0xf bank_mask:0xf bound_ctrl:1
	v_mov_b32_e32 v19, v18
	s_nop 1
	v_permlane16_swap_b32_e32 v18, v19
	v_add_f32_e32 v18, v18, v19
	v_mov_b32_e32 v19, v18
	s_nop 1
	v_permlane32_swap_b32_e32 v18, v19
	v_add_f32_e32 v18, v18, v19
	v_fmamk_f32 v18, v18, 0x3b000000, v135
	v_mul_f32_e32 v19, 0x4f800000, v18
	v_cmp_gt_f32_e32 vcc, s26, v18
	s_nop 1
	v_cndmask_b32_e32 v18, v18, v19, vcc
	v_sqrt_f32_e32 v19, v18
	s_nop 0
	v_add_u32_e32 v22, -1, v19
	v_add_u32_e32 v23, 1, v19
	v_fma_f32 v32, -v22, v19, v18
	v_fma_f32 v33, -v23, v19, v18
	v_cmp_ge_f32_e64 s[4:5], 0, v32
	s_nop 1
	v_cndmask_b32_e64 v19, v19, v22, s[4:5]
	v_cmp_lt_f32_e64 s[4:5], 0, v33
	s_nop 1
	v_cndmask_b32_e64 v19, v19, v23, s[4:5]
	v_mul_f32_e32 v22, 0x37800000, v19
	v_cndmask_b32_e32 v19, v19, v22, vcc
	v_cmp_class_f32_e32 vcc, v18, v136
	s_waitcnt vmcnt(2)
	v_mov_b32_e32 v22, v12
	v_mov_b32_e32 v23, v14
	v_cndmask_b32_e32 v32, v19, v18, vcc
	v_div_scale_f32 v33, s[4:5], v32, v32, 1.0
	v_rcp_f32_e32 v34, v33
	v_div_scale_f32 v35, vcc, 1.0, v32, 1.0
	v_mov_b32_e32 v19, v10
	v_fma_f32 v18, -v33, v34, 1.0
	v_fmac_f32_e32 v34, v18, v34
	v_mul_f32_e32 v36, v35, v34
	v_fma_f32 v37, -v33, v36, v35
	v_fmac_f32_e32 v36, v37, v34
	v_mov_b32_e32 v18, v8
	v_fma_f32 v8, -v33, v36, v35
	v_div_fmas_f32 v8, v8, v34, v36
	v_div_fixup_f32 v32, v8, v32, 1.0
	v_mov_b32_e32 v10, v9
	v_mul_f32_e32 v8, v24, v32
	v_mul_f32_e32 v9, v25, v32
	v_mov_b32_e32 v14, v13
	v_fma_f32 v24, v18, v8, v22
	v_fma_f32 v25, v19, v9, v23
	s_waitcnt vmcnt(0)
	v_mov_b32_e32 v13, v6
	v_mul_f32_e32 v8, 0xbfb8aa3b, v24
	v_exp_f32_e32 v12, v8
	v_mul_f32_e32 v8, v26, v32
	v_mul_f32_e32 v9, v27, v32
	v_mov_b32_e32 v6, v5
	v_fma_f32 v26, v10, v8, v14
	v_fma_f32 v27, v11, v9, v15
	v_add_f32_e32 v9, 1.0, v12
	v_mul_f32_e32 v8, 0xbfb8aa3b, v26
	v_exp_f32_e32 v8, v8
	v_rcp_f32_e32 v34, v9
	v_mul_f32_e32 v9, 0xbfb8aa3b, v25
	v_mul_f32_e32 v12, 0xbfb8aa3b, v27
	v_exp_f32_e32 v9, v9
	v_exp_f32_e32 v12, v12
	v_add_f32_e32 v8, 1.0, v8
	v_rcp_f32_e32 v36, v8
	v_add_f32_e32 v8, 1.0, v9
	v_add_f32_e32 v33, 1.0, v12
	v_rcp_f32_e32 v35, v8
	v_mul_f32_e32 v28, v28, v32
	v_mul_f32_e32 v29, v29, v32
	v_mov_b32_e32 v8, v0
	v_mov_b32_e32 v9, v2
	v_mov_b32_e32 v12, v4
	v_fma_f32 v28, v8, v28, v12
	v_fma_f32 v29, v9, v29, v13
	v_mul_f32_e32 v30, v30, v32
	v_mul_f32_e32 v31, v31, v32
	v_mul_f32_e32 v0, 0xbfb8aa3b, v28
	v_mov_b32_e32 v2, v1
	v_exp_f32_e32 v4, v0
	v_fma_f32 v0, v2, v30, v6
	v_fma_f32 v1, v3, v31, v7
	v_mul_f32_e32 v30, 0xbfb8aa3b, v29
	v_mul_f32_e32 v5, 0xbfb8aa3b, v0
	v_exp_f32_e32 v5, v5
	v_exp_f32_e32 v31, v30
	v_mul_f32_e32 v30, 0xbfb8aa3b, v1
	v_exp_f32_e32 v32, v30
	v_add_f32_e32 v5, 1.0, v5
	v_rcp_f32_e32 v30, v5
	v_add_f32_e32 v5, 1.0, v31
	v_add_f32_e32 v31, 1.0, v32
	v_rcp_f32_e32 v37, v33
	v_add_f32_e32 v4, 1.0, v4
	v_rcp_f32_e32 v31, v31
	v_rcp_f32_e32 v4, v4
	v_rcp_f32_e32 v5, v5
	v_mul_f32_e32 v26, v26, v36
	v_mul_f32_e32 v27, v27, v37
	v_mul_f32_e32 v0, v0, v30
	v_mul_f32_e32 v1, v1, v31
	v_mul_f32_e32 v24, v24, v34
	v_mul_f32_e32 v25, v25, v35
	v_mul_f32_e32 v4, v28, v4
	v_mul_f32_e32 v5, v29, v5
	v_bfe_u32 v29, v0, 16, 1
	v_bfe_u32 v31, v26, 16, 1
	v_add3_u32 v32, v26, v31, s27
	v_add3_u32 v26, v0, v29, s27
	v_bfe_u32 v0, v24, 16, 1
	v_add3_u32 v0, v24, v0, s27
	v_lshrrev_b32_e32 v24, 16, v0
	v_add_f32_e32 v0, 0, v60
	v_add_f32_e32 v0, v58, v0
	v_add_f32_e32 v0, v61, v0
	v_add_f32_e32 v0, v59, v0
	v_add_f32_e32 v0, v54, v0
	v_add_f32_e32 v0, v56, v0
	v_add_f32_e32 v0, v55, v0
	v_add_f32_e32 v0, v57, v0
	v_bfe_u32 v28, v1, 16, 1
	v_bfe_u32 v30, v27, 16, 1
	v_add_f32_dpp v0, v0, v0 quad_perm:[1,0,3,2] row_mask:0xf bank_mask:0xf bound_ctrl:1
	v_add3_u32 v33, v27, v30, s27
	v_add3_u32 v27, v1, v28, s27
	v_add_f32_dpp v0, v0, v0 quad_perm:[2,3,0,1] row_mask:0xf bank_mask:0xf bound_ctrl:1
	v_bfe_u32 v1, v25, 16, 1
	v_add3_u32 v1, v25, v1, s27
	v_add_f32_dpp v0, v0, v0 row_half_mirror row_mask:0xf bank_mask:0xf bound_ctrl:1
	v_lshrrev_b32_e32 v25, 16, v1
	v_bfe_u32 v28, v4, 16, 1
	v_add_f32_dpp v0, v0, v0 row_ror:8 row_mask:0xf bank_mask:0xf bound_ctrl:1
	v_mov_b32_e32 v1, v0
	s_nop 1
	v_permlane16_swap_b32_e32 v0, v1
	v_add_f32_e32 v0, v0, v1
	v_mov_b32_e32 v1, v0
	s_nop 1
	v_permlane32_swap_b32_e32 v0, v1
	v_bfe_u32 v29, v5, 16, 1
	v_add_f32_e32 v0, v0, v1
	v_add3_u32 v5, v5, v29, s27
	v_add3_u32 v4, v4, v28, s27
	v_mul_f32_e32 v0, 0x3b000000, v0
	v_lshrrev_b32_e32 v34, 16, v4
	v_lshrrev_b32_e32 v35, 16, v5
	v_add_f32_e64 v4, v60, -v0
	v_add_f32_e64 v5, v61, -v0
	v_add_f32_e64 v28, v58, -v0
	v_add_f32_e64 v29, v59, -v0
	v_fma_f32 v36, v4, v4, 0
	v_fmac_f32_e32 v36, v28, v28
	v_fmac_f32_e32 v36, v5, v5
	v_fmac_f32_e32 v36, v29, v29
	v_add_f32_e64 v30, v54, -v0
	v_add_f32_e64 v31, v55, -v0
	v_add_f32_e64 v1, v57, -v0
	v_add_f32_e64 v0, v56, -v0
	v_fmac_f32_e32 v36, v30, v30
	v_fmac_f32_e32 v36, v0, v0
	v_fmac_f32_e32 v36, v31, v31
	v_fmac_f32_e32 v36, v1, v1
	v_and_or_b32 v25, v33, s25, v25
	v_and_or_b32 v26, v26, s25, v34
	v_add_f32_dpp v36, v36, v36 quad_perm:[1,0,3,2] row_mask:0xf bank_mask:0xf bound_ctrl:1
	v_and_or_b32 v27, v27, s25, v35
	v_and_or_b32 v24, v32, s25, v24
	v_add_f32_dpp v36, v36, v36 quad_perm:[2,3,0,1] row_mask:0xf bank_mask:0xf bound_ctrl:1
	s_nop 1
	v_add_f32_dpp v36, v36, v36 row_half_mirror row_mask:0xf bank_mask:0xf bound_ctrl:1
	s_nop 1
	v_add_f32_dpp v36, v36, v36 row_ror:8 row_mask:0xf bank_mask:0xf bound_ctrl:1
	v_mov_b32_e32 v37, v36
	s_nop 1
	v_permlane16_swap_b32_e32 v36, v37
	v_add_f32_e32 v36, v36, v37
	v_mov_b32_e32 v37, v36
	s_nop 1
	v_permlane32_swap_b32_e32 v36, v37
	v_add_f32_e32 v36, v36, v37
	v_fmamk_f32 v36, v36, 0x3b000000, v135
	v_mul_f32_e32 v37, 0x4f800000, v36
	v_cmp_gt_f32_e32 vcc, s26, v36
	s_nop 1
	v_cndmask_b32_e32 v36, v36, v37, vcc
	v_sqrt_f32_e32 v37, v36
	s_nop 0
	v_add_u32_e32 v33, -1, v37
	v_fma_f32 v34, -v33, v37, v36
	v_cmp_ge_f32_e64 s[4:5], 0, v34
	v_add_u32_e32 v34, 1, v37
	v_fma_f32 v35, -v34, v37, v36
	v_cndmask_b32_e64 v33, v37, v33, s[4:5]
	v_cmp_lt_f32_e64 s[4:5], 0, v35
	s_nop 1
	v_cndmask_b32_e64 v33, v33, v34, s[4:5]
	v_mul_f32_e32 v34, 0x37800000, v33
	v_cndmask_b32_e32 v33, v33, v34, vcc
	v_cmp_class_f32_e32 vcc, v36, v136
	s_nop 1
	v_cndmask_b32_e32 v34, v33, v36, vcc
	v_div_scale_f32 v35, s[4:5], v34, v34, 1.0
	v_rcp_f32_e32 v36, v35
	s_lshl_b64 s[4:5], s[44:45], 11
	v_lshl_add_u64 v[32:33], v[98:99], 0, s[4:5]
	global_store_dwordx4 v[32:33], v[24:27], off offset:1024
	v_fma_f32 v37, -v35, v36, 1.0
	v_fmac_f32_e32 v36, v37, v36
	v_div_scale_f32 v37, vcc, 1.0, v34, 1.0
	v_mul_f32_e32 v38, v37, v36
	v_fma_f32 v39, -v35, v38, v37
	v_fmac_f32_e32 v38, v39, v36
	v_fma_f32 v35, -v35, v38, v37
	v_div_fmas_f32 v35, v35, v36, v38
	v_div_fixup_f32 v34, v35, v34, 1.0
	v_mul_f32_e32 v4, v4, v34
	v_mul_f32_e32 v5, v5, v34
	s_lshl_b64 s[4:5], s[12:13], 13
	v_fma_f32 v4, v18, v4, v22
	v_fma_f32 v5, v19, v5, v23
	s_add_u32 s4, s18, s4
	v_mul_f32_e32 v35, 0xbfb8aa3b, v4
	v_exp_f32_e32 v35, v35
	v_mul_f32_e32 v26, 0xbfb8aa3b, v5
	v_exp_f32_e32 v27, v26
	s_addc_u32 s5, s19, s5
	v_mul_f32_e32 v28, v28, v34
	v_mul_f32_e32 v29, v29, v34
	v_mul_f32_e32 v0, v0, v34
	v_mul_f32_e32 v1, v1, v34
	v_fma_f32 v28, v10, v28, v14
	v_fma_f32 v29, v11, v29, v15
	v_mul_f32_e32 v30, v30, v34
	v_mul_f32_e32 v31, v31, v34
	v_mul_f32_e32 v36, 0xbfb8aa3b, v28
	v_exp_f32_e32 v36, v36
	v_mul_f32_e32 v26, 0xbfb8aa3b, v29
	v_exp_f32_e32 v32, v26
	v_fma_f32 v0, v2, v0, v6
	v_fma_f32 v1, v3, v1, v7
	v_add_f32_e32 v25, 1.0, v36
	v_fma_f32 v30, v8, v30, v12
	v_fma_f32 v31, v9, v31, v13
	v_mul_f32_e32 v33, 0xbfb8aa3b, v0
	v_rcp_f32_e32 v26, v25
	v_add_f32_e32 v25, 1.0, v27
	v_add_f32_e32 v27, 1.0, v32
	v_mul_f32_e32 v32, 0xbfb8aa3b, v30
	v_exp_f32_e32 v33, v33
	v_mul_f32_e32 v34, 0xbfb8aa3b, v31
	v_add_f32_e32 v24, 1.0, v35
	v_exp_f32_e32 v32, v32
	v_exp_f32_e32 v35, v34
	v_mul_f32_e32 v34, 0xbfb8aa3b, v1
	v_exp_f32_e32 v36, v34
	v_add_f32_e32 v33, 1.0, v33
	v_rcp_f32_e32 v24, v24
	v_rcp_f32_e32 v25, v25
	v_rcp_f32_e32 v27, v27
	v_add_f32_e32 v32, 1.0, v32
	v_rcp_f32_e32 v34, v33
	v_add_f32_e32 v33, 1.0, v35
	v_rcp_f32_e32 v32, v32
	v_rcp_f32_e32 v33, v33
	v_add_f32_e32 v35, 1.0, v36
	v_rcp_f32_e32 v35, v35
	v_mul_f32_e32 v4, v4, v24
	v_mul_f32_e32 v5, v5, v25
	v_mul_f32_e32 v24, v28, v26
	v_mul_f32_e32 v25, v29, v27
	v_mul_f32_e32 v26, v30, v32
	v_mul_f32_e32 v27, v31, v33
	v_bfe_u32 v30, v25, 16, 1
	v_mul_f32_e32 v0, v0, v34
	v_mul_f32_e32 v1, v1, v35
	v_add3_u32 v25, v25, v30, s27
	v_bfe_u32 v30, v26, 16, 1
	v_bfe_u32 v29, v0, 16, 1
	v_add3_u32 v26, v26, v30, s27
	v_add3_u32 v0, v0, v29, s27
	v_lshrrev_b32_e32 v26, 16, v26
	v_and_or_b32 v26, v0, s25, v26
	v_add_f32_e32 v0, 0, v52
	v_add_f32_e32 v0, v50, v0
	v_add_f32_e32 v0, v53, v0
	v_add_f32_e32 v0, v51, v0
	v_add_f32_e32 v0, v46, v0
	v_add_f32_e32 v0, v48, v0
	v_add_f32_e32 v0, v47, v0
	v_add_f32_e32 v0, v49, v0
	v_bfe_u32 v31, v24, 16, 1
	v_add3_u32 v24, v24, v31, s27
	v_add_f32_dpp v0, v0, v0 quad_perm:[1,0,3,2] row_mask:0xf bank_mask:0xf bound_ctrl:1
	v_bfe_u32 v31, v27, 16, 1
	v_bfe_u32 v28, v1, 16, 1
	v_add_f32_dpp v0, v0, v0 quad_perm:[2,3,0,1] row_mask:0xf bank_mask:0xf bound_ctrl:1
	v_add3_u32 v27, v27, v31, s27
	v_add3_u32 v1, v1, v28, s27
	v_add_f32_dpp v0, v0, v0 row_half_mirror row_mask:0xf bank_mask:0xf bound_ctrl:1
	v_lshrrev_b32_e32 v27, 16, v27
	v_and_or_b32 v27, v1, s25, v27
	v_add_f32_dpp v0, v0, v0 row_ror:8 row_mask:0xf bank_mask:0xf bound_ctrl:1
	v_mov_b32_e32 v1, v0
	s_nop 1
	v_permlane16_swap_b32_e32 v0, v1
	v_add_f32_e32 v0, v0, v1
	v_mov_b32_e32 v1, v0
	v_bfe_u32 v28, v4, 16, 1
	v_bfe_u32 v29, v5, 16, 1
	v_permlane32_swap_b32_e32 v0, v1
	v_add3_u32 v5, v5, v29, s27
	v_add3_u32 v4, v4, v28, s27
	v_add_f32_e32 v0, v0, v1
	v_lshrrev_b32_e32 v4, 16, v4
	v_lshrrev_b32_e32 v5, 16, v5
	v_mul_f32_e32 v0, 0x3b000000, v0
	v_and_or_b32 v25, v25, s25, v5
	v_and_or_b32 v24, v24, s25, v4
	v_add_f32_e64 v4, v52, -v0
	v_add_f32_e64 v5, v53, -v0
	v_add_f32_e64 v28, v50, -v0
	v_add_f32_e64 v29, v51, -v0
	v_fma_f32 v32, v4, v4, 0
	v_fmac_f32_e32 v32, v28, v28
	v_fmac_f32_e32 v32, v5, v5
	v_fmac_f32_e32 v32, v29, v29
	v_add_f32_e64 v30, v46, -v0
	v_add_f32_e64 v31, v47, -v0
	v_add_f32_e64 v1, v49, -v0
	v_add_f32_e64 v0, v48, -v0
	v_fmac_f32_e32 v32, v30, v30
	v_fmac_f32_e32 v32, v0, v0
	v_fmac_f32_e32 v32, v31, v31
	v_fmac_f32_e32 v32, v1, v1
	s_add_i32 s12, s12, s14
	s_add_u32 s6, s6, s24
	v_add_f32_dpp v32, v32, v32 quad_perm:[1,0,3,2] row_mask:0xf bank_mask:0xf bound_ctrl:1
	s_addc_u32 s7, s7, s15
	s_add_u32 s8, s8, s24
	v_add_f32_dpp v32, v32, v32 quad_perm:[2,3,0,1] row_mask:0xf bank_mask:0xf bound_ctrl:1
	s_addc_u32 s9, s9, s15
	s_cmp_lt_i32 s12, 32
	v_add_f32_dpp v32, v32, v32 row_half_mirror row_mask:0xf bank_mask:0xf bound_ctrl:1
	s_nop 1
	v_add_f32_dpp v32, v32, v32 row_ror:8 row_mask:0xf bank_mask:0xf bound_ctrl:1
	v_mov_b32_e32 v33, v32
	s_nop 1
	v_permlane16_swap_b32_e32 v32, v33
	v_add_f32_e32 v32, v32, v33
	v_mov_b32_e32 v33, v32
	s_nop 1
	v_permlane32_swap_b32_e32 v32, v33
	v_add_f32_e32 v32, v32, v33
	v_fmamk_f32 v32, v32, 0x3b000000, v135
	v_mul_f32_e32 v33, 0x4f800000, v32
	v_cmp_gt_f32_e32 vcc, s26, v32
	s_nop 1
	v_cndmask_b32_e32 v34, v32, v33, vcc
	v_sqrt_f32_e32 v35, v34
	v_lshl_add_u64 v[32:33], s[4:5], 0, v[110:111]
	v_add_u32_e32 v36, -1, v35
	v_fma_f32 v37, -v36, v35, v34
	v_cmp_ge_f32_e64 s[4:5], 0, v37
	v_add_u32_e32 v37, 1, v35
	s_nop 0
	v_cndmask_b32_e64 v36, v35, v36, s[4:5]
	v_fma_f32 v35, -v37, v35, v34
	v_cmp_lt_f32_e64 s[4:5], 0, v35
	s_nop 1
	v_cndmask_b32_e64 v35, v36, v37, s[4:5]
	v_mul_f32_e32 v36, 0x37800000, v35
	v_cndmask_b32_e32 v35, v35, v36, vcc
	v_cmp_class_f32_e32 vcc, v34, v136
	s_nop 1
	v_cndmask_b32_e32 v36, v35, v34, vcc
	v_div_scale_f32 v37, s[4:5], v36, v36, 1.0
	v_rcp_f32_e32 v38, v37
	v_add_co_u32_e32 v34, vcc, s28, v32
	v_fma_f32 v39, -v37, v38, 1.0
	s_nop 0
	v_addc_co_u32_e32 v35, vcc, 0, v33, vcc
	v_fmac_f32_e32 v38, v39, v38
	v_div_scale_f32 v39, vcc, 1.0, v36, 1.0
	v_mul_f32_e32 v40, v39, v38
	v_fma_f32 v41, -v37, v40, v39
	v_fmac_f32_e32 v40, v41, v38
	v_fma_f32 v37, -v37, v40, v39
	v_div_fmas_f32 v37, v37, v38, v40
	v_div_fixup_f32 v36, v37, v36, 1.0
	v_mul_f32_e32 v4, v4, v36
	v_mul_f32_e32 v5, v5, v36
	global_store_dwordx4 v[34:35], v[24:27], off offset:3072
	v_fma_f32 v4, v18, v4, v22
	v_fma_f32 v5, v19, v5, v23
	s_nop 0
	v_mul_f32_e32 v37, 0xbfb8aa3b, v4
	v_exp_f32_e32 v37, v37
	v_mul_f32_e32 v26, 0xbfb8aa3b, v5
	v_exp_f32_e32 v27, v26
	v_mul_f32_e32 v28, v28, v36
	v_mul_f32_e32 v29, v29, v36
	s_nop 0
	v_fma_f32 v28, v10, v28, v14
	v_fma_f32 v29, v11, v29, v15
	v_mul_f32_e32 v30, v30, v36
	v_mul_f32_e32 v31, v31, v36
	v_mul_f32_e32 v38, 0xbfb8aa3b, v28
	v_exp_f32_e32 v38, v38
	v_mul_f32_e32 v26, 0xbfb8aa3b, v29
	v_exp_f32_e32 v34, v26
	v_mul_f32_e32 v0, v0, v36
	v_mul_f32_e32 v1, v1, v36
	v_fma_f32 v30, v8, v30, v12
	v_fma_f32 v31, v9, v31, v13
	v_fma_f32 v0, v2, v0, v6
	v_fma_f32 v1, v3, v1, v7
	v_mul_f32_e32 v36, 0xbfb8aa3b, v31
	v_mul_f32_e32 v35, 0xbfb8aa3b, v0
	v_add_f32_e32 v24, 1.0, v37
	v_add_f32_e32 v25, 1.0, v38
	v_exp_f32_e32 v35, v35
	v_exp_f32_e32 v37, v36
	v_mul_f32_e32 v36, 0xbfb8aa3b, v1
	v_rcp_f32_e32 v26, v25
	v_add_f32_e32 v25, 1.0, v27
	v_add_f32_e32 v27, 1.0, v34
	v_mul_f32_e32 v34, 0xbfb8aa3b, v30
	v_exp_f32_e32 v38, v36
	v_exp_f32_e32 v34, v34
	v_add_f32_e32 v35, 1.0, v35
	v_rcp_f32_e32 v36, v35
	v_add_f32_e32 v35, 1.0, v37
	v_add_f32_e32 v37, 1.0, v38
	v_rcp_f32_e32 v24, v24
	v_rcp_f32_e32 v25, v25
	v_rcp_f32_e32 v27, v27
	v_add_f32_e32 v34, 1.0, v34
	v_rcp_f32_e32 v37, v37
	v_rcp_f32_e32 v34, v34
	v_rcp_f32_e32 v35, v35
	v_mul_f32_e32 v4, v4, v24
	v_mul_f32_e32 v5, v5, v25
	v_mul_f32_e32 v24, v28, v26
	v_mul_f32_e32 v25, v29, v27
	v_mul_f32_e32 v0, v0, v36
	v_mul_f32_e32 v1, v1, v37
	v_mul_f32_e32 v26, v30, v34
	v_mul_f32_e32 v27, v31, v35
	v_bfe_u32 v28, v1, 16, 1
	v_bfe_u32 v29, v0, 16, 1
	v_bfe_u32 v30, v25, 16, 1
	v_bfe_u32 v31, v24, 16, 1
	v_add3_u32 v24, v24, v31, s27
	v_add3_u32 v25, v25, v30, s27
	v_add3_u32 v30, v0, v29, s27
	v_add3_u32 v0, v1, v28, s27
	v_bfe_u32 v1, v4, 16, 1
	v_bfe_u32 v31, v27, 16, 1
	v_add3_u32 v27, v27, v31, s27
	v_add3_u32 v1, v4, v1, s27
	v_lshrrev_b32_e32 v31, 16, v1
	v_lshrrev_b32_e32 v1, 16, v27
	v_and_or_b32 v27, v0, s25, v1
	v_add_f32_e32 v0, 0, v44
	v_add_f32_e32 v0, v42, v0
	v_add_f32_e32 v0, v45, v0
	v_add_f32_e32 v0, v43, v0
	v_add_f32_e32 v0, v16, v0
	v_add_f32_e32 v0, v20, v0
	v_add_f32_e32 v0, v17, v0
	v_add_f32_e32 v0, v21, v0
	v_bfe_u32 v28, v5, 16, 1
	v_add3_u32 v5, v5, v28, s27
	v_add_f32_dpp v0, v0, v0 quad_perm:[1,0,3,2] row_mask:0xf bank_mask:0xf bound_ctrl:1
	v_bfe_u32 v29, v26, 16, 1
	v_lshrrev_b32_e32 v34, 16, v5
	v_add_f32_dpp v0, v0, v0 quad_perm:[2,3,0,1] row_mask:0xf bank_mask:0xf bound_ctrl:1
	v_add3_u32 v26, v26, v29, s27
	v_lshrrev_b32_e32 v26, 16, v26
	v_add_f32_dpp v0, v0, v0 row_half_mirror row_mask:0xf bank_mask:0xf bound_ctrl:1
	v_and_or_b32 v26, v30, s25, v26
	v_and_or_b32 v24, v24, s25, v31
	v_add_f32_dpp v0, v0, v0 row_ror:8 row_mask:0xf bank_mask:0xf bound_ctrl:1
	v_mov_b32_e32 v1, v0
	s_nop 1
	v_permlane16_swap_b32_e32 v0, v1
	v_add_f32_e32 v0, v0, v1
	v_mov_b32_e32 v1, v0
	s_nop 1
	v_permlane32_swap_b32_e32 v0, v1
	v_add_f32_e32 v0, v0, v1
	v_mul_f32_e32 v0, 0x3b000000, v0
	v_add_f32_e64 v4, v44, -v0
	v_add_f32_e64 v5, v45, -v0
	v_add_f32_e64 v28, v42, -v0
	v_add_f32_e64 v29, v43, -v0
	v_fma_f32 v35, v4, v4, 0
	v_fmac_f32_e32 v35, v28, v28
	v_fmac_f32_e32 v35, v5, v5
	v_fmac_f32_e32 v35, v29, v29
	v_add_f32_e64 v16, v16, -v0
	v_add_f32_e64 v17, v17, -v0
	v_add_f32_e64 v1, v21, -v0
	v_add_f32_e64 v0, v20, -v0
	v_fmac_f32_e32 v35, v16, v16
	v_fmac_f32_e32 v35, v0, v0
	v_fmac_f32_e32 v35, v17, v17
	v_fmac_f32_e32 v35, v1, v1
	v_and_or_b32 v25, v25, s25, v34
	s_nop 0
	v_add_f32_dpp v20, v35, v35 quad_perm:[1,0,3,2] row_mask:0xf bank_mask:0xf bound_ctrl:1
	s_nop 1
	v_add_f32_dpp v20, v20, v20 quad_perm:[2,3,0,1] row_mask:0xf bank_mask:0xf bound_ctrl:1
	s_nop 1
	v_add_f32_dpp v20, v20, v20 row_half_mirror row_mask:0xf bank_mask:0xf bound_ctrl:1
	s_nop 1
	v_add_f32_dpp v20, v20, v20 row_ror:8 row_mask:0xf bank_mask:0xf bound_ctrl:1
	v_mov_b32_e32 v21, v20
	s_nop 1
	v_permlane16_swap_b32_e32 v20, v21
	v_add_f32_e32 v20, v20, v21
	v_mov_b32_e32 v21, v20
	s_nop 1
	v_permlane32_swap_b32_e32 v20, v21
	v_add_f32_e32 v20, v20, v21
	v_fmamk_f32 v20, v20, 0x3b000000, v135
	v_mul_f32_e32 v21, 0x4f800000, v20
	v_cmp_gt_f32_e32 vcc, s26, v20
	s_nop 1
	v_cndmask_b32_e32 v20, v20, v21, vcc
	v_sqrt_f32_e32 v21, v20
	s_nop 0
	v_add_u32_e32 v30, -1, v21
	v_fma_f32 v31, -v30, v21, v20
	v_cmp_ge_f32_e64 s[4:5], 0, v31
	v_add_u32_e32 v31, 1, v21
	s_nop 0
	v_cndmask_b32_e64 v30, v21, v30, s[4:5]
	v_fma_f32 v21, -v31, v21, v20
	v_cmp_lt_f32_e64 s[4:5], 0, v21
	s_nop 1
	v_cndmask_b32_e64 v21, v30, v31, s[4:5]
	v_mul_f32_e32 v30, 0x37800000, v21
	v_cndmask_b32_e32 v21, v21, v30, vcc
	v_cmp_class_f32_e32 vcc, v20, v136
	s_nop 1
	v_cndmask_b32_e32 v30, v21, v20, vcc
	v_div_scale_f32 v31, s[4:5], v30, v30, 1.0
	v_rcp_f32_e32 v34, v31
	v_add_co_u32_e32 v20, vcc, s29, v32
	v_fma_f32 v32, -v31, v34, 1.0
	s_nop 0
	v_addc_co_u32_e32 v21, vcc, 0, v33, vcc
	v_fmac_f32_e32 v34, v32, v34
	v_div_scale_f32 v32, vcc, 1.0, v30, 1.0
	v_mul_f32_e32 v33, v32, v34
	v_fma_f32 v35, -v31, v33, v32
	v_fmac_f32_e32 v33, v35, v34
	v_fma_f32 v31, -v31, v33, v32
	v_div_fmas_f32 v31, v31, v34, v33
	v_div_fixup_f32 v30, v31, v30, 1.0
	v_mul_f32_e32 v4, v4, v30
	v_mul_f32_e32 v5, v5, v30
	v_mul_f32_e32 v16, v16, v30
	v_mul_f32_e32 v17, v17, v30
	v_fma_f32 v4, v18, v4, v22
	v_fma_f32 v5, v19, v5, v23
	v_fma_f32 v8, v8, v16, v12
	v_fma_f32 v9, v9, v17, v13
	v_mul_f32_e32 v18, 0xbfb8aa3b, v4
	v_mul_f32_e32 v12, 0xbfb8aa3b, v8
	v_exp_f32_e32 v22, v18
	v_mul_f32_e32 v18, v28, v30
	v_mul_f32_e32 v19, v29, v30
	v_exp_f32_e32 v12, v12
	v_mul_f32_e32 v0, v0, v30
	v_mul_f32_e32 v1, v1, v30
	v_fma_f32 v10, v10, v18, v14
	v_fma_f32 v11, v11, v19, v15
	v_fma_f32 v0, v2, v0, v6
	v_fma_f32 v1, v3, v1, v7
	v_mul_f32_e32 v14, 0xbfb8aa3b, v10
	v_mul_f32_e32 v18, 0xbfb8aa3b, v5
	v_mul_f32_e32 v2, 0xbfb8aa3b, v0
	v_mul_f32_e32 v6, 0xbfb8aa3b, v9
	v_exp_f32_e32 v15, v14
	v_exp_f32_e32 v19, v18
	v_mul_f32_e32 v18, 0xbfb8aa3b, v11
	v_exp_f32_e32 v3, v2
	v_exp_f32_e32 v7, v6
	v_mul_f32_e32 v6, 0xbfb8aa3b, v1
	v_add_f32_e32 v14, 1.0, v22
	v_exp_f32_e32 v22, v18
	v_add_f32_e32 v2, 1.0, v12
	v_exp_f32_e32 v12, v6
	v_add_f32_e32 v15, 1.0, v15
	v_add_f32_e32 v3, 1.0, v3
	v_rcp_f32_e32 v18, v15
	v_add_f32_e32 v15, 1.0, v19
	v_add_f32_e32 v19, 1.0, v22
	v_rcp_f32_e32 v6, v3
	v_add_f32_e32 v3, 1.0, v7
	v_add_f32_e32 v7, 1.0, v12
	v_rcp_f32_e32 v19, v19
	v_rcp_f32_e32 v7, v7
	v_rcp_f32_e32 v14, v14
	v_rcp_f32_e32 v15, v15
	v_rcp_f32_e32 v2, v2
	v_rcp_f32_e32 v3, v3
	v_mul_f32_e32 v10, v10, v18
	v_mul_f32_e32 v11, v11, v19
	v_mul_f32_e32 v0, v0, v6
	v_mul_f32_e32 v1, v1, v7
	v_mul_f32_e32 v4, v4, v14
	v_mul_f32_e32 v5, v5, v15
	v_mul_f32_e32 v2, v8, v2
	v_mul_f32_e32 v3, v9, v3
	v_bfe_u32 v6, v1, 16, 1
	v_bfe_u32 v7, v0, 16, 1
	v_bfe_u32 v8, v11, 16, 1
	v_bfe_u32 v9, v10, 16, 1
	v_add3_u32 v9, v10, v9, s27
	v_add3_u32 v8, v11, v8, s27
	v_add3_u32 v0, v0, v7, s27
	v_add3_u32 v1, v1, v6, s27
	v_bfe_u32 v6, v4, 16, 1
	v_bfe_u32 v7, v5, 16, 1
	v_bfe_u32 v10, v2, 16, 1
	v_bfe_u32 v11, v3, 16, 1
	v_add3_u32 v3, v3, v11, s27
	v_add3_u32 v2, v2, v10, s27
	v_add3_u32 v5, v5, v7, s27
	v_add3_u32 v4, v4, v6, s27
	v_lshrrev_b32_e32 v4, 16, v4
	v_lshrrev_b32_e32 v5, 16, v5
	v_lshrrev_b32_e32 v2, 16, v2
	v_lshrrev_b32_e32 v3, 16, v3
	v_and_or_b32 v3, v1, s25, v3
	v_and_or_b32 v2, v0, s25, v2
	v_and_or_b32 v1, v8, s25, v5
	v_and_or_b32 v0, v9, s25, v4
	global_store_dwordx4 v[20:21], v[24:27], off offset:1024
	global_store_dwordx4 v[20:21], v[0:3], off offset:3072
	s_cbranch_scc0 .LBB0_548

.LBB0_517:
	s_waitcnt lgkmcnt(1)
	v_mov_b32_e32 v36, v30
	v_mov_b32_e32 v37, v32
	v_fma_f32 v78, v36, v24, v66
	v_fma_f32 v79, v37, v25, v67
	s_waitcnt lgkmcnt(0)
	v_mov_b32_e32 v82, v26
	v_mov_b32_e32 v83, v28
	v_mov_b32_e32 v28, v27
	v_fma_f32 v100, v74, v24, v60
	v_fma_f32 v101, v75, v25, v61
	v_fma_f32 v108, v70, v24, v52
	v_fma_f32 v109, v71, v25, v53
	v_fma_f32 v132, v132, v24, v44
	v_fma_f32 v133, v133, v25, v45
	ds_read_b128 v[24:27], v137 offset:16384
	v_fma_f32 v140, v12, v0, v16
	v_fma_f32 v141, v13, v1, v17
	v_fma_f32 v142, v10, v6, v20
	v_fma_f32 v143, v11, v7, v21
	ds_read_b128 v[10:13], v137 offset:16400
	s_add_i32 s35, s35, 6
	s_add_u32 s46, s46, 0x3000
	v_mov_b32_e32 v32, v31
	s_addc_u32 s47, s47, 0
	v_fma_f32 v30, v32, v2, v68
	v_fma_f32 v31, v33, v3, v69
	v_fma_f32 v84, v82, v0, v62
	v_fma_f32 v85, v83, v1, v63
	v_fma_f32 v86, v28, v6, v64
	v_fma_f32 v87, v29, v7, v65
	v_fma_f32 v102, v4, v2, v58
	v_fma_f32 v103, v5, v3, v59
	v_fma_f32 v104, v76, v0, v54
	v_fma_f32 v105, v77, v1, v55
	v_fma_f32 v106, v8, v6, v56
	v_fma_f32 v107, v9, v7, v57
	v_fma_f32 v114, v22, v2, v50
	v_fma_f32 v115, v23, v3, v51
	v_fma_f32 v116, v72, v0, v46
	v_fma_f32 v117, v73, v1, v47
	v_fma_f32 v138, v18, v6, v48
	v_fma_f32 v139, v19, v7, v49
	v_fma_f32 v14, v14, v2, v42
	v_fma_f32 v15, v15, v3, v43
	s_waitcnt lgkmcnt(1)
	v_mov_b32_e32 v0, v24
	v_mov_b32_e32 v1, v26
	v_mov_b32_e32 v26, v25
	s_waitcnt lgkmcnt(0)
	v_mov_b32_e32 v2, v10
	v_mov_b32_e32 v3, v12
	v_mov_b32_e32 v12, v11
	s_add_u32 s4, s4, 0x3000
	v_fma_f32 v0, v0, v34, v78
	v_fma_f32 v1, v1, v35, v79
	v_fma_f32 v6, v26, v40, v30
	v_fma_f32 v7, v27, v41, v31
	v_fma_f32 v130, v2, v38, v84
	v_fma_f32 v131, v3, v39, v85
	v_fma_f32 v2, v12, v80, v86
	v_fma_f32 v3, v13, v81, v87
	v_fma_f32 v128, v36, v34, v100
	v_fma_f32 v129, v37, v35, v101
	v_fma_f32 v126, v32, v40, v102
	v_fma_f32 v127, v33, v41, v103
	v_fma_f32 v124, v82, v38, v104
	v_fma_f32 v125, v83, v39, v105
	v_fma_f32 v122, v28, v80, v106
	v_fma_f32 v123, v29, v81, v107
	v_fma_f32 v120, v74, v34, v108
	v_fma_f32 v121, v75, v35, v109
	v_fma_f32 v118, v4, v40, v114
	v_fma_f32 v119, v5, v41, v115
	v_fmac_f32_e32 v116, v76, v38
	v_fmac_f32_e32 v117, v77, v39
	v_fma_f32 v114, v8, v80, v138
	v_fma_f32 v115, v9, v81, v139
	v_fma_f32 v108, v70, v34, v132
	v_fma_f32 v109, v71, v35, v133
	v_fma_f32 v106, v22, v40, v14
	v_fma_f32 v107, v23, v41, v15
	v_fma_f32 v104, v72, v38, v140
	v_fma_f32 v105, v73, v39, v141
	v_fma_f32 v102, v18, v80, v142
	v_fma_f32 v103, v19, v81, v143
	s_addc_u32 s5, s5, 0
	s_mov_b64 s[48:49], 0

.LBB0_539:
	s_waitcnt vmcnt(0)
	v_mov_b32_e32 v5, v38
	v_mov_b32_e32 v38, v37
	v_mov_b32_e32 v37, v34
	v_mov_b32_e32 v34, v33
	s_waitcnt lgkmcnt(11)
	v_mov_b32_e32 v33, v30
	v_mov_b32_e32 v30, v29
	s_waitcnt lgkmcnt(10)
	v_mov_b32_e32 v29, v26
	v_mov_b32_e32 v26, v25
	s_waitcnt lgkmcnt(9)
	v_mov_b32_e32 v25, v46
	v_mov_b32_e32 v46, v45
	v_mov_b32_e32 v4, v36
	v_mov_b32_e32 v36, v32
	v_mov_b32_e32 v32, v28
	v_mov_b32_e32 v28, v24
	v_mov_b32_e32 v24, v44
	v_fma_f32 v44, v46, v38, v126
	v_fma_f32 v45, v47, v39, v127
	s_waitcnt lgkmcnt(8)
	v_mov_b32_e32 v127, v42
	v_mov_b32_e32 v42, v41
	v_mov_b32_e32 v126, v40
	v_fma_f32 v40, v42, v34, v122
	v_fma_f32 v41, v43, v35, v123
	s_waitcnt lgkmcnt(7)
	v_mov_b32_e32 v123, v54
	v_mov_b32_e32 v54, v53
	v_mov_b32_e32 v122, v52
	v_fma_f32 v52, v54, v38, v118
	v_fma_f32 v53, v55, v39, v119
	s_waitcnt lgkmcnt(6)
	v_mov_b32_e32 v119, v50
	v_mov_b32_e32 v50, v49
	v_mov_b32_e32 v118, v48
	v_fma_f32 v48, v50, v34, v114
	v_fma_f32 v49, v51, v35, v115
	s_waitcnt lgkmcnt(5)
	v_mov_b32_e32 v114, v68
	v_mov_b32_e32 v115, v70
	v_mov_b32_e32 v70, v69
	s_waitcnt lgkmcnt(4)
	v_mov_b32_e32 v69, v66
	v_mov_b32_e32 v66, v65
	v_fmac_f32_e32 v0, v32, v4
	v_fmac_f32_e32 v1, v33, v5
	v_fmac_f32_e32 v6, v30, v38
	v_fmac_f32_e32 v7, v31, v39
	v_fmac_f32_e32 v2, v26, v34
	v_fmac_f32_e32 v3, v27, v35
	v_fmac_f32_e32 v128, v24, v4
	v_fmac_f32_e32 v129, v25, v5
	v_fmac_f32_e32 v120, v122, v4
	v_fmac_f32_e32 v121, v123, v5
	v_fma_f32 v4, v114, v4, v108
	v_fma_f32 v5, v115, v5, v109
	v_fma_f32 v38, v70, v38, v106
	v_fma_f32 v39, v71, v39, v107
	v_mov_b32_e32 v68, v64
	v_fma_f32 v34, v66, v34, v102
	v_fma_f32 v35, v67, v35, v103
	v_mov_b32_e32 v64, v56
	v_mov_b32_e32 v65, v58
	v_mov_b32_e32 v58, v57
	v_mov_b32_e32 v57, v62
	v_mov_b32_e32 v62, v61
	s_waitcnt lgkmcnt(3)
	v_mov_b32_e32 v133, v14
	v_mov_b32_e32 v14, v13
	s_waitcnt lgkmcnt(2)
	v_mov_b32_e32 v13, v10
	v_mov_b32_e32 v10, v9
	v_mov_b32_e32 v132, v12
	v_fmac_f32_e32 v6, v14, v58
	v_fmac_f32_e32 v7, v15, v59
	v_mov_b32_e32 v12, v8
	v_fmac_f32_e32 v2, v10, v62
	v_fmac_f32_e32 v3, v11, v63
	v_fma_f32 v8, v32, v64, v128
	v_fma_f32 v9, v33, v65, v129
	v_fmac_f32_e32 v4, v122, v64
	v_fmac_f32_e32 v5, v123, v65
	v_fmac_f32_e32 v38, v54, v58
	v_fmac_f32_e32 v39, v55, v59
	v_fmac_f32_e32 v34, v50, v62
	v_fmac_f32_e32 v35, v51, v63
	v_mov_b32_e32 v50, v72
	v_mov_b32_e32 v51, v74
	v_mov_b32_e32 v74, v73
	v_mov_b32_e32 v55, v78
	v_mov_b32_e32 v78, v77
	s_waitcnt lgkmcnt(1)
	v_mov_b32_e32 v71, v22
	v_mov_b32_e32 v22, v21
	s_waitcnt lgkmcnt(0)
	v_mov_b32_e32 v73, v18
	v_mov_b32_e32 v18, v17
	v_fmac_f32_e32 v130, v28, v36
	v_fmac_f32_e32 v131, v29, v37
	v_fmac_f32_e32 v124, v126, v36
	v_fmac_f32_e32 v125, v127, v37
	v_fmac_f32_e32 v116, v118, v36
	v_fmac_f32_e32 v117, v119, v37
	v_fma_f32 v36, v68, v36, v104
	v_fma_f32 v37, v69, v37, v105
	v_fmac_f32_e32 v44, v30, v58
	v_fmac_f32_e32 v45, v31, v59
	v_fma_f32 v68, v24, v64, v120
	v_fma_f32 v69, v25, v65, v121
	v_fmac_f32_e32 v52, v46, v58
	v_fmac_f32_e32 v53, v47, v59
	v_mov_b32_e32 v70, v20
	v_fma_f32 v20, v22, v74, v6
	v_fma_f32 v21, v23, v75, v7
	v_mov_b32_e32 v72, v16
	v_fma_f32 v16, v18, v78, v2
	v_fma_f32 v17, v19, v79, v3
	v_fma_f32 v58, v132, v50, v8
	v_fma_f32 v59, v133, v51, v9
	v_fma_f32 v24, v24, v50, v4
	v_fma_f32 v25, v25, v51, v5
	ds_read_b128 v[2:5], v137 offset:12288
	ds_read_b128 v[6:9], v137 offset:12304
	v_mov_b32_e32 v56, v60
	v_fmac_f32_e32 v0, v132, v64
	v_fmac_f32_e32 v1, v133, v65
	v_fma_f32 v60, v12, v56, v130
	v_fma_f32 v61, v13, v57, v131
	v_fma_f32 v66, v28, v56, v124
	v_fma_f32 v67, v29, v57, v125
	v_fmac_f32_e32 v40, v26, v62
	v_fmac_f32_e32 v41, v27, v63
	v_fma_f32 v102, v126, v56, v116
	v_fma_f32 v103, v127, v57, v117
	v_fmac_f32_e32 v48, v42, v62
	v_fmac_f32_e32 v49, v43, v63
	v_fmac_f32_e32 v36, v118, v56
	v_fmac_f32_e32 v37, v119, v57
	v_mov_b32_e32 v54, v76
	v_fmac_f32_e32 v0, v70, v50
	v_fmac_f32_e32 v1, v71, v51
	v_fma_f32 v56, v72, v54, v60
	v_fma_f32 v57, v73, v55, v61
	v_fmac_f32_e32 v44, v14, v74
	v_fmac_f32_e32 v45, v15, v75
	v_fma_f32 v104, v12, v54, v66
	v_fma_f32 v105, v13, v55, v67
	v_fmac_f32_e32 v40, v10, v78
	v_fmac_f32_e32 v41, v11, v79
	v_fma_f32 v106, v32, v50, v68
	v_fma_f32 v107, v33, v51, v69
	v_fma_f32 v108, v30, v74, v52
	v_fma_f32 v109, v31, v75, v53
	v_fmac_f32_e32 v102, v28, v54
	v_fmac_f32_e32 v103, v29, v55
	v_fmac_f32_e32 v48, v26, v78
	v_fmac_f32_e32 v49, v27, v79
	v_fmac_f32_e32 v38, v46, v74
	v_fmac_f32_e32 v39, v47, v75
	v_fmac_f32_e32 v36, v126, v54
	v_fmac_f32_e32 v37, v127, v55
	v_fmac_f32_e32 v34, v42, v78
	v_fmac_f32_e32 v35, v43, v79
	v_mov_b32_e32 v42, v80
	v_mov_b32_e32 v43, v82
	v_mov_b32_e32 v82, v81
	v_mov_b32_e32 v78, v84
	v_mov_b32_e32 v79, v86
	v_mov_b32_e32 v86, v85
	s_waitcnt lgkmcnt(1)
	v_mov_b32_e32 v74, v2
	v_mov_b32_e32 v75, v4
	v_mov_b32_e32 v4, v3
	s_waitcnt lgkmcnt(0)
	v_mov_b32_e32 v76, v6
	v_mov_b32_e32 v77, v8
	v_mov_b32_e32 v8, v7
	v_fma_f32 v66, v74, v42, v0
	v_fma_f32 v67, v75, v43, v1
	v_fma_f32 v68, v4, v82, v20
	v_fma_f32 v69, v5, v83, v21
	v_fma_f32 v62, v76, v78, v56
	v_fma_f32 v63, v77, v79, v57
	v_fma_f32 v64, v8, v86, v16
	v_fma_f32 v65, v9, v87, v17
	v_fma_f32 v60, v70, v42, v58
	v_fma_f32 v61, v71, v43, v59
	v_fma_f32 v58, v22, v82, v44
	v_fma_f32 v59, v23, v83, v45
	v_fma_f32 v54, v72, v78, v104
	v_fma_f32 v55, v73, v79, v105
	v_fma_f32 v56, v18, v86, v40
	v_fma_f32 v57, v19, v87, v41
	v_fma_f32 v52, v132, v42, v106
	v_fma_f32 v53, v133, v43, v107
	v_fma_f32 v50, v14, v82, v108
	v_fma_f32 v51, v15, v83, v109
	v_fma_f32 v46, v12, v78, v102
	v_fma_f32 v47, v13, v79, v103
	v_fmac_f32_e32 v48, v10, v86
	v_fmac_f32_e32 v49, v11, v87
	v_fma_f32 v44, v32, v42, v24
	v_fma_f32 v45, v33, v43, v25
	v_fma_f32 v42, v30, v82, v38
	v_fma_f32 v43, v31, v83, v39
	v_fma_f32 v16, v28, v78, v36
	v_fma_f32 v17, v29, v79, v37
	v_fma_f32 v20, v26, v86, v34
	v_fma_f32 v21, v27, v87, v35
	s_cmp_eq_u32 s35, 30
	s_mov_b64 s[48:49], -1
	s_cbranch_scc1 .LBB0_518
	s_cmp_lt_u32 s35, 26
	s_cbranch_scc1 .LBB0_542
	s_sub_i32 s48, s35, 26
	s_add_u32 s48, s44, s48
	s_addc_u32 s49, s45, 0
	s_lshl_b64 s[48:49], s[48:49], 10
	v_lshl_add_u64 v[0:1], v[90:91], 0, s[48:49]
	global_load_dwordx4 v[26:29], v[0:1], off
	s_mov_b64 s[48:49], 0
	s_waitcnt vmcnt(0)
	v_lshlrev_b32_e32 v24, 16, v26
	v_lshlrev_b32_e32 v25, 16, v27
	v_and_b32_e32 v3, 0xffff0000, v27
	v_and_b32_e32 v2, 0xffff0000, v26
	v_lshlrev_b32_e32 v0, 16, v28
	v_lshlrev_b32_e32 v1, 16, v29
	v_and_b32_e32 v7, 0xffff0000, v29
	v_and_b32_e32 v6, 0xffff0000, v28

.LBB0_566:
	s_lshr_b32 s42, s53, 3
	s_cmp_eq_u32 s42, 2
	s_cselect_b32 s6, s47, s49
	s_cmp_eq_u32 s42, 1
	s_waitcnt vmcnt(8)
	v_cvt_pk_bf16_f32 v112, v144, v145
	v_cvt_pk_bf16_f32 v113, v146, v147
	s_cselect_b32 s6, s45, s6
	s_cmp_lt_u32 s53, 8
	ds_write_b64 v181, v[112:113] offset:43008
	v_cvt_pk_bf16_f32 v112, v140, v141
	v_cvt_pk_bf16_f32 v113, v142, v143
	s_cselect_b32 s6, s22, s6
	ds_write_b64 v181, v[112:113] offset:43552
	v_cvt_pk_bf16_f32 v112, v136, v137
	v_cvt_pk_bf16_f32 v113, v138, v139
	s_ashr_i32 s7, s6, 31
	s_and_b32 s46, s51, 0x60
	ds_write_b64 v181, v[112:113] offset:44096
	v_cvt_pk_bf16_f32 v112, v132, v133
	v_cvt_pk_bf16_f32 v113, v134, v135
	s_or_b32 s16, s46, 16
	s_lshl_b64 s[40:41], s[6:7], 18
	ds_write_b64 v181, v[112:113] offset:44640
	v_cvt_pk_bf16_f32 v112, v128, v129
	v_cvt_pk_bf16_f32 v113, v130, v131
	s_add_u32 s6, s8, s40
	ds_write_b64 v181, v[112:113] offset:45184
	v_cvt_pk_bf16_f32 v112, v124, v125
	v_cvt_pk_bf16_f32 v113, v126, v127
	s_addc_u32 s7, s9, s41
	s_lshl_b32 s44, s16, 11
	ds_write_b64 v181, v[112:113] offset:45728
	v_cvt_pk_bf16_f32 v112, v120, v121
	v_cvt_pk_bf16_f32 v113, v122, v123
	s_add_u32 s54, s6, s44
	ds_write_b64 v181, v[112:113] offset:46272
	v_cvt_pk_bf16_f32 v112, v116, v117
	v_cvt_pk_bf16_f32 v113, v118, v119
	s_addc_u32 s55, s7, 0
	ds_write_b64 v181, v[112:113] offset:46816
	v_lshl_add_u64 v[112:113], s[54:55], 0, v[168:169]
	v_add_co_u32_e64 v114, s[6:7], s14, v112
	v_mov_b32_e32 v183, v182
	s_nop 0
	v_addc_co_u32_e64 v115, s[6:7], 0, v113, s[6:7]
	global_load_dwordx4 v[140:143], v[114:115], off offset:-4096 nt
	global_load_dwordx4 v[136:139], v[114:115], off nt
	v_add_co_u32_e64 v114, s[6:7], s15, v112
	s_nop 1
	v_addc_co_u32_e64 v115, s[6:7], 0, v113, s[6:7]
	global_load_dwordx4 v[132:135], v[114:115], off offset:-4096 nt
	global_load_dwordx4 v[128:131], v[114:115], off nt
	v_add_co_u32_e64 v114, s[6:7], s26, v112
	s_nop 1
	v_addc_co_u32_e64 v115, s[6:7], 0, v113, s[6:7]
	v_add_co_u32_e64 v112, s[6:7], s27, v112
	global_load_dwordx4 v[124:127], v[114:115], off offset:-4096 nt
	global_load_dwordx4 v[120:123], v[114:115], off nt
	v_addc_co_u32_e64 v113, s[6:7], 0, v113, s[6:7]
	global_load_dwordx4 v[144:147], v168, s[54:55] nt
	global_load_dwordx4 v[116:119], v[112:113], off nt
	s_or_b32 s6, s42, s25
	s_lshl_b32 s42, s6, 7
	s_or_b32 s6, s42, s46
	v_add_u32_e32 v112, s6, v179
	v_add_u32_e32 v113, -1, v112
	v_add_u32_e32 v114, -2, v112
	v_add_u32_e32 v115, -3, v112
	s_waitcnt lgkmcnt(0)
	v_cvt_f32_i32_e32 v152, v112
	v_cvt_f32_i32_e32 v153, v113
	v_cvt_f32_i32_e32 v155, v115
	v_cvt_f32_i32_e32 v154, v114
	ds_read_b128 v[112:115], v190 offset:43008
	ds_read_b128 v[148:151], v190 offset:43072
	v_mul_f32_e32 v152, v184, v152
	v_mul_f32_e32 v153, v185, v153
	v_mul_f32_e32 v154, v182, v154
	v_mul_f32_e32 v155, v183, v155
	s_waitcnt lgkmcnt(1)
	s_nop 0
	v_mfma_f32_16x16x32_bf16 v[112:115], v[24:27], v[112:115], v[152:155]
	s_waitcnt lgkmcnt(0)
	v_mfma_f32_16x16x32_bf16 v[112:115], v[48:51], v[148:151], v[112:115]
	ds_read_b128 v[148:151], v190 offset:43136
	ds_read_b128 v[152:155], v190 offset:43200
	s_waitcnt lgkmcnt(1)
	v_mfma_f32_16x16x32_bf16 v[112:115], v[52:55], v[148:151], v[112:115]
	s_waitcnt lgkmcnt(0)
	v_mfma_f32_16x16x32_bf16 v[112:115], v[60:63], v[152:155], v[112:115]
	s_nop 7
	v_mov_b32_dpp v148, v112 quad_perm:[1,0,3,2] row_mask:0xf bank_mask:0xf bound_ctrl:1
	v_max_f32_e32 v149, v112, v112
	v_max_f32_e32 v148, v148, v148
	v_max_f32_e32 v148, v149, v148
	s_nop 1
	v_mov_b32_dpp v149, v148 quad_perm:[2,3,0,1] row_mask:0xf bank_mask:0xf bound_ctrl:1
	v_max_f32_e32 v149, v149, v149
	v_max_f32_e32 v148, v148, v149
	s_nop 1
	v_mov_b32_dpp v149, v148 row_half_mirror row_mask:0xf bank_mask:0xf bound_ctrl:1
	v_max_f32_e32 v149, v149, v149
	v_max_f32_e32 v148, v148, v149
	s_nop 1
	v_mov_b32_dpp v149, v148 row_ror:8 row_mask:0xf bank_mask:0xf bound_ctrl:1
	v_max3_f32 v192, v172, v148, v149
	v_mov_b32_dpp v148, v113 quad_perm:[1,0,3,2] row_mask:0xf bank_mask:0xf bound_ctrl:1
	v_max_f32_e32 v149, v113, v113
	v_max_f32_e32 v148, v148, v148
	v_max_f32_e32 v148, v149, v148
	v_sub_f32_e32 v112, v112, v192
	v_exp_f32_e32 v112, v112
	v_mov_b32_dpp v149, v148 quad_perm:[2,3,0,1] row_mask:0xf bank_mask:0xf bound_ctrl:1
	v_max_f32_e32 v149, v149, v149
	v_max_f32_e32 v148, v148, v149
	s_nop 1
	v_mov_b32_dpp v149, v148 row_half_mirror row_mask:0xf bank_mask:0xf bound_ctrl:1
	v_max_f32_e32 v149, v149, v149
	v_max_f32_e32 v148, v148, v149
	s_nop 1
	v_mov_b32_dpp v149, v148 row_ror:8 row_mask:0xf bank_mask:0xf bound_ctrl:1
	v_max3_f32 v193, v178, v148, v149
	v_mov_b32_dpp v148, v114 quad_perm:[1,0,3,2] row_mask:0xf bank_mask:0xf bound_ctrl:1
	v_max_f32_e32 v149, v114, v114
	v_max_f32_e32 v148, v148, v148
	v_max_f32_e32 v148, v149, v148
	v_sub_f32_e32 v113, v113, v193
	v_exp_f32_e32 v113, v113
	v_mov_b32_dpp v149, v148 quad_perm:[2,3,0,1] row_mask:0xf bank_mask:0xf bound_ctrl:1
	v_max_f32_e32 v149, v149, v149
	v_max_f32_e32 v148, v148, v149
	s_nop 1
	v_mov_b32_dpp v149, v148 row_half_mirror row_mask:0xf bank_mask:0xf bound_ctrl:1
	v_max_f32_e32 v149, v149, v149
	v_max_f32_e32 v148, v148, v149
	s_nop 1
	v_mov_b32_dpp v149, v148 row_ror:8 row_mask:0xf bank_mask:0xf bound_ctrl:1
	v_max3_f32 v194, v180, v148, v149
	v_mov_b32_dpp v148, v115 quad_perm:[1,0,3,2] row_mask:0xf bank_mask:0xf bound_ctrl:1
	v_max_f32_e32 v149, v115, v115
	v_max_f32_e32 v148, v148, v148
	v_max_f32_e32 v148, v149, v148
	v_sub_f32_e32 v114, v114, v194
	v_exp_f32_e32 v114, v114
	v_mov_b32_dpp v149, v148 quad_perm:[2,3,0,1] row_mask:0xf bank_mask:0xf bound_ctrl:1
	v_max_f32_e32 v149, v149, v149
	v_max_f32_e32 v148, v148, v149
	s_nop 1
	v_mov_b32_dpp v149, v148 row_half_mirror row_mask:0xf bank_mask:0xf bound_ctrl:1
	v_max_f32_e32 v149, v149, v149
	v_max_f32_e32 v148, v148, v149
	s_nop 1
	v_mov_b32_dpp v149, v148 row_ror:8 row_mask:0xf bank_mask:0xf bound_ctrl:1
	v_max3_f32 v195, v170, v148, v149
	v_sub_f32_e32 v115, v115, v195
	v_exp_f32_e32 v115, v115
	s_and_saveexec_b64 s[6:7], vcc
	ds_write_b128 v191, v[112:115] offset:34816
	s_or_b64 exec, exec, s[6:7]
	s_cmp_eq_u32 s53, 0
	s_cbranch_scc1 .LBB0_570
	ds_read_b128 v[196:199], v173 offset:35328
	ds_read_b128 v[200:203], v173 offset:35344
	ds_read_b128 v[204:207], v173 offset:35392
	ds_read_b128 v[208:211], v173 offset:35408
	ds_read_b128 v[212:215], v173 offset:35456
	ds_read_b128 v[216:219], v173 offset:35472
	ds_read_b128 v[220:223], v173 offset:35520
	ds_read_b128 v[164:167], v173 offset:35536
	ds_read_b128 v[224:227], v173 offset:35584
	ds_read_b128 v[160:163], v173 offset:35600
	ds_read_b128 v[228:231], v173 offset:35648
	ds_read_b128 v[156:159], v173 offset:35664
	ds_read_b128 v[232:235], v173 offset:35712
	ds_read_b128 v[152:155], v173 offset:35728
	ds_read_b128 v[236:239], v173 offset:35776
	ds_read_b128 v[148:151], v173 offset:35792
	s_waitcnt lgkmcnt(14)
	v_fmac_f32_e32 v10, v200, v110
	v_fmac_f32_e32 v11, v200, v111
	v_fmac_f32_e32 v8, v200, v108
	v_fmac_f32_e32 v9, v200, v109
	v_fmac_f32_e32 v22, v201, v110
	v_fmac_f32_e32 v23, v201, v111
	v_fmac_f32_e32 v20, v201, v108
	v_fmac_f32_e32 v21, v201, v109
	s_waitcnt lgkmcnt(12)
	v_fmac_f32_e32 v10, v208, v102
	v_fmac_f32_e32 v11, v208, v103
	v_fmac_f32_e32 v8, v208, v100
	v_fmac_f32_e32 v9, v208, v101
	v_fmac_f32_e32 v22, v209, v102
	v_fmac_f32_e32 v23, v209, v103
	v_fmac_f32_e32 v20, v209, v100
	v_fmac_f32_e32 v21, v209, v101
	s_waitcnt lgkmcnt(10)
	v_fmac_f32_e32 v10, v216, v70
	v_fmac_f32_e32 v11, v216, v71
	v_fmac_f32_e32 v8, v216, v68
	v_fmac_f32_e32 v9, v216, v69
	v_fmac_f32_e32 v22, v217, v70
	v_fmac_f32_e32 v23, v217, v71
	v_fmac_f32_e32 v20, v217, v68
	v_fmac_f32_e32 v21, v217, v69
	s_waitcnt lgkmcnt(8)
	v_fmac_f32_e32 v10, v164, v66
	v_fmac_f32_e32 v11, v164, v67
	v_fmac_f32_e32 v8, v164, v64
	v_fmac_f32_e32 v9, v164, v65
	v_fmac_f32_e32 v22, v165, v66
	v_fmac_f32_e32 v23, v165, v67
	v_fmac_f32_e32 v20, v165, v64
	v_fmac_f32_e32 v21, v165, v65
	s_waitcnt lgkmcnt(6)
	v_fmac_f32_e32 v10, v160, v58
	v_fmac_f32_e32 v11, v160, v59
	v_fmac_f32_e32 v8, v160, v56
	v_fmac_f32_e32 v9, v160, v57
	v_fmac_f32_e32 v22, v161, v58
	v_fmac_f32_e32 v23, v161, v59
	v_fmac_f32_e32 v20, v161, v56
	v_fmac_f32_e32 v21, v161, v57
	s_waitcnt lgkmcnt(4)
	v_fmac_f32_e32 v10, v156, v42
	v_fmac_f32_e32 v11, v156, v43
	v_fmac_f32_e32 v8, v156, v40
	v_fmac_f32_e32 v9, v156, v41
	v_fmac_f32_e32 v22, v157, v42
	v_fmac_f32_e32 v23, v157, v43
	v_fmac_f32_e32 v20, v157, v40
	v_fmac_f32_e32 v21, v157, v41
	s_waitcnt lgkmcnt(2)
	v_fmac_f32_e32 v10, v152, v14
	v_fmac_f32_e32 v11, v152, v15
	v_fmac_f32_e32 v8, v152, v12
	v_fmac_f32_e32 v9, v152, v13
	v_fmac_f32_e32 v22, v153, v14
	v_fmac_f32_e32 v23, v153, v15
	v_fmac_f32_e32 v20, v153, v12
	v_fmac_f32_e32 v21, v153, v13
	s_waitcnt lgkmcnt(0)
	v_fmac_f32_e32 v10, v148, v2
	v_fmac_f32_e32 v11, v148, v3
	v_fmac_f32_e32 v8, v148, v0
	v_fmac_f32_e32 v9, v148, v1
	v_fmac_f32_e32 v22, v149, v2
	v_fmac_f32_e32 v23, v149, v3
	v_fmac_f32_e32 v20, v149, v0
	v_fmac_f32_e32 v21, v149, v1
	v_mov_b32_e32 v148, v199
	v_fmac_f32_e32 v38, v148, v110
	v_fmac_f32_e32 v39, v148, v111
	v_fmac_f32_e32 v36, v148, v108
	v_fmac_f32_e32 v37, v148, v109
	v_mov_b32_e32 v148, v207
	v_fmac_f32_e32 v38, v148, v102
	v_fmac_f32_e32 v39, v148, v103
	v_fmac_f32_e32 v36, v148, v100
	v_fmac_f32_e32 v37, v148, v101
	v_mov_b32_e32 v148, v215
	v_fmac_f32_e32 v38, v148, v70
	v_fmac_f32_e32 v39, v148, v71
	v_fmac_f32_e32 v36, v148, v68
	v_fmac_f32_e32 v37, v148, v69
	v_mov_b32_e32 v148, v223
	v_fmac_f32_e32 v38, v148, v66
	v_fmac_f32_e32 v39, v148, v67
	v_fmac_f32_e32 v36, v148, v64
	v_fmac_f32_e32 v37, v148, v65
	v_mov_b32_e32 v148, v227
	v_fmac_f32_e32 v38, v148, v58
	v_fmac_f32_e32 v39, v148, v59
	v_fmac_f32_e32 v36, v148, v56
	v_fmac_f32_e32 v37, v148, v57
	v_mov_b32_e32 v148, v231
	v_fmac_f32_e32 v38, v148, v42
	v_fmac_f32_e32 v39, v148, v43
	v_fmac_f32_e32 v36, v148, v40
	v_fmac_f32_e32 v37, v148, v41
	v_mov_b32_e32 v148, v235
	v_fmac_f32_e32 v38, v148, v14
	v_fmac_f32_e32 v39, v148, v15
	v_fmac_f32_e32 v36, v148, v12
	v_fmac_f32_e32 v37, v148, v13
	v_mov_b32_e32 v148, v239
	v_fmac_f32_e32 v38, v148, v2
	v_fmac_f32_e32 v39, v148, v3
	v_fmac_f32_e32 v36, v148, v0
	v_fmac_f32_e32 v37, v148, v1
	v_mov_b32_e32 v148, v203
	v_fmac_f32_e32 v6, v196, v110
	v_fmac_f32_e32 v7, v196, v111
	v_fmac_f32_e32 v4, v196, v108
	v_fmac_f32_e32 v5, v196, v109
	v_fmac_f32_e32 v18, v197, v110
	v_fmac_f32_e32 v19, v197, v111
	v_fmac_f32_e32 v16, v197, v108
	v_fmac_f32_e32 v17, v197, v109
	v_fmac_f32_e32 v30, v198, v110
	v_fmac_f32_e32 v31, v198, v111
	v_fmac_f32_e32 v28, v198, v108
	v_fmac_f32_e32 v29, v198, v109
	v_fmac_f32_e32 v34, v202, v110
	v_fmac_f32_e32 v35, v202, v111
	v_fmac_f32_e32 v32, v202, v108
	v_fmac_f32_e32 v33, v202, v109
	v_fmac_f32_e32 v46, v148, v110
	v_fmac_f32_e32 v47, v148, v111
	v_fmac_f32_e32 v44, v148, v108
	v_fmac_f32_e32 v45, v148, v109
	v_mov_b32_e32 v108, v211
	v_fmac_f32_e32 v6, v204, v102
	v_fmac_f32_e32 v7, v204, v103
	v_fmac_f32_e32 v4, v204, v100
	v_fmac_f32_e32 v5, v204, v101
	v_fmac_f32_e32 v18, v205, v102
	v_fmac_f32_e32 v19, v205, v103
	v_fmac_f32_e32 v16, v205, v100
	v_fmac_f32_e32 v17, v205, v101
	v_fmac_f32_e32 v30, v206, v102
	v_fmac_f32_e32 v31, v206, v103
	v_fmac_f32_e32 v28, v206, v100
	v_fmac_f32_e32 v29, v206, v101
	v_fmac_f32_e32 v34, v210, v102
	v_fmac_f32_e32 v35, v210, v103
	v_fmac_f32_e32 v32, v210, v100
	v_fmac_f32_e32 v33, v210, v101
	v_fmac_f32_e32 v46, v108, v102
	v_fmac_f32_e32 v47, v108, v103
	v_fmac_f32_e32 v44, v108, v100
	v_fmac_f32_e32 v45, v108, v101
	v_mov_b32_e32 v100, v219
	v_fmac_f32_e32 v6, v212, v70
	v_fmac_f32_e32 v7, v212, v71
	v_fmac_f32_e32 v4, v212, v68
	v_fmac_f32_e32 v5, v212, v69
	v_fmac_f32_e32 v18, v213, v70
	v_fmac_f32_e32 v19, v213, v71
	v_fmac_f32_e32 v16, v213, v68
	v_fmac_f32_e32 v17, v213, v69
	v_fmac_f32_e32 v30, v214, v70
	v_fmac_f32_e32 v31, v214, v71
	v_fmac_f32_e32 v28, v214, v68
	v_fmac_f32_e32 v29, v214, v69
	v_fmac_f32_e32 v34, v218, v70
	v_fmac_f32_e32 v35, v218, v71
	v_fmac_f32_e32 v32, v218, v68
	v_fmac_f32_e32 v33, v218, v69
	v_fmac_f32_e32 v46, v100, v70
	v_fmac_f32_e32 v47, v100, v71
	v_fmac_f32_e32 v44, v100, v68
	v_fmac_f32_e32 v45, v100, v69
	v_mov_b32_e32 v68, v167
	v_fmac_f32_e32 v6, v220, v66
	v_fmac_f32_e32 v7, v220, v67
	v_fmac_f32_e32 v4, v220, v64
	v_fmac_f32_e32 v5, v220, v65
	v_fmac_f32_e32 v18, v221, v66
	v_fmac_f32_e32 v19, v221, v67
	v_fmac_f32_e32 v16, v221, v64
	v_fmac_f32_e32 v17, v221, v65
	v_fmac_f32_e32 v30, v222, v66
	v_fmac_f32_e32 v31, v222, v67
	v_fmac_f32_e32 v28, v222, v64
	v_fmac_f32_e32 v29, v222, v65
	v_fmac_f32_e32 v34, v166, v66
	v_fmac_f32_e32 v35, v166, v67
	v_fmac_f32_e32 v32, v166, v64
	v_fmac_f32_e32 v33, v166, v65
	v_fmac_f32_e32 v46, v68, v66
	v_fmac_f32_e32 v47, v68, v67
	v_fmac_f32_e32 v44, v68, v64
	v_fmac_f32_e32 v45, v68, v65
	v_mov_b32_e32 v64, v163
	v_fmac_f32_e32 v6, v224, v58
	v_fmac_f32_e32 v7, v224, v59
	v_fmac_f32_e32 v4, v224, v56
	v_fmac_f32_e32 v5, v224, v57
	v_fmac_f32_e32 v18, v225, v58
	v_fmac_f32_e32 v19, v225, v59
	v_fmac_f32_e32 v16, v225, v56
	v_fmac_f32_e32 v17, v225, v57
	v_fmac_f32_e32 v30, v226, v58
	v_fmac_f32_e32 v31, v226, v59
	v_fmac_f32_e32 v28, v226, v56
	v_fmac_f32_e32 v29, v226, v57
	v_fmac_f32_e32 v34, v162, v58
	v_fmac_f32_e32 v35, v162, v59
	v_fmac_f32_e32 v32, v162, v56
	v_fmac_f32_e32 v33, v162, v57
	v_fmac_f32_e32 v46, v64, v58
	v_fmac_f32_e32 v47, v64, v59
	v_fmac_f32_e32 v44, v64, v56
	v_fmac_f32_e32 v45, v64, v57
	v_mov_b32_e32 v56, v159
	v_fmac_f32_e32 v6, v228, v42
	v_fmac_f32_e32 v7, v228, v43
	v_fmac_f32_e32 v4, v228, v40
	v_fmac_f32_e32 v5, v228, v41
	v_fmac_f32_e32 v18, v229, v42
	v_fmac_f32_e32 v19, v229, v43
	v_fmac_f32_e32 v16, v229, v40
	v_fmac_f32_e32 v17, v229, v41
	v_fmac_f32_e32 v30, v230, v42
	v_fmac_f32_e32 v31, v230, v43
	v_fmac_f32_e32 v28, v230, v40
	v_fmac_f32_e32 v29, v230, v41
	v_fmac_f32_e32 v34, v158, v42
	v_fmac_f32_e32 v35, v158, v43
	v_fmac_f32_e32 v32, v158, v40
	v_fmac_f32_e32 v33, v158, v41
	v_fma_f32 v42, v56, v42, v46
	v_fma_f32 v43, v56, v43, v47
	v_fma_f32 v40, v56, v40, v44
	v_fma_f32 v41, v56, v41, v45
	v_mov_b32_e32 v44, v155
	v_fmac_f32_e32 v6, v232, v14
	v_fmac_f32_e32 v7, v232, v15
	v_fmac_f32_e32 v4, v232, v12
	v_fmac_f32_e32 v5, v232, v13
	v_fmac_f32_e32 v18, v233, v14
	v_fmac_f32_e32 v19, v233, v15
	v_fmac_f32_e32 v16, v233, v12
	v_fmac_f32_e32 v17, v233, v13
	v_fmac_f32_e32 v30, v234, v14
	v_fmac_f32_e32 v31, v234, v15
	v_fmac_f32_e32 v28, v234, v12
	v_fmac_f32_e32 v29, v234, v13
	v_fmac_f32_e32 v34, v154, v14
	v_fmac_f32_e32 v35, v154, v15
	v_fmac_f32_e32 v32, v154, v12
	v_fmac_f32_e32 v33, v154, v13
	v_fma_f32 v14, v44, v14, v42
	v_fma_f32 v15, v44, v15, v43
	v_fma_f32 v12, v44, v12, v40
	v_fma_f32 v13, v44, v13, v41
	v_mov_b32_e32 v40, v151
	v_fmac_f32_e32 v6, v236, v2
	v_fmac_f32_e32 v7, v236, v3
	v_fmac_f32_e32 v4, v236, v0
	v_fmac_f32_e32 v5, v236, v1
	v_fmac_f32_e32 v18, v237, v2
	v_fmac_f32_e32 v19, v237, v3
	v_fmac_f32_e32 v16, v237, v0
	v_fmac_f32_e32 v17, v237, v1
	v_fmac_f32_e32 v30, v238, v2
	v_fmac_f32_e32 v31, v238, v3
	v_fmac_f32_e32 v28, v238, v0
	v_fmac_f32_e32 v29, v238, v1
	v_fmac_f32_e32 v34, v150, v2
	v_fmac_f32_e32 v35, v150, v3
	v_fmac_f32_e32 v32, v150, v0
	v_fmac_f32_e32 v33, v150, v1
	v_fma_f32 v46, v40, v2, v14
	v_fma_f32 v47, v40, v3, v15
	v_fma_f32 v44, v40, v0, v12
	v_fma_f32 v45, v40, v1, v13
.LBB0_570:
	s_add_u32 s6, s10, s40
	v_sub_f32_e32 v0, v172, v192
	s_addc_u32 s7, s11, s41
	v_exp_f32_e32 v152, v0
	v_sub_f32_e32 v0, v178, v193
	s_add_u32 s40, s6, s44
	v_exp_f32_e32 v153, v0
	v_sub_f32_e32 v0, v180, v194
	s_addc_u32 s41, s7, 0
	v_exp_f32_e32 v154, v0
	v_lshl_add_u64 v[0:1], s[40:41], 0, v[168:169]
	v_add_co_u32_e64 v2, s[6:7], s14, v0
	v_mov_b32_e32 v183, v182
	s_nop 0
	v_addc_co_u32_e64 v3, s[6:7], 0, v1, s[6:7]
	global_load_dwordx4 v[100:103], v[2:3], off offset:-4096 nt
	global_load_dwordx4 v[68:71], v[2:3], off nt
	v_add_co_u32_e64 v2, s[6:7], s15, v0
	v_sub_f32_e32 v155, v170, v195
	s_nop 0
	v_addc_co_u32_e64 v3, s[6:7], 0, v1, s[6:7]
	global_load_dwordx4 v[64:67], v[2:3], off offset:-4096 nt
	global_load_dwordx4 v[56:59], v[2:3], off nt
	v_add_co_u32_e64 v2, s[6:7], s26, v0
	v_exp_f32_e32 v155, v155
	s_nop 0
	v_addc_co_u32_e64 v3, s[6:7], 0, v1, s[6:7]
	v_add_co_u32_e64 v0, s[6:7], s27, v0
	global_load_dwordx4 v[40:43], v[2:3], off offset:-4096 nt
	global_load_dwordx4 v[12:15], v[2:3], off nt
	v_addc_co_u32_e64 v1, s[6:7], 0, v1, s[6:7]
	s_min_u32 s6, s53, 29
	global_load_dwordx4 v[108:111], v168, s[40:41] nt
	s_nop 0
	global_load_dwordx4 v[0:3], v[0:1], off nt
	s_add_i32 s40, s6, 2
	s_lshr_b32 s6, s40, 3
	s_cmp_eq_u32 s6, 2
	s_cselect_b32 s7, s47, s49
	s_cmp_eq_u32 s6, 1
	s_cselect_b32 s6, s45, s7
	s_cmp_lt_u32 s53, 6
	s_cselect_b32 s6, s22, s6
	s_ashr_i32 s7, s6, 31
	s_lshl_b32 s40, s40, 15
	s_and_b32 s56, s40, 0x38000
	s_lshl_b64 s[40:41], s[6:7], 18
	s_add_u32 s6, s8, s40
	s_addc_u32 s7, s9, s41
	s_add_u32 s54, s6, s56
	s_waitcnt lgkmcnt(0)
	s_waitcnt vmcnt(9)
	v_cvt_pk_bf16_f32 v144, v144, v145
	v_cvt_pk_bf16_f32 v145, v146, v147
	ds_write_b64 v181, v[144:145] offset:43008
	v_cvt_pk_bf16_f32 v140, v140, v141
	v_cvt_pk_bf16_f32 v141, v142, v143
	ds_write_b64 v181, v[140:141] offset:43552
	v_cvt_pk_bf16_f32 v136, v136, v137
	v_cvt_pk_bf16_f32 v137, v138, v139
	ds_write_b64 v181, v[136:137] offset:44096
	v_cvt_pk_bf16_f32 v132, v132, v133
	v_cvt_pk_bf16_f32 v133, v134, v135
	ds_write_b64 v181, v[132:133] offset:44640
	v_cvt_pk_bf16_f32 v128, v128, v129
	v_cvt_pk_bf16_f32 v129, v130, v131
	ds_write_b64 v181, v[128:129] offset:45184
	v_cvt_pk_bf16_f32 v124, v124, v125
	v_cvt_pk_bf16_f32 v125, v126, v127
	ds_write_b64 v181, v[124:125] offset:45728
	v_cvt_pk_bf16_f32 v120, v120, v121
	v_cvt_pk_bf16_f32 v121, v122, v123
	ds_write_b64 v181, v[120:121] offset:46272
	s_waitcnt vmcnt(8)
	v_cvt_pk_bf16_f32 v116, v116, v117
	v_cvt_pk_bf16_f32 v117, v118, v119
	s_addc_u32 s55, s7, 0
	ds_write_b64 v181, v[116:117] offset:46816
	v_lshl_add_u64 v[116:117], s[54:55], 0, v[168:169]
	v_add_co_u32_e64 v118, s[6:7], s14, v116
	v_readlane_b32 s46, v152, 0
	s_nop 0
	v_addc_co_u32_e64 v119, s[6:7], 0, v117, s[6:7]
	global_load_dwordx4 v[140:143], v[118:119], off offset:-4096 nt
	global_load_dwordx4 v[136:139], v[118:119], off nt
	v_add_co_u32_e64 v118, s[6:7], s15, v116
	v_readlane_b32 s44, v152, 16
	s_nop 0
	v_addc_co_u32_e64 v119, s[6:7], 0, v117, s[6:7]
	global_load_dwordx4 v[132:135], v[118:119], off offset:-4096 nt
	global_load_dwordx4 v[128:131], v[118:119], off nt
	v_add_co_u32_e64 v118, s[6:7], s26, v116
	v_readlane_b32 s52, v154, 16
	s_nop 0
	v_addc_co_u32_e64 v119, s[6:7], 0, v117, s[6:7]
	v_add_co_u32_e64 v116, s[6:7], s27, v116
	global_load_dwordx4 v[124:127], v[118:119], off offset:-4096 nt
	global_load_dwordx4 v[120:123], v[118:119], off nt
	v_addc_co_u32_e64 v117, s[6:7], 0, v117, s[6:7]
	global_load_dwordx4 v[144:147], v168, s[54:55] nt
	s_nop 0
	global_load_dwordx4 v[116:119], v[116:117], off nt
	s_or_b32 s6, s42, s16
	v_add_u32_e32 v148, s6, v179
	v_add_u32_e32 v149, -1, v148
	v_add_u32_e32 v150, -2, v148
	v_add_u32_e32 v151, -3, v148
	s_waitcnt lgkmcnt(0)
	v_cvt_f32_i32_e32 v160, v148
	v_cvt_f32_i32_e32 v161, v149
	v_cvt_f32_i32_e32 v163, v151
	v_cvt_f32_i32_e32 v162, v150
	ds_read_b128 v[148:151], v190 offset:43008
	ds_read_b128 v[156:159], v190 offset:43072
	v_mul_f32_e32 v160, v184, v160
	v_mul_f32_e32 v161, v185, v161
	v_readlane_b32 s42, v153, 0
	v_mul_f32_e32 v162, v182, v162
	v_mul_f32_e32 v163, v183, v163
	v_readlane_b32 s16, v153, 16
	v_readlane_b32 s6, v154, 0
	s_waitcnt lgkmcnt(1)
	v_mfma_f32_16x16x32_bf16 v[148:151], v[24:27], v[148:151], v[160:163]
	v_readlane_b32 s50, v155, 0
	v_readlane_b32 s48, v155, 16
	s_nop 0
	ds_read_b128 v[160:163], v190 offset:43136
	s_waitcnt lgkmcnt(1)
	v_mfma_f32_16x16x32_bf16 v[148:151], v[48:51], v[156:159], v[148:151]
	ds_read_b128 v[156:159], v190 offset:43200
	s_waitcnt lgkmcnt(1)
	v_mfma_f32_16x16x32_bf16 v[148:151], v[52:55], v[160:163], v[148:151]
	s_waitcnt lgkmcnt(0)
	v_mfma_f32_16x16x32_bf16 v[148:151], v[60:63], v[156:159], v[148:151]
	s_nop 7
	v_mov_b32_dpp v156, v148 quad_perm:[1,0,3,2] row_mask:0xf bank_mask:0xf bound_ctrl:1
	v_max_f32_e32 v157, v148, v148
	v_max_f32_e32 v156, v156, v156
	v_max_f32_e32 v156, v157, v156
	s_nop 1
	v_mov_b32_dpp v157, v156 quad_perm:[2,3,0,1] row_mask:0xf bank_mask:0xf bound_ctrl:1
	v_max_f32_e32 v157, v157, v157
	v_max_f32_e32 v156, v156, v157
	s_nop 1
	v_mov_b32_dpp v157, v156 row_half_mirror row_mask:0xf bank_mask:0xf bound_ctrl:1
	v_max_f32_e32 v157, v157, v157
	v_max_f32_e32 v156, v156, v157
	s_nop 1
	v_mov_b32_dpp v157, v156 row_ror:8 row_mask:0xf bank_mask:0xf bound_ctrl:1
	v_max3_f32 v172, v192, v156, v157
	v_mov_b32_dpp v156, v149 quad_perm:[1,0,3,2] row_mask:0xf bank_mask:0xf bound_ctrl:1
	v_max_f32_e32 v157, v149, v149
	v_max_f32_e32 v156, v156, v156
	v_max_f32_e32 v156, v157, v156
	v_sub_f32_e32 v148, v148, v172
	v_exp_f32_e32 v148, v148
	v_mov_b32_dpp v157, v156 quad_perm:[2,3,0,1] row_mask:0xf bank_mask:0xf bound_ctrl:1
	v_max_f32_e32 v157, v157, v157
	v_max_f32_e32 v156, v156, v157
	s_nop 1
	v_mov_b32_dpp v157, v156 row_half_mirror row_mask:0xf bank_mask:0xf bound_ctrl:1
	v_max_f32_e32 v157, v157, v157
	v_max_f32_e32 v156, v156, v157
	s_nop 1
	v_mov_b32_dpp v157, v156 row_ror:8 row_mask:0xf bank_mask:0xf bound_ctrl:1
	v_max3_f32 v178, v193, v156, v157
	v_mov_b32_dpp v156, v150 quad_perm:[1,0,3,2] row_mask:0xf bank_mask:0xf bound_ctrl:1
	v_max_f32_e32 v157, v150, v150
	v_max_f32_e32 v156, v156, v156
	v_max_f32_e32 v156, v157, v156
	v_sub_f32_e32 v149, v149, v178
	v_exp_f32_e32 v149, v149
	v_mov_b32_dpp v157, v156 quad_perm:[2,3,0,1] row_mask:0xf bank_mask:0xf bound_ctrl:1
	v_max_f32_e32 v157, v157, v157
	v_max_f32_e32 v156, v156, v157
	s_nop 1
	v_mov_b32_dpp v157, v156 row_half_mirror row_mask:0xf bank_mask:0xf bound_ctrl:1
	v_max_f32_e32 v157, v157, v157
	v_max_f32_e32 v156, v156, v157
	s_nop 1
	v_mov_b32_dpp v157, v156 row_ror:8 row_mask:0xf bank_mask:0xf bound_ctrl:1
	v_max3_f32 v180, v194, v156, v157
	v_mov_b32_dpp v156, v151 quad_perm:[1,0,3,2] row_mask:0xf bank_mask:0xf bound_ctrl:1
	v_max_f32_e32 v157, v151, v151
	v_max_f32_e32 v156, v156, v156
	v_max_f32_e32 v156, v157, v156
	v_sub_f32_e32 v150, v150, v180
	v_exp_f32_e32 v150, v150
	v_mov_b32_dpp v157, v156 quad_perm:[2,3,0,1] row_mask:0xf bank_mask:0xf bound_ctrl:1
	v_max_f32_e32 v157, v157, v157
	v_max_f32_e32 v156, v156, v157
	s_nop 1
	v_mov_b32_dpp v157, v156 row_half_mirror row_mask:0xf bank_mask:0xf bound_ctrl:1
	v_max_f32_e32 v157, v157, v157
	v_max_f32_e32 v156, v156, v157
	s_nop 1
	v_mov_b32_dpp v157, v156 row_ror:8 row_mask:0xf bank_mask:0xf bound_ctrl:1
	v_max3_f32 v170, v195, v156, v157
	v_sub_f32_e32 v151, v151, v170
	v_exp_f32_e32 v151, v151
	s_and_saveexec_b64 s[54:55], vcc
	ds_write_b128 v191, v[148:151] offset:35328
	s_or_b64 exec, exec, s[54:55]
	v_mul_f32_e32 v216, s46, v6
	v_mul_f32_e32 v217, s46, v7
	v_mul_f32_e32 v218, s46, v4
	v_mul_f32_e32 v219, s46, v5
	v_mul_f32_e32 v220, s44, v10
	v_mul_f32_e32 v221, s44, v11
	v_mul_f32_e32 v222, s44, v8
	v_mul_f32_e32 v223, s44, v9
	v_mul_f32_e32 v224, s42, v18
	v_mul_f32_e32 v225, s42, v19
	v_mul_f32_e32 v226, s42, v16
	v_mul_f32_e32 v227, s42, v17
	v_mul_f32_e32 v228, s16, v22
	v_mul_f32_e32 v229, s16, v23
	v_mul_f32_e32 v230, s16, v20
	v_mul_f32_e32 v231, s16, v21
	v_mul_f32_e32 v232, s6, v30
	v_mul_f32_e32 v233, s6, v31
	v_mul_f32_e32 v234, s6, v28
	v_mul_f32_e32 v235, s6, v29
	v_mul_f32_e32 v236, s52, v34
	v_mul_f32_e32 v237, s52, v35
	v_mul_f32_e32 v238, s52, v32
	v_mul_f32_e32 v239, s52, v33
	v_mul_f32_e32 v240, s50, v38
	v_mul_f32_e32 v241, s50, v39
	v_mul_f32_e32 v242, s50, v36
	v_mul_f32_e32 v243, s50, v37
	v_mul_f32_e32 v244, s48, v46
	v_mul_f32_e32 v245, s48, v47
	v_mul_f32_e32 v246, s48, v44
	v_mul_f32_e32 v247, s48, v45
	ds_read_b128 v[4:7], v173 offset:34816
	ds_read_b128 v[8:11], v173 offset:34832
	ds_read_b128 v[16:19], v173 offset:34880
	ds_read_b128 v[20:23], v173 offset:34896
	ds_read_b128 v[28:31], v173 offset:34944
	ds_read_b128 v[32:35], v173 offset:34960
	ds_read_b128 v[36:39], v173 offset:35008
	ds_read_b128 v[44:47], v173 offset:35024
	ds_read_b128 v[156:159], v173 offset:35072
	ds_read_b128 v[160:163], v173 offset:35088
	ds_read_b128 v[164:167], v173 offset:35136
	ds_read_b128 v[196:199], v173 offset:35152
	ds_read_b128 v[200:203], v173 offset:35200
	ds_read_b128 v[204:207], v173 offset:35216
	ds_read_b128 v[208:211], v173 offset:35264
	ds_read_b128 v[212:215], v173 offset:35280
	s_waitcnt lgkmcnt(14)
	v_fmac_f32_e32 v216, v4, v74
	v_fmac_f32_e32 v217, v4, v75
	v_fmac_f32_e32 v218, v4, v72
	v_fmac_f32_e32 v219, v4, v73
	v_fmac_f32_e32 v224, v5, v74
	v_fmac_f32_e32 v225, v5, v75
	v_fma_f32 v4, v5, v72, v226
	v_fma_f32 v5, v5, v73, v227
	s_waitcnt lgkmcnt(13)
	v_fmac_f32_e32 v218, v16, v80
	v_fmac_f32_e32 v219, v16, v81
	v_fmac_f32_e32 v4, v17, v80
	v_fmac_f32_e32 v5, v17, v81
	v_fmac_f32_e32 v216, v16, v82
	v_fmac_f32_e32 v217, v16, v83
	s_waitcnt lgkmcnt(11)
	v_fmac_f32_e32 v4, v29, v76
	v_fmac_f32_e32 v5, v29, v77
	v_fma_f32 v16, v17, v82, v224
	v_fma_f32 v17, v17, v83, v225
	s_waitcnt lgkmcnt(9)
	v_fmac_f32_e32 v4, v37, v88
	v_fmac_f32_e32 v5, v37, v89
	v_fmac_f32_e32 v216, v28, v78
	v_fmac_f32_e32 v217, v28, v79
	s_waitcnt lgkmcnt(7)
	v_fmac_f32_e32 v4, v157, v84
	v_fmac_f32_e32 v5, v157, v85
	v_fmac_f32_e32 v218, v28, v76
	v_fmac_f32_e32 v219, v28, v77
	s_waitcnt lgkmcnt(5)
	v_fmac_f32_e32 v4, v165, v96
	v_fmac_f32_e32 v5, v165, v97
	v_fmac_f32_e32 v16, v29, v78
	v_fmac_f32_e32 v17, v29, v79
	s_waitcnt lgkmcnt(3)
	v_fmac_f32_e32 v4, v201, v92
	v_fmac_f32_e32 v5, v201, v93
	v_fmac_f32_e32 v220, v8, v74
	v_fmac_f32_e32 v221, v8, v75
	s_waitcnt lgkmcnt(1)
	v_fma_f32 v28, v209, v104, v4
	v_fma_f32 v29, v209, v105, v5
	v_fma_f32 v4, v9, v74, v228
	v_fma_f32 v5, v9, v75, v229
	v_fmac_f32_e32 v222, v8, v72
	v_fmac_f32_e32 v223, v8, v73
	v_fma_f32 v8, v9, v72, v230
	v_fma_f32 v9, v9, v73, v231
	v_fmac_f32_e32 v4, v21, v82
	v_fmac_f32_e32 v5, v21, v83
	v_fmac_f32_e32 v8, v21, v80
	v_fmac_f32_e32 v9, v21, v81
	v_fmac_f32_e32 v4, v33, v78
	v_fmac_f32_e32 v5, v33, v79
	v_fmac_f32_e32 v8, v33, v76
	v_fmac_f32_e32 v9, v33, v77
	v_fmac_f32_e32 v4, v45, v90
	v_fmac_f32_e32 v5, v45, v91
	v_fmac_f32_e32 v8, v45, v88
	v_fmac_f32_e32 v9, v45, v89
	v_fmac_f32_e32 v4, v161, v86
	v_fmac_f32_e32 v5, v161, v87
	v_fmac_f32_e32 v8, v161, v84
	v_fmac_f32_e32 v9, v161, v85
	v_fmac_f32_e32 v4, v197, v98
	v_fmac_f32_e32 v5, v197, v99
	v_fmac_f32_e32 v222, v20, v80
	v_fmac_f32_e32 v223, v20, v81
	v_fmac_f32_e32 v220, v20, v82
	v_fmac_f32_e32 v221, v20, v83
	v_fmac_f32_e32 v8, v197, v96
	v_fmac_f32_e32 v9, v197, v97
	v_fmac_f32_e32 v4, v205, v94
	v_fmac_f32_e32 v5, v205, v95
	v_fmac_f32_e32 v220, v32, v78
	v_fmac_f32_e32 v221, v32, v79
	v_fmac_f32_e32 v222, v32, v76
	v_fmac_f32_e32 v223, v32, v77
	v_fmac_f32_e32 v8, v205, v92
	v_fmac_f32_e32 v9, v205, v93
	s_waitcnt lgkmcnt(0)
	v_fma_f32 v32, v213, v106, v4
	v_fma_f32 v33, v213, v107, v5
	v_fma_f32 v4, v6, v74, v232
	v_fma_f32 v5, v6, v75, v233
	v_fma_f32 v20, v213, v104, v8
	v_fma_f32 v21, v213, v105, v9
	v_fma_f32 v8, v6, v72, v234
	v_fma_f32 v9, v6, v73, v235
	v_fmac_f32_e32 v4, v18, v82
	v_fmac_f32_e32 v5, v18, v83
	v_fmac_f32_e32 v8, v18, v80
	v_fmac_f32_e32 v9, v18, v81
	v_fmac_f32_e32 v4, v30, v78
	v_fmac_f32_e32 v5, v30, v79
	v_fmac_f32_e32 v8, v30, v76
	v_fmac_f32_e32 v9, v30, v77
	v_fmac_f32_e32 v4, v38, v90
	v_fmac_f32_e32 v5, v38, v91
	v_fmac_f32_e32 v8, v38, v88
	v_fmac_f32_e32 v9, v38, v89
	v_fmac_f32_e32 v4, v158, v86
	v_fmac_f32_e32 v5, v158, v87
	v_fmac_f32_e32 v8, v158, v84
	v_fmac_f32_e32 v9, v158, v85
	v_fmac_f32_e32 v4, v166, v98
	v_fmac_f32_e32 v5, v166, v99
	v_fmac_f32_e32 v8, v166, v96
	v_fmac_f32_e32 v9, v166, v97
	v_fmac_f32_e32 v4, v202, v94
	v_fmac_f32_e32 v5, v202, v95
	v_fmac_f32_e32 v222, v44, v88
	v_fmac_f32_e32 v223, v44, v89
	v_fmac_f32_e32 v220, v44, v90
	v_fmac_f32_e32 v221, v44, v91
	v_fmac_f32_e32 v8, v202, v92
	v_fmac_f32_e32 v9, v202, v93
	v_fma_f32 v44, v210, v106, v4
	v_fma_f32 v45, v210, v107, v5
	v_fma_f32 v4, v10, v74, v236
	v_fma_f32 v5, v10, v75, v237
	v_fmac_f32_e32 v218, v36, v88
	v_fmac_f32_e32 v219, v36, v89
	v_fmac_f32_e32 v216, v36, v90
	v_fmac_f32_e32 v217, v36, v91
	v_fmac_f32_e32 v16, v37, v90
	v_fmac_f32_e32 v17, v37, v91
	v_fma_f32 v36, v210, v104, v8
	v_fma_f32 v37, v210, v105, v9
	v_fma_f32 v8, v10, v72, v238
	v_fma_f32 v9, v10, v73, v239
	v_fmac_f32_e32 v4, v22, v82
	v_fmac_f32_e32 v5, v22, v83
	v_fmac_f32_e32 v8, v22, v80
	v_fmac_f32_e32 v9, v22, v81
	v_fmac_f32_e32 v4, v34, v78
	v_fmac_f32_e32 v5, v34, v79
	v_fmac_f32_e32 v8, v34, v76
	v_fmac_f32_e32 v9, v34, v77
	v_fmac_f32_e32 v4, v46, v90
	v_fmac_f32_e32 v5, v46, v91
	v_fmac_f32_e32 v8, v46, v88
	v_fmac_f32_e32 v9, v46, v89
	v_fmac_f32_e32 v4, v162, v86
	v_fmac_f32_e32 v5, v162, v87
	v_fmac_f32_e32 v8, v162, v84
	v_fmac_f32_e32 v9, v162, v85
	v_fmac_f32_e32 v4, v198, v98
	v_fmac_f32_e32 v5, v198, v99
	v_fmac_f32_e32 v8, v198, v96
	v_fmac_f32_e32 v9, v198, v97
	v_fmac_f32_e32 v4, v206, v94
	v_fmac_f32_e32 v5, v206, v95
	v_fmac_f32_e32 v220, v160, v86
	v_fmac_f32_e32 v221, v160, v87
	v_fmac_f32_e32 v222, v160, v84
	v_fmac_f32_e32 v223, v160, v85
	v_fmac_f32_e32 v8, v206, v92
	v_fmac_f32_e32 v9, v206, v93
	v_fma_f32 v160, v214, v106, v4
	v_fma_f32 v161, v214, v107, v5
	v_mov_b32_e32 v4, v7
	v_fmac_f32_e32 v216, v156, v86
	v_fmac_f32_e32 v217, v156, v87
	v_fmac_f32_e32 v218, v156, v84
	v_fmac_f32_e32 v219, v156, v85
	v_fmac_f32_e32 v16, v157, v86
	v_fmac_f32_e32 v17, v157, v87
	v_fma_f32 v156, v214, v104, v8
	v_fma_f32 v157, v214, v105, v9
	v_fma_f32 v6, v4, v74, v240
	v_fma_f32 v7, v4, v75, v241
	v_fma_f32 v5, v4, v73, v243
	v_fma_f32 v4, v4, v72, v242
	v_mov_b32_e32 v8, v19
	v_fmac_f32_e32 v4, v8, v80
	v_fmac_f32_e32 v5, v8, v81
	v_fmac_f32_e32 v6, v8, v82
	v_fmac_f32_e32 v7, v8, v83
	v_mov_b32_e32 v8, v31
	v_fmac_f32_e32 v6, v8, v78
	v_fmac_f32_e32 v7, v8, v79
	v_fmac_f32_e32 v4, v8, v76
	v_fmac_f32_e32 v5, v8, v77
	v_mov_b32_e32 v8, v39
	v_fmac_f32_e32 v4, v8, v88
	v_fmac_f32_e32 v5, v8, v89
	v_fmac_f32_e32 v6, v8, v90
	v_fmac_f32_e32 v7, v8, v91
	v_mov_b32_e32 v8, v159
	v_fmac_f32_e32 v6, v8, v86
	v_fmac_f32_e32 v7, v8, v87
	v_fmac_f32_e32 v4, v8, v84
	v_fmac_f32_e32 v5, v8, v85
	v_mov_b32_e32 v8, v167
	v_fmac_f32_e32 v4, v8, v96
	v_fmac_f32_e32 v5, v8, v97
	v_fmac_f32_e32 v6, v8, v98
	v_fmac_f32_e32 v7, v8, v99
	v_mov_b32_e32 v8, v203
	v_fmac_f32_e32 v6, v8, v94
	v_fmac_f32_e32 v7, v8, v95
	v_fmac_f32_e32 v4, v8, v92
	v_fmac_f32_e32 v5, v8, v93
	v_mov_b32_e32 v8, v211
	v_fma_f32 v158, v8, v104, v4
	v_fma_f32 v159, v8, v105, v5
	v_mov_b32_e32 v4, v11
	v_fma_f32 v38, v8, v106, v6
	v_fma_f32 v39, v8, v107, v7
	v_fma_f32 v6, v4, v74, v244
	v_fma_f32 v7, v4, v75, v245
	v_fma_f32 v5, v4, v73, v247
	v_fma_f32 v4, v4, v72, v246
	v_mov_b32_e32 v8, v23
	v_fmac_f32_e32 v4, v8, v80
	v_fmac_f32_e32 v5, v8, v81
	v_fmac_f32_e32 v6, v8, v82
	v_fmac_f32_e32 v7, v8, v83
	v_mov_b32_e32 v8, v35
	v_fmac_f32_e32 v6, v8, v78
	v_fmac_f32_e32 v7, v8, v79
	v_fmac_f32_e32 v4, v8, v76
	v_fmac_f32_e32 v5, v8, v77
	v_mov_b32_e32 v8, v47
	v_fmac_f32_e32 v4, v8, v88
	v_fmac_f32_e32 v5, v8, v89
	v_fmac_f32_e32 v6, v8, v90
	v_fmac_f32_e32 v7, v8, v91
	v_mov_b32_e32 v8, v163
	s_add_u32 s6, s10, s40
	v_fmac_f32_e32 v6, v8, v86
	v_fmac_f32_e32 v7, v8, v87
	v_fmac_f32_e32 v4, v8, v84
	v_fmac_f32_e32 v5, v8, v85
	v_mov_b32_e32 v8, v199
	s_addc_u32 s7, s11, s41
	v_fmac_f32_e32 v4, v8, v96
	v_fmac_f32_e32 v5, v8, v97
	v_fmac_f32_e32 v6, v8, v98
	v_fmac_f32_e32 v7, v8, v99
	v_mov_b32_e32 v8, v207
	s_add_u32 s40, s6, s56
	v_fmac_f32_e32 v6, v8, v94
	v_fmac_f32_e32 v7, v8, v95
	v_fmac_f32_e32 v4, v8, v92
	v_fmac_f32_e32 v5, v8, v93
	v_mov_b32_e32 v8, v215
	s_addc_u32 s41, s7, 0
	v_fma_f32 v162, v8, v104, v4
	v_fma_f32 v163, v8, v105, v5
	v_lshl_add_u64 v[4:5], s[40:41], 0, v[168:169]
	v_fma_f32 v46, v8, v106, v6
	v_fma_f32 v47, v8, v107, v7
	v_add_co_u32_e64 v6, s[6:7], s14, v4
	v_fmac_f32_e32 v218, v164, v96
	v_fmac_f32_e32 v219, v164, v97
	s_nop 0
	v_addc_co_u32_e64 v7, s[6:7], 0, v5, s[6:7]
	global_load_dwordx4 v[80:83], v[6:7], off offset:-4096 nt
	global_load_dwordx4 v[76:79], v[6:7], off nt
	v_add_co_u32_e64 v6, s[6:7], s15, v4
	v_fmac_f32_e32 v216, v164, v98
	v_fmac_f32_e32 v217, v164, v99
	s_nop 0
	v_addc_co_u32_e64 v7, s[6:7], 0, v5, s[6:7]
	global_load_dwordx4 v[88:91], v[6:7], off offset:-4096 nt
	global_load_dwordx4 v[84:87], v[6:7], off nt
	v_add_co_u32_e64 v6, s[6:7], s26, v4
	v_fmac_f32_e32 v222, v196, v96
	v_fmac_f32_e32 v223, v196, v97
	v_fmac_f32_e32 v220, v196, v98
	v_fmac_f32_e32 v221, v196, v99
	v_fmac_f32_e32 v16, v165, v98
	v_fmac_f32_e32 v17, v165, v99
	v_addc_co_u32_e64 v7, s[6:7], 0, v5, s[6:7]
	v_fmac_f32_e32 v216, v200, v94
	v_fmac_f32_e32 v217, v200, v95
	v_fmac_f32_e32 v218, v200, v92
	v_fmac_f32_e32 v219, v200, v93
	v_fmac_f32_e32 v220, v204, v94
	v_fmac_f32_e32 v221, v204, v95
	v_fmac_f32_e32 v222, v204, v92
	v_fmac_f32_e32 v223, v204, v93
	v_fmac_f32_e32 v16, v201, v94
	v_fmac_f32_e32 v17, v201, v95
	v_add_co_u32_e64 v4, s[6:7], s27, v4
	v_fmac_f32_e32 v218, v208, v104
	v_fmac_f32_e32 v219, v208, v105
	v_fmac_f32_e32 v216, v208, v106
	v_fmac_f32_e32 v217, v208, v107
	v_fmac_f32_e32 v222, v212, v104
	v_fmac_f32_e32 v223, v212, v105
	v_fmac_f32_e32 v220, v212, v106
	v_fmac_f32_e32 v221, v212, v107
	v_fmac_f32_e32 v16, v209, v106
	v_fmac_f32_e32 v17, v209, v107
	global_load_dwordx4 v[96:99], v[6:7], off offset:-4096 nt
	global_load_dwordx4 v[92:95], v[6:7], off nt
	v_addc_co_u32_e64 v5, s[6:7], 0, v5, s[6:7]
	global_load_dwordx4 v[72:75], v168, s[40:41] nt
	global_load_dwordx4 v[104:107], v[4:5], off nt
	v_sub_f32_e32 v4, v192, v172
	v_exp_f32_e32 v18, v4
	v_sub_f32_e32 v4, v193, v178
	v_exp_f32_e32 v19, v4
	v_sub_f32_e32 v4, v194, v180
	v_exp_f32_e32 v164, v4
	v_sub_f32_e32 v4, v195, v170
	v_exp_f32_e32 v165, v4
	v_fma_f32 v4, v174, v152, v112
	v_fma_f32 v5, v175, v153, v113
	v_fma_f32 v6, v176, v154, v114
	v_fma_f32 v7, v177, v155, v115
	v_readlane_b32 s6, v18, 0
	v_fma_f32 v174, v4, v18, v148
	v_fma_f32 v175, v5, v19, v149
	v_fma_f32 v176, v6, v164, v150
	v_fma_f32 v177, v7, v165, v151
	v_readlane_b32 s16, v18, 16
	v_mul_f32_e32 v6, s6, v216
	v_mul_f32_e32 v7, s6, v217
	v_mul_f32_e32 v4, s6, v218
	v_mul_f32_e32 v5, s6, v219
	v_readlane_b32 s6, v19, 0
	v_mul_f32_e32 v10, s16, v220
	v_mul_f32_e32 v11, s16, v221
	v_mul_f32_e32 v8, s16, v222
	v_mul_f32_e32 v9, s16, v223
	v_readlane_b32 s16, v19, 16
	v_mul_f32_e32 v18, s6, v16
	v_mul_f32_e32 v19, s6, v17
	v_mul_f32_e32 v16, s6, v28
	v_mul_f32_e32 v17, s6, v29
	v_readlane_b32 s6, v164, 0
	v_mul_f32_e32 v22, s16, v32
	v_mul_f32_e32 v23, s16, v33
	v_mul_f32_e32 v20, s16, v20
	v_mul_f32_e32 v21, s16, v21
	v_readlane_b32 s16, v164, 16
	v_mul_f32_e32 v30, s6, v44
	v_mul_f32_e32 v31, s6, v45
	v_mul_f32_e32 v28, s6, v36
	v_mul_f32_e32 v29, s6, v37
	v_readlane_b32 s6, v165, 0
	s_waitcnt lgkmcnt(0)
	v_mul_f32_e32 v34, s16, v160
	v_mul_f32_e32 v35, s16, v161
	v_mul_f32_e32 v32, s16, v156
	v_mul_f32_e32 v33, s16, v157
	v_readlane_b32 s16, v165, 16
	v_mul_f32_e32 v38, s6, v38
	v_mul_f32_e32 v39, s6, v39
	v_mul_f32_e32 v36, s6, v158
	v_mul_f32_e32 v37, s6, v159
	s_add_i32 s6, s53, 2
	s_add_i32 s51, s51, 32
	v_mul_f32_e32 v46, s16, v46
	v_mul_f32_e32 v47, s16, v47
	v_mul_f32_e32 v44, s16, v162
	v_mul_f32_e32 v45, s16, v163
	s_cmp_gt_u32 s53, 29
	s_cbranch_scc1 .LBB0_574
	s_mov_b32 s53, s6
	s_branch .LBB0_566
.LBB0_574:
	ds_read_b128 v[24:27], v173 offset:35328
	ds_read_b128 v[48:51], v173 offset:35344
	s_waitcnt vmcnt(17) lgkmcnt(1)
	v_fma_f32 v4, v24, v108, v4
	v_fmac_f32_e32 v5, v24, v109
	v_fma_f32 v6, v24, v110, v6
	v_fmac_f32_e32 v7, v24, v111
	s_waitcnt lgkmcnt(0)
	v_fma_f32 v8, v48, v108, v8
	v_fmac_f32_e32 v9, v48, v109
	v_fma_f32 v10, v48, v110, v10
	v_fmac_f32_e32 v11, v48, v111
	v_fma_f32 v16, v25, v108, v16
	v_fmac_f32_e32 v17, v25, v109
	v_fma_f32 v18, v25, v110, v18
	v_fmac_f32_e32 v19, v25, v111
	v_fma_f32 v20, v49, v108, v20
	v_fmac_f32_e32 v21, v49, v109
	v_fma_f32 v22, v49, v110, v22
	v_fmac_f32_e32 v23, v49, v111
	v_fma_f32 v28, v26, v108, v28
	v_fmac_f32_e32 v29, v26, v109
	v_fma_f32 v30, v26, v110, v30
	v_fmac_f32_e32 v31, v26, v111
	v_fma_f32 v32, v50, v108, v32
	v_fmac_f32_e32 v33, v50, v109
	v_fma_f32 v34, v50, v110, v34
	v_fmac_f32_e32 v35, v50, v111
	v_fma_f32 v36, v27, v108, v36
	v_fmac_f32_e32 v37, v27, v109
	v_fma_f32 v38, v27, v110, v38
	v_fmac_f32_e32 v39, v27, v111
	v_fma_f32 v44, v51, v108, v44
	ds_read_b128 v[24:27], v173 offset:35392
	v_fmac_f32_e32 v45, v51, v109
	v_fma_f32 v46, v51, v110, v46
	v_fmac_f32_e32 v47, v51, v111
	ds_read_b128 v[48:51], v173 offset:35408
	s_waitcnt lgkmcnt(1)
	v_fmac_f32_e32 v4, v24, v100
	v_fmac_f32_e32 v5, v24, v101
	v_fmac_f32_e32 v6, v24, v102
	v_fmac_f32_e32 v7, v24, v103
	s_waitcnt lgkmcnt(0)
	v_fmac_f32_e32 v8, v48, v100
	v_fmac_f32_e32 v9, v48, v101
	v_fmac_f32_e32 v10, v48, v102
	v_fmac_f32_e32 v11, v48, v103
	v_fmac_f32_e32 v16, v25, v100
	v_fmac_f32_e32 v17, v25, v101
	v_fmac_f32_e32 v18, v25, v102
	v_fmac_f32_e32 v19, v25, v103
	v_fmac_f32_e32 v20, v49, v100
	v_fmac_f32_e32 v21, v49, v101
	v_fmac_f32_e32 v22, v49, v102
	v_fmac_f32_e32 v23, v49, v103
	v_fmac_f32_e32 v28, v26, v100
	v_fmac_f32_e32 v29, v26, v101
	v_fmac_f32_e32 v30, v26, v102
	v_fmac_f32_e32 v31, v26, v103
	v_fmac_f32_e32 v32, v50, v100
	v_fmac_f32_e32 v33, v50, v101
	v_fmac_f32_e32 v34, v50, v102
	v_fmac_f32_e32 v35, v50, v103
	v_fmac_f32_e32 v36, v27, v100
	v_fmac_f32_e32 v37, v27, v101
	v_fmac_f32_e32 v38, v27, v102
	v_fmac_f32_e32 v39, v27, v103
	v_fmac_f32_e32 v44, v51, v100
	ds_read_b128 v[24:27], v173 offset:35456
	v_fmac_f32_e32 v45, v51, v101
	v_fmac_f32_e32 v46, v51, v102
	v_fmac_f32_e32 v47, v51, v103
	ds_read_b128 v[48:51], v173 offset:35472
	s_waitcnt lgkmcnt(1)
	v_fmac_f32_e32 v4, v24, v68
	v_fmac_f32_e32 v5, v24, v69
	v_fmac_f32_e32 v6, v24, v70
	v_fmac_f32_e32 v7, v24, v71
	s_waitcnt lgkmcnt(0)
	v_fmac_f32_e32 v8, v48, v68
	v_fmac_f32_e32 v9, v48, v69
	v_fmac_f32_e32 v10, v48, v70
	v_fmac_f32_e32 v11, v48, v71
	v_fmac_f32_e32 v16, v25, v68
	v_fmac_f32_e32 v17, v25, v69
	v_fmac_f32_e32 v18, v25, v70
	v_fmac_f32_e32 v19, v25, v71
	v_fmac_f32_e32 v20, v49, v68
	v_fmac_f32_e32 v21, v49, v69
	v_fmac_f32_e32 v22, v49, v70
	v_fmac_f32_e32 v23, v49, v71
	v_fmac_f32_e32 v28, v26, v68
	v_fmac_f32_e32 v29, v26, v69
	v_fmac_f32_e32 v30, v26, v70
	v_fmac_f32_e32 v31, v26, v71
	v_fmac_f32_e32 v32, v50, v68
	v_fmac_f32_e32 v33, v50, v69
	v_fmac_f32_e32 v34, v50, v70
	v_fmac_f32_e32 v35, v50, v71
	v_fmac_f32_e32 v36, v27, v68
	v_fmac_f32_e32 v37, v27, v69
	v_fmac_f32_e32 v38, v27, v70
	v_fmac_f32_e32 v39, v27, v71
	v_fmac_f32_e32 v44, v51, v68
	ds_read_b128 v[24:27], v173 offset:35520
	v_fmac_f32_e32 v45, v51, v69
	v_fmac_f32_e32 v46, v51, v70
	v_fmac_f32_e32 v47, v51, v71
	ds_read_b128 v[48:51], v173 offset:35536
	s_waitcnt lgkmcnt(1)
	v_fmac_f32_e32 v4, v24, v64
	v_fmac_f32_e32 v5, v24, v65
	v_fmac_f32_e32 v6, v24, v66
	v_fmac_f32_e32 v7, v24, v67
	s_waitcnt lgkmcnt(0)
	v_fmac_f32_e32 v8, v48, v64
	v_fmac_f32_e32 v9, v48, v65
	v_fmac_f32_e32 v10, v48, v66
	v_fmac_f32_e32 v11, v48, v67
	v_fmac_f32_e32 v16, v25, v64
	v_fmac_f32_e32 v17, v25, v65
	v_fmac_f32_e32 v18, v25, v66
	v_fmac_f32_e32 v19, v25, v67
	v_fmac_f32_e32 v20, v49, v64
	v_fmac_f32_e32 v21, v49, v65
	v_fmac_f32_e32 v22, v49, v66
	v_fmac_f32_e32 v23, v49, v67
	v_fmac_f32_e32 v28, v26, v64
	v_fmac_f32_e32 v29, v26, v65
	v_fmac_f32_e32 v30, v26, v66
	v_fmac_f32_e32 v31, v26, v67
	v_fmac_f32_e32 v32, v50, v64
	v_fmac_f32_e32 v33, v50, v65
	v_fmac_f32_e32 v34, v50, v66
	v_fmac_f32_e32 v35, v50, v67
	v_fmac_f32_e32 v36, v27, v64
	v_fmac_f32_e32 v37, v27, v65
	v_fmac_f32_e32 v38, v27, v66
	v_fmac_f32_e32 v39, v27, v67
	v_fmac_f32_e32 v44, v51, v64
	ds_read_b128 v[24:27], v173 offset:35584
	v_fmac_f32_e32 v45, v51, v65
	v_fmac_f32_e32 v46, v51, v66
	v_fmac_f32_e32 v47, v51, v67
	ds_read_b128 v[48:51], v173 offset:35600
	s_waitcnt lgkmcnt(1)
	v_fmac_f32_e32 v4, v24, v56
	v_fmac_f32_e32 v5, v24, v57
	v_fmac_f32_e32 v6, v24, v58
	v_fmac_f32_e32 v7, v24, v59
	s_waitcnt lgkmcnt(0)
	v_fmac_f32_e32 v8, v48, v56
	v_fmac_f32_e32 v9, v48, v57
	v_fmac_f32_e32 v10, v48, v58
	v_fmac_f32_e32 v11, v48, v59
	v_fmac_f32_e32 v16, v25, v56
	v_fmac_f32_e32 v17, v25, v57
	v_fmac_f32_e32 v18, v25, v58
	v_fmac_f32_e32 v19, v25, v59
	v_fmac_f32_e32 v20, v49, v56
	v_fmac_f32_e32 v21, v49, v57
	v_fmac_f32_e32 v22, v49, v58
	v_fmac_f32_e32 v23, v49, v59
	v_fmac_f32_e32 v28, v26, v56
	v_fmac_f32_e32 v29, v26, v57
	v_fmac_f32_e32 v30, v26, v58
	v_fmac_f32_e32 v31, v26, v59
	v_fmac_f32_e32 v32, v50, v56
	v_fmac_f32_e32 v33, v50, v57
	v_fmac_f32_e32 v34, v50, v58
	v_fmac_f32_e32 v35, v50, v59
	v_fmac_f32_e32 v36, v27, v56
	v_fmac_f32_e32 v37, v27, v57
	v_fmac_f32_e32 v38, v27, v58
	v_fmac_f32_e32 v39, v27, v59
	v_fmac_f32_e32 v44, v51, v56
	ds_read_b128 v[24:27], v173 offset:35648
	v_fmac_f32_e32 v45, v51, v57
	v_fmac_f32_e32 v46, v51, v58
	v_fmac_f32_e32 v47, v51, v59
	ds_read_b128 v[48:51], v173 offset:35664
	s_waitcnt lgkmcnt(1)
	v_fmac_f32_e32 v4, v24, v40
	v_fmac_f32_e32 v5, v24, v41
	v_fmac_f32_e32 v6, v24, v42
	v_fmac_f32_e32 v7, v24, v43
	s_waitcnt lgkmcnt(0)
	v_fmac_f32_e32 v8, v48, v40
	v_fmac_f32_e32 v9, v48, v41
	v_fmac_f32_e32 v10, v48, v42
	v_fmac_f32_e32 v11, v48, v43
	v_fmac_f32_e32 v16, v25, v40
	v_fmac_f32_e32 v17, v25, v41
	v_fmac_f32_e32 v18, v25, v42
	v_fmac_f32_e32 v19, v25, v43
	v_fmac_f32_e32 v20, v49, v40
	v_fmac_f32_e32 v21, v49, v41
	v_fmac_f32_e32 v22, v49, v42
	v_fmac_f32_e32 v23, v49, v43
	v_fmac_f32_e32 v28, v26, v40
	v_fmac_f32_e32 v29, v26, v41
	v_fmac_f32_e32 v30, v26, v42
	v_fmac_f32_e32 v31, v26, v43
	v_fmac_f32_e32 v32, v50, v40
	v_fmac_f32_e32 v33, v50, v41
	v_fmac_f32_e32 v34, v50, v42
	v_fmac_f32_e32 v35, v50, v43
	v_fmac_f32_e32 v36, v27, v40
	v_fmac_f32_e32 v37, v27, v41
	v_fmac_f32_e32 v38, v27, v42
	v_fmac_f32_e32 v39, v27, v43
	v_fmac_f32_e32 v44, v51, v40
	ds_read_b128 v[24:27], v173 offset:35712
	v_fmac_f32_e32 v45, v51, v41
	v_fmac_f32_e32 v46, v51, v42
	v_fmac_f32_e32 v47, v51, v43
	ds_read_b128 v[40:43], v173 offset:35728
	s_waitcnt lgkmcnt(1)
	v_fmac_f32_e32 v4, v24, v12
	v_fmac_f32_e32 v5, v24, v13
	v_fmac_f32_e32 v6, v24, v14
	v_fmac_f32_e32 v7, v24, v15
	s_waitcnt lgkmcnt(0)
	v_fmac_f32_e32 v8, v40, v12
	v_fmac_f32_e32 v9, v40, v13
	v_fmac_f32_e32 v10, v40, v14
	v_fmac_f32_e32 v11, v40, v15
	v_fmac_f32_e32 v16, v25, v12
	v_fmac_f32_e32 v17, v25, v13
	v_fmac_f32_e32 v18, v25, v14
	v_fmac_f32_e32 v19, v25, v15
	v_fmac_f32_e32 v20, v41, v12
	v_fmac_f32_e32 v21, v41, v13
	v_fmac_f32_e32 v22, v41, v14
	v_fmac_f32_e32 v23, v41, v15
	v_fmac_f32_e32 v28, v26, v12
	v_fmac_f32_e32 v29, v26, v13
	v_fmac_f32_e32 v30, v26, v14
	v_fmac_f32_e32 v31, v26, v15
	v_fmac_f32_e32 v32, v42, v12
	v_fmac_f32_e32 v33, v42, v13
	v_fmac_f32_e32 v34, v42, v14
	v_fmac_f32_e32 v35, v42, v15
	v_fmac_f32_e32 v36, v27, v12
	v_fmac_f32_e32 v37, v27, v13
	v_fmac_f32_e32 v38, v27, v14
	v_fmac_f32_e32 v39, v27, v15
	v_fmac_f32_e32 v44, v43, v12
	ds_read_b128 v[24:27], v173 offset:35776
	v_fmac_f32_e32 v45, v43, v13
	v_fmac_f32_e32 v46, v43, v14
	v_fmac_f32_e32 v47, v43, v15
	ds_read_b128 v[12:15], v173 offset:35792
	s_waitcnt vmcnt(16) lgkmcnt(1)
	v_fmac_f32_e32 v4, v24, v0
	v_fmac_f32_e32 v5, v24, v1
	v_fmac_f32_e32 v6, v24, v2
	v_fmac_f32_e32 v7, v24, v3
	s_waitcnt lgkmcnt(0)
	v_fmac_f32_e32 v8, v12, v0
	v_fmac_f32_e32 v16, v25, v0
	v_fmac_f32_e32 v20, v13, v0
	v_fmac_f32_e32 v28, v26, v0
	v_fmac_f32_e32 v32, v14, v0
	v_fmac_f32_e32 v36, v27, v0
	v_fmac_f32_e32 v44, v15, v0
	v_add_f32_dpp v0, v174, v174 quad_perm:[1,0,3,2] row_mask:0xf bank_mask:0xf bound_ctrl:1
	v_add_f32_dpp v24, v175, v175 quad_perm:[1,0,3,2] row_mask:0xf bank_mask:0xf bound_ctrl:1
	v_add_f32_dpp v48, v176, v176 quad_perm:[1,0,3,2] row_mask:0xf bank_mask:0xf bound_ctrl:1
	v_add_f32_dpp v56, v177, v177 quad_perm:[1,0,3,2] row_mask:0xf bank_mask:0xf bound_ctrl:1
	v_fmac_f32_e32 v9, v12, v1
	v_fmac_f32_e32 v10, v12, v2
	v_fmac_f32_e32 v11, v12, v3
	v_fmac_f32_e32 v17, v25, v1
	v_fmac_f32_e32 v18, v25, v2
	v_fmac_f32_e32 v19, v25, v3
	v_fmac_f32_e32 v21, v13, v1
	v_fmac_f32_e32 v22, v13, v2
	v_fmac_f32_e32 v23, v13, v3
	v_fmac_f32_e32 v29, v26, v1
	v_fmac_f32_e32 v30, v26, v2
	v_fmac_f32_e32 v31, v26, v3
	v_fmac_f32_e32 v33, v14, v1
	v_fmac_f32_e32 v34, v14, v2
	v_fmac_f32_e32 v35, v14, v3
	v_fmac_f32_e32 v37, v27, v1
	v_fmac_f32_e32 v38, v27, v2
	v_fmac_f32_e32 v39, v27, v3
	v_fmac_f32_e32 v45, v15, v1
	v_fmac_f32_e32 v46, v15, v2
	v_fmac_f32_e32 v47, v15, v3
	v_add_f32_dpp v0, v0, v0 quad_perm:[2,3,0,1] row_mask:0xf bank_mask:0xf bound_ctrl:1
	v_add_f32_dpp v24, v24, v24 quad_perm:[2,3,0,1] row_mask:0xf bank_mask:0xf bound_ctrl:1
	v_add_f32_dpp v48, v48, v48 quad_perm:[2,3,0,1] row_mask:0xf bank_mask:0xf bound_ctrl:1
	v_add_f32_dpp v56, v56, v56 quad_perm:[2,3,0,1] row_mask:0xf bank_mask:0xf bound_ctrl:1
	v_add_f32_dpp v64, v0, v0 row_half_mirror row_mask:0xf bank_mask:0xf bound_ctrl:1
	v_mov_b32_e32 v0, v4
	v_mov_b32_e32 v1, v5
	v_mov_b32_e32 v2, v6
	v_mov_b32_e32 v3, v7
	v_mov_b32_e32 v12, v8
	v_mov_b32_e32 v13, v9
	v_mov_b32_e32 v14, v10
	v_mov_b32_e32 v15, v11
	v_add_f32_dpp v66, v24, v24 row_half_mirror row_mask:0xf bank_mask:0xf bound_ctrl:1
	v_mov_b32_e32 v24, v16
	v_mov_b32_e32 v25, v17
	v_mov_b32_e32 v26, v18
	v_mov_b32_e32 v27, v19
	v_mov_b32_e32 v40, v20
	v_mov_b32_e32 v41, v21
	v_mov_b32_e32 v42, v22
	v_mov_b32_e32 v43, v23
	v_add_f32_dpp v68, v48, v48 row_half_mirror row_mask:0xf bank_mask:0xf bound_ctrl:1
	v_mov_b32_e32 v48, v28
	v_mov_b32_e32 v49, v29
	v_mov_b32_e32 v50, v30
	v_mov_b32_e32 v51, v31
	v_mov_b32_e32 v52, v32
	v_mov_b32_e32 v53, v33
	v_mov_b32_e32 v54, v34
	v_mov_b32_e32 v55, v35
	v_add_f32_dpp v70, v56, v56 row_half_mirror row_mask:0xf bank_mask:0xf bound_ctrl:1
	v_mov_b32_e32 v56, v36
	v_mov_b32_e32 v57, v37
	v_mov_b32_e32 v58, v38
	v_mov_b32_e32 v59, v39
	v_mov_b32_e32 v60, v44
	v_mov_b32_e32 v61, v45
	v_mov_b32_e32 v62, v46
	v_mov_b32_e32 v63, v47
	v_mov_b32_dpp v65, v64 row_ror:8 row_mask:0xf bank_mask:0xf bound_ctrl:1
	v_permlane32_swap_b32_e32 v4, v0
	v_permlane32_swap_b32_e32 v5, v1
	v_permlane32_swap_b32_e32 v6, v2
	v_permlane32_swap_b32_e32 v7, v3
	v_permlane32_swap_b32_e32 v8, v12
	v_permlane32_swap_b32_e32 v9, v13
	v_permlane32_swap_b32_e32 v10, v14
	v_permlane32_swap_b32_e32 v11, v15
	v_mov_b32_dpp v67, v66 row_ror:8 row_mask:0xf bank_mask:0xf bound_ctrl:1
	v_permlane32_swap_b32_e32 v16, v24
	v_permlane32_swap_b32_e32 v17, v25
	v_permlane32_swap_b32_e32 v18, v26
	v_permlane32_swap_b32_e32 v19, v27
	v_permlane32_swap_b32_e32 v20, v40
	v_permlane32_swap_b32_e32 v21, v41
	v_permlane32_swap_b32_e32 v22, v42
	v_permlane32_swap_b32_e32 v23, v43
	v_mov_b32_dpp v69, v68 row_ror:8 row_mask:0xf bank_mask:0xf bound_ctrl:1
	v_permlane32_swap_b32_e32 v28, v48
	v_permlane32_swap_b32_e32 v29, v49
	v_permlane32_swap_b32_e32 v30, v50
	v_permlane32_swap_b32_e32 v31, v51
	v_permlane32_swap_b32_e32 v32, v52
	v_permlane32_swap_b32_e32 v33, v53
	v_permlane32_swap_b32_e32 v34, v54
	v_permlane32_swap_b32_e32 v35, v55
	v_mov_b32_dpp v71, v70 row_ror:8 row_mask:0xf bank_mask:0xf bound_ctrl:1
	v_permlane32_swap_b32_e32 v36, v56
	v_permlane32_swap_b32_e32 v37, v57
	v_permlane32_swap_b32_e32 v38, v58
	v_permlane32_swap_b32_e32 v39, v59
	v_permlane32_swap_b32_e32 v44, v60
	v_permlane32_swap_b32_e32 v45, v61
	v_permlane32_swap_b32_e32 v46, v62
	v_permlane32_swap_b32_e32 v47, v63
	s_and_saveexec_b64 s[6:7], vcc
	s_cbranch_execz .LBB0_576
	v_add_f32_e32 v2, v6, v2
	v_add_f32_e32 v3, v7, v3
	v_add_f32_e32 v0, v4, v0
	v_add_f32_e32 v1, v5, v1
	v_lshl_add_u32 v4, v171, 2, s23
	v_add_f32_e32 v46, v46, v62
	v_add_f32_e32 v47, v47, v63
	v_add_f32_e32 v44, v44, v60
	v_add_f32_e32 v45, v45, v61
	v_add_f32_e32 v38, v38, v58
	v_add_f32_e32 v39, v39, v59
	v_add_f32_e32 v36, v36, v56
	v_add_f32_e32 v37, v37, v57
	v_add_f32_e32 v34, v34, v54
	v_add_f32_e32 v35, v35, v55
	v_add_f32_e32 v32, v32, v52
	v_add_f32_e32 v33, v33, v53
	v_add_f32_e32 v30, v30, v50
	v_add_f32_e32 v31, v31, v51
	v_add_f32_e32 v28, v28, v48
	v_add_f32_e32 v29, v29, v49
	v_add_f32_e32 v22, v22, v42
	v_add_f32_e32 v23, v23, v43
	v_add_f32_e32 v20, v20, v40
	v_add_f32_e32 v21, v21, v41
	v_add_f32_e32 v18, v18, v26
	v_add_f32_e32 v19, v19, v27
	v_add_f32_e32 v16, v16, v24
	v_add_f32_e32 v17, v17, v25
	v_add_f32_e32 v10, v10, v14
	v_add_f32_e32 v11, v11, v15
	v_add_f32_e32 v8, v8, v12
	v_add_f32_e32 v9, v9, v13
	ds_write_b128 v4, v[0:3] offset:32
	ds_write_b128 v4, v[8:11] offset:2208
	ds_write_b128 v4, v[16:19] offset:576
	ds_write_b128 v4, v[20:23] offset:2752
	ds_write_b128 v4, v[28:31] offset:1120
	ds_write_b128 v4, v[32:35] offset:3296
	ds_write_b128 v4, v[36:39] offset:1664
	ds_write_b128 v4, v[44:47] offset:3840
